# one s_nop 0 padded into two load segments per GEMM K-loop so every 32-MFMA run starts at an address 4 mod 8 (code placement), rest as v69
# speedup vs baseline: 1.0007x; 1.0002x over previous
; #define PG8_STAGE(bufoff, gbase, voff) do { _Pragma("unroll") for (int _i = 0; _i < 2; ++_i) \
;         __builtin_amdgcn_global_load_lds((const unsigned*)((const char*)(gbase) + (voff)[_i]), (LAS unsigned*)(lds + (bufoff) + ldsw + _i * 8192), 16, 0, 0); } while (0)
; #define PG8_LDA(dst, b, h) do { _Pragma("unroll") for (int m = 0; m < 4; ++m) _Pragma("unroll") for (int k = 0; k < 2; ++k) dst[m][k] = *(const LAS bf16x8*)(lds + PG8_SA(b, h) + aoff + m * 2048 + k * 1024); } while (0)
; #define PG8_LDB(dst, b, h) do { _Pragma("unroll") for (int n = 0; n < 2; ++n) _Pragma("unroll") for (int k = 0; k < 2; ++k) dst[n][k] = *(const LAS bf16x8*)(lds + PG8_SB(b, h) + boff + n * 2048 + k * 1024); } while (0)
; #define PG8_SCHED __builtin_amdgcn_sched_barrier(0)
; template <class Epi, bool ALIGN_EPI>
; __device__ __forceinline__ void gemm_phase(LAS unsigned char* lds, const Gemm g, const StaticOrder& S, const Epi& E, const int tid) {
;     ...
;             const bool last = (t == nt - 2);
;             const char* a1 = cA + (size_t)(t + 1) * kstepA;
;             const char* a2 = last ? nA : cA + (size_t)(t + 2) * kstepA; const char* b2 = last ? nB : cB + (size_t)(t + 2) * kstepB;
;             const char* a3 = a2 + kstepA; const char* b3 = b2 + kstepB;
;             PG8_LDB(B0, 0, 0); PG8_LDB(B1, 0, 1); PG8_SCHED; PG8_LDA(At, 0, 0); PG8_STAGE(PG8_SA(1, 1), a1 + hstepA, voffA);
.LBB0_211:
	s_add_u32 s50, s48, 0x4000
	s_addc_u32 s51, s49, 0
	s_cmp_eq_u32 s89, 28
	s_cselect_b32 s54, s87, s50
	s_cselect_b32 s55, s43, s51
	s_cselect_b32 s52, vcc_lo, vcc_hi
	s_cselect_b32 s53, s35, s88
	s_add_u32 s50, s54, 0x8000
	s_addc_u32 s51, s55, 0
	s_add_i32 s90, 0, 0x10000
	v_add_u32_e32 v0, s90, v160
	s_add_i32 s92, 0, 0x14000
	ds_read_b128 v[132:135], v0
	ds_read_b128 v[136:139], v0 offset:1024
	ds_read_b128 v[152:155], v0 offset:2048
	ds_read_b128 v[156:159], v0 offset:3072
	v_add_u32_e32 v0, s92, v160
	ds_read_b128 v[162:165], v0
	ds_read_b128 v[166:169], v0 offset:1024
	ds_read_b128 v[170:173], v0 offset:2048
	ds_read_b128 v[174:177], v0 offset:3072
	s_add_i32 m0, s72, 0xc000
	ds_read_b128 v[178:181], v161
	ds_read_b128 v[182:185], v161 offset:1024
	ds_read_b128 v[186:189], v161 offset:2048
	ds_read_b128 v[190:193], v161 offset:3072
	ds_read_b128 v[194:197], v161 offset:4096
	ds_read_b128 v[198:201], v161 offset:5120
	ds_read_b128 v[214:217], v161 offset:6144

; #define PG8_STAGE(bufoff, gbase, voff) do { _Pragma("unroll") for (int _i = 0; _i < 2; ++_i) \
;         __builtin_amdgcn_global_load_lds((const unsigned*)((const char*)(gbase) + (voff)[_i]), (LAS unsigned*)(lds + (bufoff) + ldsw + _i * 8192), 16, 0, 0); } while (0)
; #define PG8_LDA(dst, b, h) do { _Pragma("unroll") for (int m = 0; m < 4; ++m) _Pragma("unroll") for (int k = 0; k < 2; ++k) dst[m][k] = *(const LAS bf16x8*)(lds + PG8_SA(b, h) + aoff + m * 2048 + k * 1024); } while (0)
; #define PG8_LDB(dst, b, h) do { _Pragma("unroll") for (int n = 0; n < 2; ++n) _Pragma("unroll") for (int k = 0; k < 2; ++k) dst[n][k] = *(const LAS bf16x8*)(lds + PG8_SB(b, h) + boff + n * 2048 + k * 1024); } while (0)
; #define PG8_MMA(ai, bj, At, Bt) do { __builtin_amdgcn_s_setprio(1); _Pragma("unroll") for (int m = 0; m < 4; ++m) _Pragma("unroll") for (int n = 0; n < 2; ++n) _Pragma("unroll") for (int k = 0; k < 2; ++k) \
;         acc[ai][bj][m][n] = __builtin_amdgcn_mfma_f32_16x16x32_bf16(Bt[n][k], At[m][k], acc[ai][bj][m][n], 0, 0, 0); __builtin_amdgcn_s_setprio(0); } while (0)
; #define PG8_WAIT_V(n) asm volatile("s_waitcnt vmcnt(" #n ")" ::: "memory")
; #define PG8_WAIT_L(n) asm volatile("s_waitcnt lgkmcnt(" #n ")" ::: "memory")
; #define PG8_BAR __builtin_amdgcn_s_barrier()
; #define PG8_SCHED __builtin_amdgcn_sched_barrier(0)
; template <class Epi, bool ALIGN_EPI>
; __device__ __forceinline__ void gemm_phase(LAS unsigned char* lds, const Gemm g, const StaticOrder& S, const Epi& E, const int tid) {
;     ...
;             PG8_LDB(B0, 0, 0); PG8_LDB(B1, 0, 1); PG8_SCHED; PG8_LDA(At, 0, 0); PG8_STAGE(PG8_SA(1, 1), a1 + hstepA, voffA);
;             PG8_WAIT_V(8); PG8_WAIT_L(0); PG8_BAR; PG8_MMA(0, 0, At, B0); PG8_MMA(0, 1, At, B1); PG8_BAR; PG8_SCHED;
	global_load_lds_dwordx4 v148, s[48:49]
	s_add_i32 m0, s72, 0xe000
	ds_read_b128 v[218:221], v161 offset:7168
	global_load_lds_dwordx4 v150, s[48:49]
	s_waitcnt vmcnt(8)
	s_waitcnt lgkmcnt(0)
	s_barrier


; #define PG8_MMA(ai, bj, At, Bt) do { __builtin_amdgcn_s_setprio(1); _Pragma("unroll") for (int m = 0; m < 4; ++m) _Pragma("unroll") for (int n = 0; n < 2; ++n) _Pragma("unroll") for (int k = 0; k < 2; ++k) \
;         acc[ai][bj][m][n] = __builtin_amdgcn_mfma_f32_16x16x32_bf16(Bt[n][k], At[m][k], acc[ai][bj][m][n], 0, 0, 0); __builtin_amdgcn_s_setprio(0); } while (0)
; #define PG8_WAIT_V(n) asm volatile("s_waitcnt vmcnt(" #n ")" ::: "memory")
; #define PG8_WAIT_L(n) asm volatile("s_waitcnt lgkmcnt(" #n ")" ::: "memory")
; #define PG8_BAR __builtin_amdgcn_s_barrier()
; #define PG8_SCHED __builtin_amdgcn_sched_barrier(0)
; template <class Epi, bool ALIGN_EPI>
; __device__ __forceinline__ void gemm_phase(LAS unsigned char* lds, const Gemm g, const StaticOrder& S, const Epi& E, const int tid) {
;     ...
;             PG8_WAIT_V(8); PG8_WAIT_L(0); PG8_BAR; PG8_MMA(0, 0, At, B0); PG8_MMA(0, 1, At, B1); PG8_BAR; PG8_SCHED;
	v_mfma_f32_16x16x32_bf16 v[88:91], v[132:135], v[178:181], v[88:91]
	v_mfma_f32_16x16x32_bf16 v[124:127], v[152:155], v[178:181], v[124:127]
	v_mfma_f32_16x16x32_bf16 v[52:55], v[132:135], v[186:189], v[52:55]
	v_mfma_f32_16x16x32_bf16 v[120:123], v[152:155], v[186:189], v[120:123]
	v_mfma_f32_16x16x32_bf16 v[40:43], v[132:135], v[194:197], v[40:43]
	v_mfma_f32_16x16x32_bf16 v[116:119], v[152:155], v[194:197], v[116:119]
	v_mfma_f32_16x16x32_bf16 v[36:39], v[132:135], v[214:217], v[36:39]
	v_mfma_f32_16x16x32_bf16 v[112:115], v[152:155], v[214:217], v[112:115]
	v_mfma_f32_16x16x32_bf16 v[88:91], v[136:139], v[182:185], v[88:91]
	v_mfma_f32_16x16x32_bf16 v[124:127], v[156:159], v[182:185], v[124:127]
	v_mfma_f32_16x16x32_bf16 v[52:55], v[136:139], v[190:193], v[52:55]
	v_mfma_f32_16x16x32_bf16 v[120:123], v[156:159], v[190:193], v[120:123]
	v_mfma_f32_16x16x32_bf16 v[40:43], v[136:139], v[198:201], v[40:43]
	v_mfma_f32_16x16x32_bf16 v[116:119], v[156:159], v[198:201], v[116:119]
	v_mfma_f32_16x16x32_bf16 v[36:39], v[136:139], v[218:221], v[36:39]
	v_mfma_f32_16x16x32_bf16 v[112:115], v[156:159], v[218:221], v[112:115]


; #define PG8_MMA(ai, bj, At, Bt) do { __builtin_amdgcn_s_setprio(1); _Pragma("unroll") for (int m = 0; m < 4; ++m) _Pragma("unroll") for (int n = 0; n < 2; ++n) _Pragma("unroll") for (int k = 0; k < 2; ++k) \
;         acc[ai][bj][m][n] = __builtin_amdgcn_mfma_f32_16x16x32_bf16(Bt[n][k], At[m][k], acc[ai][bj][m][n], 0, 0, 0); __builtin_amdgcn_s_setprio(0); } while (0)
; #define PG8_WAIT_V(n) asm volatile("s_waitcnt vmcnt(" #n ")" ::: "memory")
; #define PG8_WAIT_L(n) asm volatile("s_waitcnt lgkmcnt(" #n ")" ::: "memory")
; #define PG8_BAR __builtin_amdgcn_s_barrier()
; #define PG8_SCHED __builtin_amdgcn_sched_barrier(0)
; template <class Epi, bool ALIGN_EPI>
; __device__ __forceinline__ void gemm_phase(LAS unsigned char* lds, const Gemm g, const StaticOrder& S, const Epi& E, const int tid) {
;     ...
;             PG8_WAIT_V(8); PG8_WAIT_L(0); PG8_BAR; PG8_MMA(0, 0, At, B0); PG8_MMA(0, 1, At, B1); PG8_BAR; PG8_SCHED;
	v_mfma_f32_16x16x32_bf16 v[80:83], v[162:165], v[178:181], v[80:83]
	v_mfma_f32_16x16x32_bf16 v[128:131], v[170:173], v[178:181], v[128:131]
	v_mfma_f32_16x16x32_bf16 v[68:71], v[162:165], v[186:189], v[68:71]
	v_mfma_f32_16x16x32_bf16 v[108:111], v[170:173], v[186:189], v[108:111]
	v_mfma_f32_16x16x32_bf16 v[60:63], v[162:165], v[194:197], v[60:63]
	v_mfma_f32_16x16x32_bf16 v[104:107], v[170:173], v[194:197], v[104:107]
	v_mfma_f32_16x16x32_bf16 v[48:51], v[162:165], v[214:217], v[48:51]
	v_mfma_f32_16x16x32_bf16 v[100:103], v[170:173], v[214:217], v[100:103]
	v_mfma_f32_16x16x32_bf16 v[80:83], v[166:169], v[182:185], v[80:83]
	v_mfma_f32_16x16x32_bf16 v[128:131], v[174:177], v[182:185], v[128:131]
	v_mfma_f32_16x16x32_bf16 v[68:71], v[166:169], v[190:193], v[68:71]
	v_mfma_f32_16x16x32_bf16 v[108:111], v[174:177], v[190:193], v[108:111]
	v_mfma_f32_16x16x32_bf16 v[60:63], v[166:169], v[198:201], v[60:63]
	v_mfma_f32_16x16x32_bf16 v[104:107], v[174:177], v[198:201], v[104:107]
	v_mfma_f32_16x16x32_bf16 v[48:51], v[166:169], v[218:221], v[48:51]
	v_mfma_f32_16x16x32_bf16 v[100:103], v[174:177], v[218:221], v[100:103]

; #define PG8_STAGE(bufoff, gbase, voff) do { _Pragma("unroll") for (int _i = 0; _i < 2; ++_i) \
;         __builtin_amdgcn_global_load_lds((const unsigned*)((const char*)(gbase) + (voff)[_i]), (LAS unsigned*)(lds + (bufoff) + ldsw + _i * 8192), 16, 0, 0); } while (0)
; #define PG8_LDA(dst, b, h) do { _Pragma("unroll") for (int m = 0; m < 4; ++m) _Pragma("unroll") for (int k = 0; k < 2; ++k) dst[m][k] = *(const LAS bf16x8*)(lds + PG8_SA(b, h) + aoff + m * 2048 + k * 1024); } while (0)
; #define PG8_MMA(ai, bj, At, Bt) do { __builtin_amdgcn_s_setprio(1); _Pragma("unroll") for (int m = 0; m < 4; ++m) _Pragma("unroll") for (int n = 0; n < 2; ++n) _Pragma("unroll") for (int k = 0; k < 2; ++k) \
;         acc[ai][bj][m][n] = __builtin_amdgcn_mfma_f32_16x16x32_bf16(Bt[n][k], At[m][k], acc[ai][bj][m][n], 0, 0, 0); __builtin_amdgcn_s_setprio(0); } while (0)
; #define PG8_WAIT_V(n) asm volatile("s_waitcnt vmcnt(" #n ")" ::: "memory")
; #define PG8_WAIT_L(n) asm volatile("s_waitcnt lgkmcnt(" #n ")" ::: "memory")
; #define PG8_BAR __builtin_amdgcn_s_barrier()
; #define PG8_SCHED __builtin_amdgcn_sched_barrier(0)
; template <class Epi, bool ALIGN_EPI>
; __device__ __forceinline__ void gemm_phase(LAS unsigned char* lds, const Gemm g, const StaticOrder& S, const Epi& E, const int tid) {
;     ...
;             PG8_WAIT_V(8); PG8_WAIT_L(0); PG8_BAR; PG8_MMA(0, 0, At, B0); PG8_MMA(0, 1, At, B1); PG8_BAR; PG8_SCHED;
;             PG8_LDA(At, 0, 1); PG8_STAGE(PG8_SB(0, 0), b2, voffB); PG8_STAGE(PG8_SB(0, 1), b2 + hstepB, voffB); PG8_STAGE(PG8_SA(0, 0), a2, voffA);
	s_barrier
	s_add_i32 s90, s90, s71
	s_mov_b32 m0, s90
	ds_read_b128 v[178:181], v161 offset:16384
	ds_read_b128 v[182:185], v161 offset:17408
	ds_read_b128 v[186:189], v161 offset:18432
	ds_read_b128 v[190:193], v161 offset:19456


; #define PG8_STAGE(bufoff, gbase, voff) do { _Pragma("unroll") for (int _i = 0; _i < 2; ++_i) \
;         __builtin_amdgcn_global_load_lds((const unsigned*)((const char*)(gbase) + (voff)[_i]), (LAS unsigned*)(lds + (bufoff) + ldsw + _i * 8192), 16, 0, 0); } while (0)
; #define PG8_LDA(dst, b, h) do { _Pragma("unroll") for (int m = 0; m < 4; ++m) _Pragma("unroll") for (int k = 0; k < 2; ++k) dst[m][k] = *(const LAS bf16x8*)(lds + PG8_SA(b, h) + aoff + m * 2048 + k * 1024); } while (0)
; #define PG8_MMA(ai, bj, At, Bt) do { __builtin_amdgcn_s_setprio(1); _Pragma("unroll") for (int m = 0; m < 4; ++m) _Pragma("unroll") for (int n = 0; n < 2; ++n) _Pragma("unroll") for (int k = 0; k < 2; ++k) \
;         acc[ai][bj][m][n] = __builtin_amdgcn_mfma_f32_16x16x32_bf16(Bt[n][k], At[m][k], acc[ai][bj][m][n], 0, 0, 0); __builtin_amdgcn_s_setprio(0); } while (0)
; #define PG8_WAIT_V(n) asm volatile("s_waitcnt vmcnt(" #n ")" ::: "memory")
; #define PG8_WAIT_L(n) asm volatile("s_waitcnt lgkmcnt(" #n ")" ::: "memory")
; #define PG8_BAR __builtin_amdgcn_s_barrier()
; #define PG8_SCHED __builtin_amdgcn_sched_barrier(0)
; template <class Epi, bool ALIGN_EPI>
; __device__ __forceinline__ void gemm_phase(LAS unsigned char* lds, const Gemm g, const StaticOrder& S, const Epi& E, const int tid) {
;     ...
;             PG8_LDA(At, 0, 1); PG8_STAGE(PG8_SB(0, 0), b2, voffB); PG8_STAGE(PG8_SB(0, 1), b2 + hstepB, voffB); PG8_STAGE(PG8_SA(0, 0), a2, voffA);
;             PG8_WAIT_V(8); PG8_WAIT_L(0); PG8_BAR; PG8_MMA(1, 0, At, B0); PG8_MMA(1, 1, At, B1); PG8_BAR; PG8_SCHED;
	global_load_lds_dwordx4 v144, s[52:53]
	s_add_i32 m0, s90, 0x2000
	s_add_u32 s90, s52, 0x4000
	s_addc_u32 s91, s53, 0
	s_add_i32 s92, s92, s71
	global_load_lds_dwordx4 v140, s[52:53]
	s_mov_b32 m0, s92
	ds_read_b128 v[218:221], v161 offset:23552
	global_load_lds_dwordx4 v144, s[90:91]
	s_add_i32 m0, s92, 0x2000
	ds_read_b128 v[214:217], v161 offset:22528
	global_load_lds_dwordx4 v140, s[90:91]
	s_mov_b32 m0, s72
	ds_read_b128 v[198:201], v161 offset:21504
	global_load_lds_dwordx4 v146, s[54:55]
	s_mov_b32 m0, s73
	ds_read_b128 v[194:197], v161 offset:20480
	global_load_lds_dwordx4 v142, s[54:55]
	s_nop 0
	s_waitcnt vmcnt(8)
	s_waitcnt lgkmcnt(0)
	s_barrier


; #define PG8_MMA(ai, bj, At, Bt) do { __builtin_amdgcn_s_setprio(1); _Pragma("unroll") for (int m = 0; m < 4; ++m) _Pragma("unroll") for (int n = 0; n < 2; ++n) _Pragma("unroll") for (int k = 0; k < 2; ++k) \
;         acc[ai][bj][m][n] = __builtin_amdgcn_mfma_f32_16x16x32_bf16(Bt[n][k], At[m][k], acc[ai][bj][m][n], 0, 0, 0); __builtin_amdgcn_s_setprio(0); } while (0)
; #define PG8_WAIT_V(n) asm volatile("s_waitcnt vmcnt(" #n ")" ::: "memory")
; #define PG8_WAIT_L(n) asm volatile("s_waitcnt lgkmcnt(" #n ")" ::: "memory")
; #define PG8_BAR __builtin_amdgcn_s_barrier()
; #define PG8_SCHED __builtin_amdgcn_sched_barrier(0)
; template <class Epi, bool ALIGN_EPI>
; __device__ __forceinline__ void gemm_phase(LAS unsigned char* lds, const Gemm g, const StaticOrder& S, const Epi& E, const int tid) {
;     ...
;             PG8_WAIT_V(8); PG8_WAIT_L(0); PG8_BAR; PG8_MMA(1, 0, At, B0); PG8_MMA(1, 1, At, B1); PG8_BAR; PG8_SCHED;
	v_mfma_f32_16x16x32_bf16 v[24:27], v[132:135], v[178:181], v[24:27]
	v_mfma_f32_16x16x32_bf16 v[92:95], v[152:155], v[178:181], v[92:95]
	v_mfma_f32_16x16x32_bf16 v[16:19], v[132:135], v[186:189], v[16:19]
	v_mfma_f32_16x16x32_bf16 v[84:87], v[152:155], v[186:189], v[84:87]
	v_mfma_f32_16x16x32_bf16 v[8:11], v[132:135], v[194:197], v[8:11]
	v_mfma_f32_16x16x32_bf16 v[76:79], v[152:155], v[194:197], v[76:79]
	v_mfma_f32_16x16x32_bf16 v[2:5], v[132:135], v[214:217], v[4:7]
	v_mfma_f32_16x16x32_bf16 v[64:67], v[152:155], v[214:217], v[64:67]
	v_mfma_f32_16x16x32_bf16 v[24:27], v[136:139], v[182:185], v[24:27]
	v_mfma_f32_16x16x32_bf16 v[92:95], v[156:159], v[182:185], v[92:95]
	v_mfma_f32_16x16x32_bf16 v[16:19], v[136:139], v[190:193], v[16:19]
	v_mfma_f32_16x16x32_bf16 v[84:87], v[156:159], v[190:193], v[84:87]
	v_mfma_f32_16x16x32_bf16 v[8:11], v[136:139], v[198:201], v[8:11]
	v_mfma_f32_16x16x32_bf16 v[76:79], v[156:159], v[198:201], v[76:79]
	v_mfma_f32_16x16x32_bf16 v[2:5], v[136:139], v[218:221], v[2:5]
	v_mfma_f32_16x16x32_bf16 v[64:67], v[156:159], v[218:221], v[64:67]


; #define PG8_MMA(ai, bj, At, Bt) do { __builtin_amdgcn_s_setprio(1); _Pragma("unroll") for (int m = 0; m < 4; ++m) _Pragma("unroll") for (int n = 0; n < 2; ++n) _Pragma("unroll") for (int k = 0; k < 2; ++k) \
;         acc[ai][bj][m][n] = __builtin_amdgcn_mfma_f32_16x16x32_bf16(Bt[n][k], At[m][k], acc[ai][bj][m][n], 0, 0, 0); __builtin_amdgcn_s_setprio(0); } while (0)
; #define PG8_WAIT_V(n) asm volatile("s_waitcnt vmcnt(" #n ")" ::: "memory")
; #define PG8_WAIT_L(n) asm volatile("s_waitcnt lgkmcnt(" #n ")" ::: "memory")
; #define PG8_BAR __builtin_amdgcn_s_barrier()
; #define PG8_SCHED __builtin_amdgcn_sched_barrier(0)
; template <class Epi, bool ALIGN_EPI>
; __device__ __forceinline__ void gemm_phase(LAS unsigned char* lds, const Gemm g, const StaticOrder& S, const Epi& E, const int tid) {
;     ...
;             PG8_WAIT_V(8); PG8_WAIT_L(0); PG8_BAR; PG8_MMA(1, 0, At, B0); PG8_MMA(1, 1, At, B1); PG8_BAR; PG8_SCHED;
	v_mfma_f32_16x16x32_bf16 v[32:35], v[162:165], v[178:181], v[32:35]
	v_mfma_f32_16x16x32_bf16 v[72:75], v[170:173], v[178:181], v[72:75]
	v_mfma_f32_16x16x32_bf16 v[28:31], v[162:165], v[186:189], v[28:31]
	v_mfma_f32_16x16x32_bf16 v[96:99], v[170:173], v[186:189], v[96:99]
	v_mfma_f32_16x16x32_bf16 v[20:23], v[162:165], v[194:197], v[20:23]
	v_mfma_f32_16x16x32_bf16 v[56:59], v[170:173], v[194:197], v[56:59]
	v_mfma_f32_16x16x32_bf16 v[12:15], v[162:165], v[214:217], v[12:15]
	v_mfma_f32_16x16x32_bf16 v[44:47], v[170:173], v[214:217], v[44:47]
	v_mfma_f32_16x16x32_bf16 v[32:35], v[166:169], v[182:185], v[32:35]
	v_mfma_f32_16x16x32_bf16 v[72:75], v[174:177], v[182:185], v[72:75]
	v_mfma_f32_16x16x32_bf16 v[28:31], v[166:169], v[190:193], v[28:31]
	v_mfma_f32_16x16x32_bf16 v[96:99], v[174:177], v[190:193], v[96:99]
	v_mfma_f32_16x16x32_bf16 v[20:23], v[166:169], v[198:201], v[20:23]
	v_mfma_f32_16x16x32_bf16 v[56:59], v[174:177], v[198:201], v[56:59]
	v_mfma_f32_16x16x32_bf16 v[12:15], v[166:169], v[218:221], v[12:15]
	v_mfma_f32_16x16x32_bf16 v[44:47], v[174:177], v[218:221], v[44:47]

; #define PG8_STAGE(bufoff, gbase, voff) do { _Pragma("unroll") for (int _i = 0; _i < 2; ++_i) \
;         __builtin_amdgcn_global_load_lds((const unsigned*)((const char*)(gbase) + (voff)[_i]), (LAS unsigned*)(lds + (bufoff) + ldsw + _i * 8192), 16, 0, 0); } while (0)
; #define PG8_LDA(dst, b, h) do { _Pragma("unroll") for (int m = 0; m < 4; ++m) _Pragma("unroll") for (int k = 0; k < 2; ++k) dst[m][k] = *(const LAS bf16x8*)(lds + PG8_SA(b, h) + aoff + m * 2048 + k * 1024); } while (0)
; #define PG8_LDB(dst, b, h) do { _Pragma("unroll") for (int n = 0; n < 2; ++n) _Pragma("unroll") for (int k = 0; k < 2; ++k) dst[n][k] = *(const LAS bf16x8*)(lds + PG8_SB(b, h) + boff + n * 2048 + k * 1024); } while (0)
; #define PG8_SCHED __builtin_amdgcn_sched_barrier(0)
; template <class Epi, bool ALIGN_EPI>
; __device__ __forceinline__ void gemm_phase(LAS unsigned char* lds, const Gemm g, const StaticOrder& S, const Epi& E, const int tid) {
;     ...
;             PG8_LDB(B0, 1, 0); PG8_LDB(B1, 1, 1); PG8_SCHED; PG8_LDA(At, 1, 0); PG8_STAGE(PG8_SA(0, 1), a2 + hstepA, voffA);
	s_barrier
	s_add_i32 s90, 0, 0x18000
	v_add_u32_e32 v0, s90, v160
	s_add_i32 s91, 0, 0x1c000
	ds_read_b128 v[132:135], v0
	ds_read_b128 v[136:139], v0 offset:1024
	ds_read_b128 v[152:155], v0 offset:2048
	ds_read_b128 v[156:159], v0 offset:3072
	v_add_u32_e32 v0, s91, v160
	ds_read_b128 v[162:165], v0
	ds_read_b128 v[166:169], v0 offset:1024
	ds_read_b128 v[170:173], v0 offset:2048
	ds_read_b128 v[174:177], v0 offset:3072
	s_add_u32 s54, s54, 0x4000
	s_addc_u32 s55, s55, 0
	s_mov_b32 m0, s74
	ds_read_b128 v[178:181], v161 offset:32768
	ds_read_b128 v[182:185], v161 offset:33792
	ds_read_b128 v[186:189], v161 offset:34816
	ds_read_b128 v[190:193], v161 offset:35840
	ds_read_b128 v[194:197], v161 offset:36864
	ds_read_b128 v[198:201], v161 offset:37888
	ds_read_b128 v[214:217], v161 offset:38912

; #define PG8_STAGE(bufoff, gbase, voff) do { _Pragma("unroll") for (int _i = 0; _i < 2; ++_i) \
;         __builtin_amdgcn_global_load_lds((const unsigned*)((const char*)(gbase) + (voff)[_i]), (LAS unsigned*)(lds + (bufoff) + ldsw + _i * 8192), 16, 0, 0); } while (0)
; #define PG8_LDA(dst, b, h) do { _Pragma("unroll") for (int m = 0; m < 4; ++m) _Pragma("unroll") for (int k = 0; k < 2; ++k) dst[m][k] = *(const LAS bf16x8*)(lds + PG8_SA(b, h) + aoff + m * 2048 + k * 1024); } while (0)
; #define PG8_LDB(dst, b, h) do { _Pragma("unroll") for (int n = 0; n < 2; ++n) _Pragma("unroll") for (int k = 0; k < 2; ++k) dst[n][k] = *(const LAS bf16x8*)(lds + PG8_SB(b, h) + boff + n * 2048 + k * 1024); } while (0)
; #define PG8_MMA(ai, bj, At, Bt) do { __builtin_amdgcn_s_setprio(1); _Pragma("unroll") for (int m = 0; m < 4; ++m) _Pragma("unroll") for (int n = 0; n < 2; ++n) _Pragma("unroll") for (int k = 0; k < 2; ++k) \
;         acc[ai][bj][m][n] = __builtin_amdgcn_mfma_f32_16x16x32_bf16(Bt[n][k], At[m][k], acc[ai][bj][m][n], 0, 0, 0); __builtin_amdgcn_s_setprio(0); } while (0)
; #define PG8_WAIT_V(n) asm volatile("s_waitcnt vmcnt(" #n ")" ::: "memory")
; #define PG8_WAIT_L(n) asm volatile("s_waitcnt lgkmcnt(" #n ")" ::: "memory")
; #define PG8_BAR __builtin_amdgcn_s_barrier()
; #define PG8_SCHED __builtin_amdgcn_sched_barrier(0)
; template <class Epi, bool ALIGN_EPI>
; __device__ __forceinline__ void gemm_phase(LAS unsigned char* lds, const Gemm g, const StaticOrder& S, const Epi& E, const int tid) {
;     ...
;             PG8_LDB(B0, 1, 0); PG8_LDB(B1, 1, 1); PG8_SCHED; PG8_LDA(At, 1, 0); PG8_STAGE(PG8_SA(0, 1), a2 + hstepA, voffA);
;             PG8_WAIT_V(8); PG8_WAIT_L(0); PG8_BAR; PG8_MMA(0, 0, At, B0); PG8_MMA(0, 1, At, B1); PG8_BAR; PG8_SCHED;
	global_load_lds_dwordx4 v146, s[54:55]
	s_mov_b32 m0, s75
	ds_read_b128 v[218:221], v161 offset:39936
	global_load_lds_dwordx4 v142, s[54:55]
	s_nop 0
	s_waitcnt vmcnt(8)
	s_waitcnt lgkmcnt(0)
	s_barrier


; #define PG8_MMA(ai, bj, At, Bt) do { __builtin_amdgcn_s_setprio(1); _Pragma("unroll") for (int m = 0; m < 4; ++m) _Pragma("unroll") for (int n = 0; n < 2; ++n) _Pragma("unroll") for (int k = 0; k < 2; ++k) \
;         acc[ai][bj][m][n] = __builtin_amdgcn_mfma_f32_16x16x32_bf16(Bt[n][k], At[m][k], acc[ai][bj][m][n], 0, 0, 0); __builtin_amdgcn_s_setprio(0); } while (0)
; #define PG8_WAIT_V(n) asm volatile("s_waitcnt vmcnt(" #n ")" ::: "memory")
; #define PG8_WAIT_L(n) asm volatile("s_waitcnt lgkmcnt(" #n ")" ::: "memory")
; #define PG8_BAR __builtin_amdgcn_s_barrier()
; #define PG8_SCHED __builtin_amdgcn_sched_barrier(0)
; template <class Epi, bool ALIGN_EPI>
; __device__ __forceinline__ void gemm_phase(LAS unsigned char* lds, const Gemm g, const StaticOrder& S, const Epi& E, const int tid) {
;     ...
;             PG8_WAIT_V(8); PG8_WAIT_L(0); PG8_BAR; PG8_MMA(0, 0, At, B0); PG8_MMA(0, 1, At, B1); PG8_BAR; PG8_SCHED;
	v_mfma_f32_16x16x32_bf16 v[88:91], v[132:135], v[178:181], v[88:91]
	v_mfma_f32_16x16x32_bf16 v[124:127], v[152:155], v[178:181], v[124:127]
	v_mfma_f32_16x16x32_bf16 v[52:55], v[132:135], v[186:189], v[52:55]
	v_mfma_f32_16x16x32_bf16 v[120:123], v[152:155], v[186:189], v[120:123]
	v_mfma_f32_16x16x32_bf16 v[40:43], v[132:135], v[194:197], v[40:43]
	v_mfma_f32_16x16x32_bf16 v[116:119], v[152:155], v[194:197], v[116:119]
	v_mfma_f32_16x16x32_bf16 v[36:39], v[132:135], v[214:217], v[36:39]
	v_mfma_f32_16x16x32_bf16 v[112:115], v[152:155], v[214:217], v[112:115]
	v_mfma_f32_16x16x32_bf16 v[88:91], v[136:139], v[182:185], v[88:91]
	v_mfma_f32_16x16x32_bf16 v[124:127], v[156:159], v[182:185], v[124:127]
	v_mfma_f32_16x16x32_bf16 v[52:55], v[136:139], v[190:193], v[52:55]
	v_mfma_f32_16x16x32_bf16 v[120:123], v[156:159], v[190:193], v[120:123]
	v_mfma_f32_16x16x32_bf16 v[40:43], v[136:139], v[198:201], v[40:43]
	v_mfma_f32_16x16x32_bf16 v[116:119], v[156:159], v[198:201], v[116:119]
	v_mfma_f32_16x16x32_bf16 v[36:39], v[136:139], v[218:221], v[36:39]
	v_mfma_f32_16x16x32_bf16 v[112:115], v[156:159], v[218:221], v[112:115]


; #define PG8_MMA(ai, bj, At, Bt) do { __builtin_amdgcn_s_setprio(1); _Pragma("unroll") for (int m = 0; m < 4; ++m) _Pragma("unroll") for (int n = 0; n < 2; ++n) _Pragma("unroll") for (int k = 0; k < 2; ++k) \
;         acc[ai][bj][m][n] = __builtin_amdgcn_mfma_f32_16x16x32_bf16(Bt[n][k], At[m][k], acc[ai][bj][m][n], 0, 0, 0); __builtin_amdgcn_s_setprio(0); } while (0)
; #define PG8_WAIT_V(n) asm volatile("s_waitcnt vmcnt(" #n ")" ::: "memory")
; #define PG8_WAIT_L(n) asm volatile("s_waitcnt lgkmcnt(" #n ")" ::: "memory")
; #define PG8_BAR __builtin_amdgcn_s_barrier()
; #define PG8_SCHED __builtin_amdgcn_sched_barrier(0)
; template <class Epi, bool ALIGN_EPI>
; __device__ __forceinline__ void gemm_phase(LAS unsigned char* lds, const Gemm g, const StaticOrder& S, const Epi& E, const int tid) {
;     ...
;             PG8_WAIT_V(8); PG8_WAIT_L(0); PG8_BAR; PG8_MMA(0, 0, At, B0); PG8_MMA(0, 1, At, B1); PG8_BAR; PG8_SCHED;
	v_mfma_f32_16x16x32_bf16 v[80:83], v[162:165], v[178:181], v[80:83]
	v_mfma_f32_16x16x32_bf16 v[128:131], v[170:173], v[178:181], v[128:131]
	v_mfma_f32_16x16x32_bf16 v[68:71], v[162:165], v[186:189], v[68:71]
	v_mfma_f32_16x16x32_bf16 v[108:111], v[170:173], v[186:189], v[108:111]
	v_mfma_f32_16x16x32_bf16 v[60:63], v[162:165], v[194:197], v[60:63]
	v_mfma_f32_16x16x32_bf16 v[104:107], v[170:173], v[194:197], v[104:107]
	v_mfma_f32_16x16x32_bf16 v[48:51], v[162:165], v[214:217], v[48:51]
	v_mfma_f32_16x16x32_bf16 v[100:103], v[170:173], v[214:217], v[100:103]
	v_mfma_f32_16x16x32_bf16 v[80:83], v[166:169], v[182:185], v[80:83]
	v_mfma_f32_16x16x32_bf16 v[128:131], v[174:177], v[182:185], v[128:131]
	v_mfma_f32_16x16x32_bf16 v[68:71], v[166:169], v[190:193], v[68:71]
	v_mfma_f32_16x16x32_bf16 v[108:111], v[174:177], v[190:193], v[108:111]
	v_mfma_f32_16x16x32_bf16 v[60:63], v[166:169], v[198:201], v[60:63]
	v_mfma_f32_16x16x32_bf16 v[104:107], v[174:177], v[198:201], v[104:107]
	v_mfma_f32_16x16x32_bf16 v[48:51], v[166:169], v[218:221], v[48:51]
	v_mfma_f32_16x16x32_bf16 v[100:103], v[174:177], v[218:221], v[100:103]

; #define PG8_STAGE(bufoff, gbase, voff) do { _Pragma("unroll") for (int _i = 0; _i < 2; ++_i) \
;         __builtin_amdgcn_global_load_lds((const unsigned*)((const char*)(gbase) + (voff)[_i]), (LAS unsigned*)(lds + (bufoff) + ldsw + _i * 8192), 16, 0, 0); } while (0)
; #define PG8_LDA(dst, b, h) do { _Pragma("unroll") for (int m = 0; m < 4; ++m) _Pragma("unroll") for (int k = 0; k < 2; ++k) dst[m][k] = *(const LAS bf16x8*)(lds + PG8_SA(b, h) + aoff + m * 2048 + k * 1024); } while (0)
; template <class Epi, bool ALIGN_EPI>
; __device__ __forceinline__ void gemm_phase(LAS unsigned char* lds, const Gemm g, const StaticOrder& S, const Epi& E, const int tid) {
;     ...
;             PG8_LDA(At, 1, 1); PG8_STAGE(PG8_SB(1, 0), b3, voffB); PG8_STAGE(PG8_SB(1, 1), b3 + hstepB, voffB); PG8_STAGE(PG8_SA(1, 0), a3, voffA);
	s_barrier
	s_add_u32 s54, s52, 0x8000
	s_addc_u32 s55, s53, 0
	s_add_i32 s90, s90, s71
	s_mov_b32 m0, s90
	ds_read_b128 v[178:181], v161 offset:49152
	ds_read_b128 v[182:185], v161 offset:50176
	ds_read_b128 v[186:189], v161 offset:51200
	ds_read_b128 v[190:193], v161 offset:52224


; #define PG8_STAGE(bufoff, gbase, voff) do { _Pragma("unroll") for (int _i = 0; _i < 2; ++_i) \
;         __builtin_amdgcn_global_load_lds((const unsigned*)((const char*)(gbase) + (voff)[_i]), (LAS unsigned*)(lds + (bufoff) + ldsw + _i * 8192), 16, 0, 0); } while (0)
; #define PG8_LDA(dst, b, h) do { _Pragma("unroll") for (int m = 0; m < 4; ++m) _Pragma("unroll") for (int k = 0; k < 2; ++k) dst[m][k] = *(const LAS bf16x8*)(lds + PG8_SA(b, h) + aoff + m * 2048 + k * 1024); } while (0)
; #define PG8_MMA(ai, bj, At, Bt) do { __builtin_amdgcn_s_setprio(1); _Pragma("unroll") for (int m = 0; m < 4; ++m) _Pragma("unroll") for (int n = 0; n < 2; ++n) _Pragma("unroll") for (int k = 0; k < 2; ++k) \
;         acc[ai][bj][m][n] = __builtin_amdgcn_mfma_f32_16x16x32_bf16(Bt[n][k], At[m][k], acc[ai][bj][m][n], 0, 0, 0); __builtin_amdgcn_s_setprio(0); } while (0)
; #define PG8_WAIT_V(n) asm volatile("s_waitcnt vmcnt(" #n ")" ::: "memory")
; #define PG8_WAIT_L(n) asm volatile("s_waitcnt lgkmcnt(" #n ")" ::: "memory")
; #define PG8_BAR __builtin_amdgcn_s_barrier()
; #define PG8_SCHED __builtin_amdgcn_sched_barrier(0)
; template <class Epi, bool ALIGN_EPI>
; __device__ __forceinline__ void gemm_phase(LAS unsigned char* lds, const Gemm g, const StaticOrder& S, const Epi& E, const int tid) {
;     ...
;             PG8_LDA(At, 1, 1); PG8_STAGE(PG8_SB(1, 0), b3, voffB); PG8_STAGE(PG8_SB(1, 1), b3 + hstepB, voffB); PG8_STAGE(PG8_SA(1, 0), a3, voffA);
;             PG8_WAIT_V(8); PG8_WAIT_L(0); PG8_BAR; PG8_MMA(1, 0, At, B0); PG8_MMA(1, 1, At, B1); PG8_BAR; PG8_SCHED;
	global_load_lds_dwordx4 v144, s[54:55]
	s_add_i32 m0, s90, 0x2000
	s_add_u32 s52, s52, 0xc000
	s_addc_u32 s53, s53, 0
	global_load_lds_dwordx4 v140, s[54:55]
	s_add_i32 s54, s91, s71
	s_mov_b32 m0, s54
	ds_read_b128 v[218:221], v161 offset:56320
	global_load_lds_dwordx4 v144, s[52:53]
	s_add_i32 m0, s54, 0x2000
	ds_read_b128 v[214:217], v161 offset:55296
	global_load_lds_dwordx4 v140, s[52:53]
	s_mov_b32 m0, s79
	ds_read_b128 v[198:201], v161 offset:54272
	global_load_lds_dwordx4 v146, s[50:51]
	s_mov_b32 m0, s80
	ds_read_b128 v[194:197], v161 offset:53248
	global_load_lds_dwordx4 v142, s[50:51]
	s_waitcnt vmcnt(8)
	s_waitcnt lgkmcnt(0)
	s_barrier


; #define PG8_MMA(ai, bj, At, Bt) do { __builtin_amdgcn_s_setprio(1); _Pragma("unroll") for (int m = 0; m < 4; ++m) _Pragma("unroll") for (int n = 0; n < 2; ++n) _Pragma("unroll") for (int k = 0; k < 2; ++k) \
;         acc[ai][bj][m][n] = __builtin_amdgcn_mfma_f32_16x16x32_bf16(Bt[n][k], At[m][k], acc[ai][bj][m][n], 0, 0, 0); __builtin_amdgcn_s_setprio(0); } while (0)
; #define PG8_WAIT_V(n) asm volatile("s_waitcnt vmcnt(" #n ")" ::: "memory")
; #define PG8_WAIT_L(n) asm volatile("s_waitcnt lgkmcnt(" #n ")" ::: "memory")
; #define PG8_BAR __builtin_amdgcn_s_barrier()
; #define PG8_SCHED __builtin_amdgcn_sched_barrier(0)
; template <class Epi, bool ALIGN_EPI>
; __device__ __forceinline__ void gemm_phase(LAS unsigned char* lds, const Gemm g, const StaticOrder& S, const Epi& E, const int tid) {
;     ...
;             PG8_WAIT_V(8); PG8_WAIT_L(0); PG8_BAR; PG8_MMA(1, 0, At, B0); PG8_MMA(1, 1, At, B1); PG8_BAR; PG8_SCHED;
	v_mfma_f32_16x16x32_bf16 v[24:27], v[132:135], v[178:181], v[24:27]
	v_mfma_f32_16x16x32_bf16 v[92:95], v[152:155], v[178:181], v[92:95]
	v_mfma_f32_16x16x32_bf16 v[16:19], v[132:135], v[186:189], v[16:19]
	v_mfma_f32_16x16x32_bf16 v[84:87], v[152:155], v[186:189], v[84:87]
	v_mfma_f32_16x16x32_bf16 v[6:9], v[132:135], v[194:197], v[8:11]
	v_mfma_f32_16x16x32_bf16 v[76:79], v[152:155], v[194:197], v[76:79]
	v_mfma_f32_16x16x32_bf16 v[2:5], v[132:135], v[214:217], v[2:5]
	v_mfma_f32_16x16x32_bf16 v[64:67], v[152:155], v[214:217], v[64:67]
	v_mfma_f32_16x16x32_bf16 v[24:27], v[136:139], v[182:185], v[24:27]
	v_mfma_f32_16x16x32_bf16 v[92:95], v[156:159], v[182:185], v[92:95]
	v_mfma_f32_16x16x32_bf16 v[16:19], v[136:139], v[190:193], v[16:19]
	v_mfma_f32_16x16x32_bf16 v[84:87], v[156:159], v[190:193], v[84:87]
	v_mfma_f32_16x16x32_bf16 v[8:11], v[136:139], v[198:201], v[6:9]
	v_mfma_f32_16x16x32_bf16 v[76:79], v[156:159], v[198:201], v[76:79]
	v_mfma_f32_16x16x32_bf16 v[4:7], v[136:139], v[218:221], v[2:5]
	v_mfma_f32_16x16x32_bf16 v[64:67], v[156:159], v[218:221], v[64:67]


; #define PG8_MMA(ai, bj, At, Bt) do { __builtin_amdgcn_s_setprio(1); _Pragma("unroll") for (int m = 0; m < 4; ++m) _Pragma("unroll") for (int n = 0; n < 2; ++n) _Pragma("unroll") for (int k = 0; k < 2; ++k) \
;         acc[ai][bj][m][n] = __builtin_amdgcn_mfma_f32_16x16x32_bf16(Bt[n][k], At[m][k], acc[ai][bj][m][n], 0, 0, 0); __builtin_amdgcn_s_setprio(0); } while (0)
; #define PG8_WAIT_V(n) asm volatile("s_waitcnt vmcnt(" #n ")" ::: "memory")
; #define PG8_WAIT_L(n) asm volatile("s_waitcnt lgkmcnt(" #n ")" ::: "memory")
; #define PG8_BAR __builtin_amdgcn_s_barrier()
; #define PG8_SCHED __builtin_amdgcn_sched_barrier(0)
; template <class Epi, bool ALIGN_EPI>
; __device__ __forceinline__ void gemm_phase(LAS unsigned char* lds, const Gemm g, const StaticOrder& S, const Epi& E, const int tid) {
;     ...
;             PG8_WAIT_V(8); PG8_WAIT_L(0); PG8_BAR; PG8_MMA(1, 0, At, B0); PG8_MMA(1, 1, At, B1); PG8_BAR; PG8_SCHED;
	v_mfma_f32_16x16x32_bf16 v[32:35], v[162:165], v[178:181], v[32:35]
	v_mfma_f32_16x16x32_bf16 v[72:75], v[170:173], v[178:181], v[72:75]
	v_mfma_f32_16x16x32_bf16 v[28:31], v[162:165], v[186:189], v[28:31]
	v_mfma_f32_16x16x32_bf16 v[96:99], v[170:173], v[186:189], v[96:99]
	v_mfma_f32_16x16x32_bf16 v[20:23], v[162:165], v[194:197], v[20:23]
	v_mfma_f32_16x16x32_bf16 v[56:59], v[170:173], v[194:197], v[56:59]
	v_mfma_f32_16x16x32_bf16 v[12:15], v[162:165], v[214:217], v[12:15]
	v_mfma_f32_16x16x32_bf16 v[44:47], v[170:173], v[214:217], v[44:47]
	v_mfma_f32_16x16x32_bf16 v[32:35], v[166:169], v[182:185], v[32:35]
	v_mfma_f32_16x16x32_bf16 v[72:75], v[174:177], v[182:185], v[72:75]
	v_mfma_f32_16x16x32_bf16 v[28:31], v[166:169], v[190:193], v[28:31]
	v_mfma_f32_16x16x32_bf16 v[96:99], v[174:177], v[190:193], v[96:99]
	v_mfma_f32_16x16x32_bf16 v[20:23], v[166:169], v[198:201], v[20:23]
	v_mfma_f32_16x16x32_bf16 v[56:59], v[174:177], v[198:201], v[56:59]
	v_mfma_f32_16x16x32_bf16 v[12:15], v[166:169], v[218:221], v[12:15]
	v_mfma_f32_16x16x32_bf16 v[44:47], v[174:177], v[218:221], v[44:47]

; #define PG8_STAGE(bufoff, gbase, voff) do { _Pragma("unroll") for (int _i = 0; _i < 2; ++_i) \
;         __builtin_amdgcn_global_load_lds((const unsigned*)((const char*)(gbase) + (voff)[_i]), (LAS unsigned*)(lds + (bufoff) + ldsw + _i * 8192), 16, 0, 0); } while (0)
; #define PG8_LDA(dst, b, h) do { _Pragma("unroll") for (int m = 0; m < 4; ++m) _Pragma("unroll") for (int k = 0; k < 2; ++k) dst[m][k] = *(const LAS bf16x8*)(lds + PG8_SA(b, h) + aoff + m * 2048 + k * 1024); } while (0)
; #define PG8_LDB(dst, b, h) do { _Pragma("unroll") for (int n = 0; n < 2; ++n) _Pragma("unroll") for (int k = 0; k < 2; ++k) dst[n][k] = *(const LAS bf16x8*)(lds + PG8_SB(b, h) + boff + n * 2048 + k * 1024); } while (0)
; #define PG8_BAR __builtin_amdgcn_s_barrier()
; template <class Epi, bool ALIGN_EPI>
; __device__ __forceinline__ void gemm_phase(LAS unsigned char* lds, const Gemm g, const StaticOrder& S, const Epi& E, const int tid) {
;     ...
;         for (int t = 0; t < nt; t += 2) {
;             const bool last = (t == nt - 2);
;             const char* a1 = cA + (size_t)(t + 1) * kstepA;
;             const char* a2 = last ? nA : cA + (size_t)(t + 2) * kstepA; const char* b2 = last ? nB : cB + (size_t)(t + 2) * kstepB;
;             const char* a3 = a2 + kstepA; const char* b3 = b2 + kstepB;
;             PG8_LDB(B0, 0, 0); PG8_LDB(B1, 0, 1); PG8_SCHED; PG8_LDA(At, 0, 0); PG8_STAGE(PG8_SA(1, 1), a1 + hstepA, voffA);
;             PG8_WAIT_V(8); PG8_WAIT_L(0); PG8_BAR; PG8_MMA(0, 0, At, B0); PG8_MMA(0, 1, At, B1); PG8_BAR; PG8_SCHED;
;             PG8_LDA(At, 0, 1); PG8_STAGE(PG8_SB(0, 0), b2, voffB); PG8_STAGE(PG8_SB(0, 1), b2 + hstepB, voffB); PG8_STAGE(PG8_SA(0, 0), a2, voffA);
;             PG8_WAIT_V(8); PG8_WAIT_L(0); PG8_BAR; PG8_MMA(1, 0, At, B0); PG8_MMA(1, 1, At, B1); PG8_BAR; PG8_SCHED;
;             PG8_LDB(B0, 1, 0); PG8_LDB(B1, 1, 1); PG8_SCHED; PG8_LDA(At, 1, 0); PG8_STAGE(PG8_SA(0, 1), a2 + hstepA, voffA);
;             PG8_WAIT_V(8); PG8_WAIT_L(0); PG8_BAR; PG8_MMA(0, 0, At, B0); PG8_MMA(0, 1, At, B1); PG8_BAR; PG8_SCHED;
;             PG8_LDA(At, 1, 1); PG8_STAGE(PG8_SB(1, 0), b3, voffB); PG8_STAGE(PG8_SB(1, 1), b3 + hstepB, voffB); PG8_STAGE(PG8_SA(1, 0), a3, voffA);
;             PG8_WAIT_V(8); PG8_WAIT_L(0); PG8_BAR; PG8_MMA(1, 0, At, B0); PG8_MMA(1, 1, At, B1); PG8_BAR; PG8_SCHED;
;         }
;         if constexpr (ALIGN_EPI) { if (wr == 0) PG8_BAR; }
	s_barrier
	s_add_i32 s89, s89, 2
	s_add_u32 s48, s48, 0x10000
	s_addc_u32 s49, s49, 0
	s_add_u32 vcc_hi, vcc_hi, 0x10000
	s_addc_u32 s88, s88, 0
	s_cmp_gt_u32 s89, 29
	s_cbranch_scc0 .LBB0_211
	s_and_b64 vcc, exec, s[22:23]
	s_cbranch_vccz .LBB0_214
	s_barrier

; #define PG8_STAGE(bufoff, gbase, voff) do { _Pragma("unroll") for (int _i = 0; _i < 2; ++_i) \
;         __builtin_amdgcn_global_load_lds((const unsigned*)((const char*)(gbase) + (voff)[_i]), (LAS unsigned*)(lds + (bufoff) + ldsw + _i * 8192), 16, 0, 0); } while (0)
; #define PG8_LDA(dst, b, h) do { _Pragma("unroll") for (int m = 0; m < 4; ++m) _Pragma("unroll") for (int k = 0; k < 2; ++k) dst[m][k] = *(const LAS bf16x8*)(lds + PG8_SA(b, h) + aoff + m * 2048 + k * 1024); } while (0)
; #define PG8_LDB(dst, b, h) do { _Pragma("unroll") for (int n = 0; n < 2; ++n) _Pragma("unroll") for (int k = 0; k < 2; ++k) dst[n][k] = *(const LAS bf16x8*)(lds + PG8_SB(b, h) + boff + n * 2048 + k * 1024); } while (0)
; #define PG8_SCHED __builtin_amdgcn_sched_barrier(0)
; template <class Epi, bool ALIGN_EPI>
; __device__ __forceinline__ void gemm_phase(LAS unsigned char* lds, const Gemm g, const StaticOrder& S, const Epi& E, const int tid) {
;     ...
;             const bool last = (t == nt - 2);
;             const char* a1 = cA + (size_t)(t + 1) * kstepA;
;             const char* a2 = last ? nA : cA + (size_t)(t + 2) * kstepA; const char* b2 = last ? nB : cB + (size_t)(t + 2) * kstepB;
;             const char* a3 = a2 + kstepA; const char* b3 = b2 + kstepB;
;             PG8_LDB(B0, 0, 0); PG8_LDB(B1, 0, 1); PG8_SCHED; PG8_LDA(At, 0, 0); PG8_STAGE(PG8_SA(1, 1), a1 + hstepA, voffA);
.LBB0_294:
	s_add_u32 s22, s10, 0x4000
	s_addc_u32 s23, s11, 0
	s_cmpk_eq_i32 s86, 0x54
	s_cselect_b32 s42, s48, s22
	s_cselect_b32 s43, s49, s23
	s_cselect_b32 s34, s50, s84
	s_cselect_b32 s35, s51, s85
	s_add_u32 s22, s42, 0x8000
	s_addc_u32 s23, s43, 0
	s_add_i32 s87, 0, 0x10000
	v_add_u32_e32 v0, s87, v154
	s_add_i32 s90, 0, 0x14000
	s_waitcnt lgkmcnt(0)
	ds_read_b128 v[132:135], v0
	ds_read_b128 v[148:151], v0 offset:1024
	ds_read_b128 v[156:159], v0 offset:2048
	ds_read_b128 v[160:163], v0 offset:3072
	v_add_u32_e32 v0, s90, v154
	ds_read_b128 v[164:167], v0
	ds_read_b128 v[168:171], v0 offset:1024
	ds_read_b128 v[172:175], v0 offset:2048
	ds_read_b128 v[176:179], v0 offset:3072
	s_add_i32 m0, s57, 0xc000
	ds_read_b128 v[180:183], v155
	ds_read_b128 v[184:187], v155 offset:1024
	ds_read_b128 v[188:191], v155 offset:2048
	ds_read_b128 v[192:195], v155 offset:3072
	ds_read_b128 v[196:199], v155 offset:4096
	ds_read_b128 v[214:217], v155 offset:5120
	ds_read_b128 v[218:221], v155 offset:6144

; #define PG8_STAGE(bufoff, gbase, voff) do { _Pragma("unroll") for (int _i = 0; _i < 2; ++_i) \
;         __builtin_amdgcn_global_load_lds((const unsigned*)((const char*)(gbase) + (voff)[_i]), (LAS unsigned*)(lds + (bufoff) + ldsw + _i * 8192), 16, 0, 0); } while (0)
; #define PG8_LDA(dst, b, h) do { _Pragma("unroll") for (int m = 0; m < 4; ++m) _Pragma("unroll") for (int k = 0; k < 2; ++k) dst[m][k] = *(const LAS bf16x8*)(lds + PG8_SA(b, h) + aoff + m * 2048 + k * 1024); } while (0)
; #define PG8_LDB(dst, b, h) do { _Pragma("unroll") for (int n = 0; n < 2; ++n) _Pragma("unroll") for (int k = 0; k < 2; ++k) dst[n][k] = *(const LAS bf16x8*)(lds + PG8_SB(b, h) + boff + n * 2048 + k * 1024); } while (0)
; #define PG8_MMA(ai, bj, At, Bt) do { __builtin_amdgcn_s_setprio(1); _Pragma("unroll") for (int m = 0; m < 4; ++m) _Pragma("unroll") for (int n = 0; n < 2; ++n) _Pragma("unroll") for (int k = 0; k < 2; ++k) \
;         acc[ai][bj][m][n] = __builtin_amdgcn_mfma_f32_16x16x32_bf16(Bt[n][k], At[m][k], acc[ai][bj][m][n], 0, 0, 0); __builtin_amdgcn_s_setprio(0); } while (0)
; #define PG8_WAIT_V(n) asm volatile("s_waitcnt vmcnt(" #n ")" ::: "memory")
; #define PG8_WAIT_L(n) asm volatile("s_waitcnt lgkmcnt(" #n ")" ::: "memory")
; #define PG8_BAR __builtin_amdgcn_s_barrier()
; #define PG8_SCHED __builtin_amdgcn_sched_barrier(0)
; template <class Epi, bool ALIGN_EPI>
; __device__ __forceinline__ void gemm_phase(LAS unsigned char* lds, const Gemm g, const StaticOrder& S, const Epi& E, const int tid) {
;     ...
;             PG8_LDB(B0, 0, 0); PG8_LDB(B1, 0, 1); PG8_SCHED; PG8_LDA(At, 0, 0); PG8_STAGE(PG8_SA(1, 1), a1 + hstepA, voffA);
;             PG8_WAIT_V(8); PG8_WAIT_L(0); PG8_BAR; PG8_MMA(0, 0, At, B0); PG8_MMA(0, 1, At, B1); PG8_BAR; PG8_SCHED;
	global_load_lds_dwordx4 v144, s[10:11]
	s_add_i32 m0, s57, 0xe000
	ds_read_b128 v[222:225], v155 offset:7168
	global_load_lds_dwordx4 v146, s[10:11]
	s_waitcnt vmcnt(8)
	s_waitcnt lgkmcnt(0)
	s_barrier


; #define PG8_MMA(ai, bj, At, Bt) do { __builtin_amdgcn_s_setprio(1); _Pragma("unroll") for (int m = 0; m < 4; ++m) _Pragma("unroll") for (int n = 0; n < 2; ++n) _Pragma("unroll") for (int k = 0; k < 2; ++k) \
;         acc[ai][bj][m][n] = __builtin_amdgcn_mfma_f32_16x16x32_bf16(Bt[n][k], At[m][k], acc[ai][bj][m][n], 0, 0, 0); __builtin_amdgcn_s_setprio(0); } while (0)
; #define PG8_WAIT_V(n) asm volatile("s_waitcnt vmcnt(" #n ")" ::: "memory")
; #define PG8_WAIT_L(n) asm volatile("s_waitcnt lgkmcnt(" #n ")" ::: "memory")
; #define PG8_BAR __builtin_amdgcn_s_barrier()
; #define PG8_SCHED __builtin_amdgcn_sched_barrier(0)
; template <class Epi, bool ALIGN_EPI>
; __device__ __forceinline__ void gemm_phase(LAS unsigned char* lds, const Gemm g, const StaticOrder& S, const Epi& E, const int tid) {
;     ...
;             PG8_WAIT_V(8); PG8_WAIT_L(0); PG8_BAR; PG8_MMA(0, 0, At, B0); PG8_MMA(0, 1, At, B1); PG8_BAR; PG8_SCHED;
	v_mfma_f32_16x16x32_bf16 v[8:11], v[132:135], v[180:183], v[8:11]
	v_mfma_f32_16x16x32_bf16 v[56:59], v[156:159], v[180:183], v[56:59]
	v_mfma_f32_16x16x32_bf16 v[52:55], v[132:135], v[188:191], v[52:55]
	v_mfma_f32_16x16x32_bf16 v[48:51], v[156:159], v[188:191], v[48:51]
	v_mfma_f32_16x16x32_bf16 v[44:47], v[132:135], v[196:199], v[44:47]
	v_mfma_f32_16x16x32_bf16 v[40:43], v[156:159], v[196:199], v[40:43]
	v_mfma_f32_16x16x32_bf16 v[36:39], v[132:135], v[218:221], v[36:39]
	v_mfma_f32_16x16x32_bf16 v[32:35], v[156:159], v[218:221], v[32:35]
	v_mfma_f32_16x16x32_bf16 v[8:11], v[148:151], v[184:187], v[8:11]
	v_mfma_f32_16x16x32_bf16 v[56:59], v[160:163], v[184:187], v[56:59]
	v_mfma_f32_16x16x32_bf16 v[52:55], v[148:151], v[192:195], v[52:55]
	v_mfma_f32_16x16x32_bf16 v[48:51], v[160:163], v[192:195], v[48:51]
	v_mfma_f32_16x16x32_bf16 v[44:47], v[148:151], v[214:217], v[44:47]
	v_mfma_f32_16x16x32_bf16 v[40:43], v[160:163], v[214:217], v[40:43]
	v_mfma_f32_16x16x32_bf16 v[36:39], v[148:151], v[222:225], v[36:39]
	v_mfma_f32_16x16x32_bf16 v[32:35], v[160:163], v[222:225], v[32:35]


; #define PG8_MMA(ai, bj, At, Bt) do { __builtin_amdgcn_s_setprio(1); _Pragma("unroll") for (int m = 0; m < 4; ++m) _Pragma("unroll") for (int n = 0; n < 2; ++n) _Pragma("unroll") for (int k = 0; k < 2; ++k) \
;         acc[ai][bj][m][n] = __builtin_amdgcn_mfma_f32_16x16x32_bf16(Bt[n][k], At[m][k], acc[ai][bj][m][n], 0, 0, 0); __builtin_amdgcn_s_setprio(0); } while (0)
; #define PG8_WAIT_V(n) asm volatile("s_waitcnt vmcnt(" #n ")" ::: "memory")
; #define PG8_WAIT_L(n) asm volatile("s_waitcnt lgkmcnt(" #n ")" ::: "memory")
; #define PG8_BAR __builtin_amdgcn_s_barrier()
; #define PG8_SCHED __builtin_amdgcn_sched_barrier(0)
; template <class Epi, bool ALIGN_EPI>
; __device__ __forceinline__ void gemm_phase(LAS unsigned char* lds, const Gemm g, const StaticOrder& S, const Epi& E, const int tid) {
;     ...
;             PG8_WAIT_V(8); PG8_WAIT_L(0); PG8_BAR; PG8_MMA(0, 0, At, B0); PG8_MMA(0, 1, At, B1); PG8_BAR; PG8_SCHED;
	v_mfma_f32_16x16x32_bf16 v[2:5], v[164:167], v[180:183], v[4:7]
	v_mfma_f32_16x16x32_bf16 v[28:31], v[172:175], v[180:183], v[28:31]
	v_mfma_f32_16x16x32_bf16 v[96:99], v[164:167], v[188:191], v[96:99]
	v_mfma_f32_16x16x32_bf16 v[92:95], v[172:175], v[188:191], v[92:95]
	v_mfma_f32_16x16x32_bf16 v[88:91], v[164:167], v[196:199], v[88:91]
	v_mfma_f32_16x16x32_bf16 v[84:87], v[172:175], v[196:199], v[84:87]
	v_mfma_f32_16x16x32_bf16 v[80:83], v[164:167], v[218:221], v[80:83]
	v_mfma_f32_16x16x32_bf16 v[76:79], v[172:175], v[218:221], v[76:79]
	v_mfma_f32_16x16x32_bf16 v[2:5], v[168:171], v[184:187], v[2:5]
	v_mfma_f32_16x16x32_bf16 v[28:31], v[176:179], v[184:187], v[28:31]
	v_mfma_f32_16x16x32_bf16 v[96:99], v[168:171], v[192:195], v[96:99]
	v_mfma_f32_16x16x32_bf16 v[92:95], v[176:179], v[192:195], v[92:95]
	v_mfma_f32_16x16x32_bf16 v[88:91], v[168:171], v[214:217], v[88:91]
	v_mfma_f32_16x16x32_bf16 v[84:87], v[176:179], v[214:217], v[84:87]
	v_mfma_f32_16x16x32_bf16 v[80:83], v[168:171], v[222:225], v[80:83]
	v_mfma_f32_16x16x32_bf16 v[76:79], v[176:179], v[222:225], v[76:79]

; #define PG8_STAGE(bufoff, gbase, voff) do { _Pragma("unroll") for (int _i = 0; _i < 2; ++_i) \
;         __builtin_amdgcn_global_load_lds((const unsigned*)((const char*)(gbase) + (voff)[_i]), (LAS unsigned*)(lds + (bufoff) + ldsw + _i * 8192), 16, 0, 0); } while (0)
; #define PG8_LDA(dst, b, h) do { _Pragma("unroll") for (int m = 0; m < 4; ++m) _Pragma("unroll") for (int k = 0; k < 2; ++k) dst[m][k] = *(const LAS bf16x8*)(lds + PG8_SA(b, h) + aoff + m * 2048 + k * 1024); } while (0)
; #define PG8_MMA(ai, bj, At, Bt) do { __builtin_amdgcn_s_setprio(1); _Pragma("unroll") for (int m = 0; m < 4; ++m) _Pragma("unroll") for (int n = 0; n < 2; ++n) _Pragma("unroll") for (int k = 0; k < 2; ++k) \
;         acc[ai][bj][m][n] = __builtin_amdgcn_mfma_f32_16x16x32_bf16(Bt[n][k], At[m][k], acc[ai][bj][m][n], 0, 0, 0); __builtin_amdgcn_s_setprio(0); } while (0)
; #define PG8_WAIT_V(n) asm volatile("s_waitcnt vmcnt(" #n ")" ::: "memory")
; #define PG8_WAIT_L(n) asm volatile("s_waitcnt lgkmcnt(" #n ")" ::: "memory")
; #define PG8_BAR __builtin_amdgcn_s_barrier()
; #define PG8_SCHED __builtin_amdgcn_sched_barrier(0)
; template <class Epi, bool ALIGN_EPI>
; __device__ __forceinline__ void gemm_phase(LAS unsigned char* lds, const Gemm g, const StaticOrder& S, const Epi& E, const int tid) {
;     ...
;             PG8_WAIT_V(8); PG8_WAIT_L(0); PG8_BAR; PG8_MMA(0, 0, At, B0); PG8_MMA(0, 1, At, B1); PG8_BAR; PG8_SCHED;
;             PG8_LDA(At, 0, 1); PG8_STAGE(PG8_SB(0, 0), b2, voffB); PG8_STAGE(PG8_SB(0, 1), b2 + hstepB, voffB); PG8_STAGE(PG8_SA(0, 0), a2, voffA);
	s_barrier
	s_add_i32 s87, s87, s56
	s_mov_b32 m0, s87
	ds_read_b128 v[180:183], v155 offset:16384
	ds_read_b128 v[184:187], v155 offset:17408
	ds_read_b128 v[188:191], v155 offset:18432
	ds_read_b128 v[192:195], v155 offset:19456


; #define PG8_STAGE(bufoff, gbase, voff) do { _Pragma("unroll") for (int _i = 0; _i < 2; ++_i) \
;         __builtin_amdgcn_global_load_lds((const unsigned*)((const char*)(gbase) + (voff)[_i]), (LAS unsigned*)(lds + (bufoff) + ldsw + _i * 8192), 16, 0, 0); } while (0)
; #define PG8_LDA(dst, b, h) do { _Pragma("unroll") for (int m = 0; m < 4; ++m) _Pragma("unroll") for (int k = 0; k < 2; ++k) dst[m][k] = *(const LAS bf16x8*)(lds + PG8_SA(b, h) + aoff + m * 2048 + k * 1024); } while (0)
; #define PG8_MMA(ai, bj, At, Bt) do { __builtin_amdgcn_s_setprio(1); _Pragma("unroll") for (int m = 0; m < 4; ++m) _Pragma("unroll") for (int n = 0; n < 2; ++n) _Pragma("unroll") for (int k = 0; k < 2; ++k) \
;         acc[ai][bj][m][n] = __builtin_amdgcn_mfma_f32_16x16x32_bf16(Bt[n][k], At[m][k], acc[ai][bj][m][n], 0, 0, 0); __builtin_amdgcn_s_setprio(0); } while (0)
; #define PG8_WAIT_V(n) asm volatile("s_waitcnt vmcnt(" #n ")" ::: "memory")
; #define PG8_WAIT_L(n) asm volatile("s_waitcnt lgkmcnt(" #n ")" ::: "memory")
; #define PG8_BAR __builtin_amdgcn_s_barrier()
; #define PG8_SCHED __builtin_amdgcn_sched_barrier(0)
; template <class Epi, bool ALIGN_EPI>
; __device__ __forceinline__ void gemm_phase(LAS unsigned char* lds, const Gemm g, const StaticOrder& S, const Epi& E, const int tid) {
;     ...
;             PG8_LDA(At, 0, 1); PG8_STAGE(PG8_SB(0, 0), b2, voffB); PG8_STAGE(PG8_SB(0, 1), b2 + hstepB, voffB); PG8_STAGE(PG8_SA(0, 0), a2, voffA);
;             PG8_WAIT_V(8); PG8_WAIT_L(0); PG8_BAR; PG8_MMA(1, 0, At, B0); PG8_MMA(1, 1, At, B1); PG8_BAR; PG8_SCHED;
	global_load_lds_dwordx4 v140, s[34:35]
	s_add_i32 m0, s87, 0x2000
	s_add_u32 s88, s34, 0x4000
	s_addc_u32 s89, s35, 0
	s_add_i32 s87, s90, s56
	global_load_lds_dwordx4 v136, s[34:35]
	s_mov_b32 m0, s87
	ds_read_b128 v[222:225], v155 offset:23552
	global_load_lds_dwordx4 v140, s[88:89]
	s_add_i32 m0, s87, 0x2000
	ds_read_b128 v[218:221], v155 offset:22528
	global_load_lds_dwordx4 v136, s[88:89]
	s_mov_b32 m0, s57
	ds_read_b128 v[214:217], v155 offset:21504
	global_load_lds_dwordx4 v142, s[42:43]
	s_mov_b32 m0, s60
	ds_read_b128 v[196:199], v155 offset:20480
	global_load_lds_dwordx4 v138, s[42:43]
	s_nop 0
	s_waitcnt vmcnt(8)
	s_waitcnt lgkmcnt(0)
	s_barrier


; #define PG8_MMA(ai, bj, At, Bt) do { __builtin_amdgcn_s_setprio(1); _Pragma("unroll") for (int m = 0; m < 4; ++m) _Pragma("unroll") for (int n = 0; n < 2; ++n) _Pragma("unroll") for (int k = 0; k < 2; ++k) \
;         acc[ai][bj][m][n] = __builtin_amdgcn_mfma_f32_16x16x32_bf16(Bt[n][k], At[m][k], acc[ai][bj][m][n], 0, 0, 0); __builtin_amdgcn_s_setprio(0); } while (0)
; #define PG8_WAIT_V(n) asm volatile("s_waitcnt vmcnt(" #n ")" ::: "memory")
; #define PG8_WAIT_L(n) asm volatile("s_waitcnt lgkmcnt(" #n ")" ::: "memory")
; #define PG8_BAR __builtin_amdgcn_s_barrier()
; #define PG8_SCHED __builtin_amdgcn_sched_barrier(0)
; template <class Epi, bool ALIGN_EPI>
; __device__ __forceinline__ void gemm_phase(LAS unsigned char* lds, const Gemm g, const StaticOrder& S, const Epi& E, const int tid) {
;     ...
;             PG8_WAIT_V(8); PG8_WAIT_L(0); PG8_BAR; PG8_MMA(1, 0, At, B0); PG8_MMA(1, 1, At, B1); PG8_BAR; PG8_SCHED;
	v_mfma_f32_16x16x32_bf16 v[24:27], v[132:135], v[180:183], v[24:27]
	v_mfma_f32_16x16x32_bf16 v[20:23], v[156:159], v[180:183], v[20:23]
	v_mfma_f32_16x16x32_bf16 v[64:67], v[132:135], v[188:191], v[64:67]
	v_mfma_f32_16x16x32_bf16 v[72:75], v[156:159], v[188:191], v[72:75]
	v_mfma_f32_16x16x32_bf16 v[16:19], v[132:135], v[196:199], v[16:19]
	v_mfma_f32_16x16x32_bf16 v[12:15], v[156:159], v[196:199], v[12:15]
	v_mfma_f32_16x16x32_bf16 v[60:63], v[132:135], v[218:221], v[60:63]
	v_mfma_f32_16x16x32_bf16 v[68:71], v[156:159], v[218:221], v[68:71]
	v_mfma_f32_16x16x32_bf16 v[24:27], v[148:151], v[184:187], v[24:27]
	v_mfma_f32_16x16x32_bf16 v[20:23], v[160:163], v[184:187], v[20:23]
	v_mfma_f32_16x16x32_bf16 v[64:67], v[148:151], v[192:195], v[64:67]
	v_mfma_f32_16x16x32_bf16 v[72:75], v[160:163], v[192:195], v[72:75]
	v_mfma_f32_16x16x32_bf16 v[16:19], v[148:151], v[214:217], v[16:19]
	v_mfma_f32_16x16x32_bf16 v[12:15], v[160:163], v[214:217], v[12:15]
	v_mfma_f32_16x16x32_bf16 v[60:63], v[148:151], v[222:225], v[60:63]
	v_mfma_f32_16x16x32_bf16 v[68:71], v[160:163], v[222:225], v[68:71]


; #define PG8_MMA(ai, bj, At, Bt) do { __builtin_amdgcn_s_setprio(1); _Pragma("unroll") for (int m = 0; m < 4; ++m) _Pragma("unroll") for (int n = 0; n < 2; ++n) _Pragma("unroll") for (int k = 0; k < 2; ++k) \
;         acc[ai][bj][m][n] = __builtin_amdgcn_mfma_f32_16x16x32_bf16(Bt[n][k], At[m][k], acc[ai][bj][m][n], 0, 0, 0); __builtin_amdgcn_s_setprio(0); } while (0)
; #define PG8_WAIT_V(n) asm volatile("s_waitcnt vmcnt(" #n ")" ::: "memory")
; #define PG8_WAIT_L(n) asm volatile("s_waitcnt lgkmcnt(" #n ")" ::: "memory")
; #define PG8_BAR __builtin_amdgcn_s_barrier()
; #define PG8_SCHED __builtin_amdgcn_sched_barrier(0)
; template <class Epi, bool ALIGN_EPI>
; __device__ __forceinline__ void gemm_phase(LAS unsigned char* lds, const Gemm g, const StaticOrder& S, const Epi& E, const int tid) {
;     ...
;             PG8_WAIT_V(8); PG8_WAIT_L(0); PG8_BAR; PG8_MMA(1, 0, At, B0); PG8_MMA(1, 1, At, B1); PG8_BAR; PG8_SCHED;
	v_mfma_f32_16x16x32_bf16 v[128:131], v[164:167], v[180:183], v[128:131]
	v_mfma_f32_16x16x32_bf16 v[124:127], v[172:175], v[180:183], v[124:127]
	v_mfma_f32_16x16x32_bf16 v[120:123], v[164:167], v[188:191], v[120:123]
	v_mfma_f32_16x16x32_bf16 v[116:119], v[172:175], v[188:191], v[116:119]
	v_mfma_f32_16x16x32_bf16 v[112:115], v[164:167], v[196:199], v[112:115]
	v_mfma_f32_16x16x32_bf16 v[108:111], v[172:175], v[196:199], v[108:111]
	v_mfma_f32_16x16x32_bf16 v[104:107], v[164:167], v[218:221], v[104:107]
	v_mfma_f32_16x16x32_bf16 v[100:103], v[172:175], v[218:221], v[100:103]
	v_mfma_f32_16x16x32_bf16 v[128:131], v[168:171], v[184:187], v[128:131]
	v_mfma_f32_16x16x32_bf16 v[124:127], v[176:179], v[184:187], v[124:127]
	v_mfma_f32_16x16x32_bf16 v[120:123], v[168:171], v[192:195], v[120:123]
	v_mfma_f32_16x16x32_bf16 v[116:119], v[176:179], v[192:195], v[116:119]
	v_mfma_f32_16x16x32_bf16 v[112:115], v[168:171], v[214:217], v[112:115]
	v_mfma_f32_16x16x32_bf16 v[108:111], v[176:179], v[214:217], v[108:111]
	v_mfma_f32_16x16x32_bf16 v[104:107], v[168:171], v[222:225], v[104:107]
	v_mfma_f32_16x16x32_bf16 v[100:103], v[176:179], v[222:225], v[100:103]

; #define PG8_STAGE(bufoff, gbase, voff) do { _Pragma("unroll") for (int _i = 0; _i < 2; ++_i) \
;         __builtin_amdgcn_global_load_lds((const unsigned*)((const char*)(gbase) + (voff)[_i]), (LAS unsigned*)(lds + (bufoff) + ldsw + _i * 8192), 16, 0, 0); } while (0)
; #define PG8_LDA(dst, b, h) do { _Pragma("unroll") for (int m = 0; m < 4; ++m) _Pragma("unroll") for (int k = 0; k < 2; ++k) dst[m][k] = *(const LAS bf16x8*)(lds + PG8_SA(b, h) + aoff + m * 2048 + k * 1024); } while (0)
; #define PG8_LDB(dst, b, h) do { _Pragma("unroll") for (int n = 0; n < 2; ++n) _Pragma("unroll") for (int k = 0; k < 2; ++k) dst[n][k] = *(const LAS bf16x8*)(lds + PG8_SB(b, h) + boff + n * 2048 + k * 1024); } while (0)
; #define PG8_SCHED __builtin_amdgcn_sched_barrier(0)
; template <class Epi, bool ALIGN_EPI>
; __device__ __forceinline__ void gemm_phase(LAS unsigned char* lds, const Gemm g, const StaticOrder& S, const Epi& E, const int tid) {
;     ...
;             PG8_LDB(B0, 1, 0); PG8_LDB(B1, 1, 1); PG8_SCHED; PG8_LDA(At, 1, 0); PG8_STAGE(PG8_SA(0, 1), a2 + hstepA, voffA);
	s_barrier
	s_add_i32 s87, 0, 0x18000
	v_add_u32_e32 v0, s87, v154
	s_add_i32 s88, 0, 0x1c000
	ds_read_b128 v[132:135], v0
	ds_read_b128 v[148:151], v0 offset:1024
	ds_read_b128 v[156:159], v0 offset:2048
	ds_read_b128 v[160:163], v0 offset:3072
	v_add_u32_e32 v0, s88, v154
	ds_read_b128 v[164:167], v0
	ds_read_b128 v[168:171], v0 offset:1024
	ds_read_b128 v[172:175], v0 offset:2048
	ds_read_b128 v[176:179], v0 offset:3072
	s_add_u32 s42, s42, 0x4000
	s_addc_u32 s43, s43, 0
	s_mov_b32 m0, s61
	ds_read_b128 v[180:183], v155 offset:32768
	ds_read_b128 v[184:187], v155 offset:33792
	ds_read_b128 v[188:191], v155 offset:34816
	ds_read_b128 v[192:195], v155 offset:35840
	ds_read_b128 v[196:199], v155 offset:36864
	ds_read_b128 v[214:217], v155 offset:37888
	ds_read_b128 v[218:221], v155 offset:38912

; #define PG8_STAGE(bufoff, gbase, voff) do { _Pragma("unroll") for (int _i = 0; _i < 2; ++_i) \
;         __builtin_amdgcn_global_load_lds((const unsigned*)((const char*)(gbase) + (voff)[_i]), (LAS unsigned*)(lds + (bufoff) + ldsw + _i * 8192), 16, 0, 0); } while (0)
; #define PG8_LDA(dst, b, h) do { _Pragma("unroll") for (int m = 0; m < 4; ++m) _Pragma("unroll") for (int k = 0; k < 2; ++k) dst[m][k] = *(const LAS bf16x8*)(lds + PG8_SA(b, h) + aoff + m * 2048 + k * 1024); } while (0)
; #define PG8_LDB(dst, b, h) do { _Pragma("unroll") for (int n = 0; n < 2; ++n) _Pragma("unroll") for (int k = 0; k < 2; ++k) dst[n][k] = *(const LAS bf16x8*)(lds + PG8_SB(b, h) + boff + n * 2048 + k * 1024); } while (0)
; #define PG8_MMA(ai, bj, At, Bt) do { __builtin_amdgcn_s_setprio(1); _Pragma("unroll") for (int m = 0; m < 4; ++m) _Pragma("unroll") for (int n = 0; n < 2; ++n) _Pragma("unroll") for (int k = 0; k < 2; ++k) \
;         acc[ai][bj][m][n] = __builtin_amdgcn_mfma_f32_16x16x32_bf16(Bt[n][k], At[m][k], acc[ai][bj][m][n], 0, 0, 0); __builtin_amdgcn_s_setprio(0); } while (0)
; #define PG8_WAIT_V(n) asm volatile("s_waitcnt vmcnt(" #n ")" ::: "memory")
; #define PG8_WAIT_L(n) asm volatile("s_waitcnt lgkmcnt(" #n ")" ::: "memory")
; #define PG8_BAR __builtin_amdgcn_s_barrier()
; #define PG8_SCHED __builtin_amdgcn_sched_barrier(0)
; template <class Epi, bool ALIGN_EPI>
; __device__ __forceinline__ void gemm_phase(LAS unsigned char* lds, const Gemm g, const StaticOrder& S, const Epi& E, const int tid) {
;     ...
;             PG8_LDB(B0, 1, 0); PG8_LDB(B1, 1, 1); PG8_SCHED; PG8_LDA(At, 1, 0); PG8_STAGE(PG8_SA(0, 1), a2 + hstepA, voffA);
;             PG8_WAIT_V(8); PG8_WAIT_L(0); PG8_BAR; PG8_MMA(0, 0, At, B0); PG8_MMA(0, 1, At, B1); PG8_BAR; PG8_SCHED;
	global_load_lds_dwordx4 v142, s[42:43]
	s_mov_b32 m0, s71
	ds_read_b128 v[222:225], v155 offset:39936
	global_load_lds_dwordx4 v138, s[42:43]
	s_nop 0
	s_waitcnt vmcnt(8)
	s_waitcnt lgkmcnt(0)
	s_barrier


; #define PG8_MMA(ai, bj, At, Bt) do { __builtin_amdgcn_s_setprio(1); _Pragma("unroll") for (int m = 0; m < 4; ++m) _Pragma("unroll") for (int n = 0; n < 2; ++n) _Pragma("unroll") for (int k = 0; k < 2; ++k) \
;         acc[ai][bj][m][n] = __builtin_amdgcn_mfma_f32_16x16x32_bf16(Bt[n][k], At[m][k], acc[ai][bj][m][n], 0, 0, 0); __builtin_amdgcn_s_setprio(0); } while (0)
; #define PG8_WAIT_V(n) asm volatile("s_waitcnt vmcnt(" #n ")" ::: "memory")
; #define PG8_WAIT_L(n) asm volatile("s_waitcnt lgkmcnt(" #n ")" ::: "memory")
; #define PG8_BAR __builtin_amdgcn_s_barrier()
; #define PG8_SCHED __builtin_amdgcn_sched_barrier(0)
; template <class Epi, bool ALIGN_EPI>
; __device__ __forceinline__ void gemm_phase(LAS unsigned char* lds, const Gemm g, const StaticOrder& S, const Epi& E, const int tid) {
;     ...
;             PG8_WAIT_V(8); PG8_WAIT_L(0); PG8_BAR; PG8_MMA(0, 0, At, B0); PG8_MMA(0, 1, At, B1); PG8_BAR; PG8_SCHED;
	v_mfma_f32_16x16x32_bf16 v[6:9], v[132:135], v[180:183], v[8:11]
	v_mfma_f32_16x16x32_bf16 v[56:59], v[156:159], v[180:183], v[56:59]
	v_mfma_f32_16x16x32_bf16 v[52:55], v[132:135], v[188:191], v[52:55]
	v_mfma_f32_16x16x32_bf16 v[48:51], v[156:159], v[188:191], v[48:51]
	v_mfma_f32_16x16x32_bf16 v[44:47], v[132:135], v[196:199], v[44:47]
	v_mfma_f32_16x16x32_bf16 v[40:43], v[156:159], v[196:199], v[40:43]
	v_mfma_f32_16x16x32_bf16 v[36:39], v[132:135], v[218:221], v[36:39]
	v_mfma_f32_16x16x32_bf16 v[32:35], v[156:159], v[218:221], v[32:35]
	v_mfma_f32_16x16x32_bf16 v[8:11], v[148:151], v[184:187], v[6:9]
	v_mfma_f32_16x16x32_bf16 v[56:59], v[160:163], v[184:187], v[56:59]
	v_mfma_f32_16x16x32_bf16 v[52:55], v[148:151], v[192:195], v[52:55]
	v_mfma_f32_16x16x32_bf16 v[48:51], v[160:163], v[192:195], v[48:51]
	v_mfma_f32_16x16x32_bf16 v[44:47], v[148:151], v[214:217], v[44:47]
	v_mfma_f32_16x16x32_bf16 v[40:43], v[160:163], v[214:217], v[40:43]
	v_mfma_f32_16x16x32_bf16 v[36:39], v[148:151], v[222:225], v[36:39]
	v_mfma_f32_16x16x32_bf16 v[32:35], v[160:163], v[222:225], v[32:35]


; #define PG8_MMA(ai, bj, At, Bt) do { __builtin_amdgcn_s_setprio(1); _Pragma("unroll") for (int m = 0; m < 4; ++m) _Pragma("unroll") for (int n = 0; n < 2; ++n) _Pragma("unroll") for (int k = 0; k < 2; ++k) \
;         acc[ai][bj][m][n] = __builtin_amdgcn_mfma_f32_16x16x32_bf16(Bt[n][k], At[m][k], acc[ai][bj][m][n], 0, 0, 0); __builtin_amdgcn_s_setprio(0); } while (0)
; #define PG8_WAIT_V(n) asm volatile("s_waitcnt vmcnt(" #n ")" ::: "memory")
; #define PG8_WAIT_L(n) asm volatile("s_waitcnt lgkmcnt(" #n ")" ::: "memory")
; #define PG8_BAR __builtin_amdgcn_s_barrier()
; #define PG8_SCHED __builtin_amdgcn_sched_barrier(0)
; template <class Epi, bool ALIGN_EPI>
; __device__ __forceinline__ void gemm_phase(LAS unsigned char* lds, const Gemm g, const StaticOrder& S, const Epi& E, const int tid) {
;     ...
;             PG8_WAIT_V(8); PG8_WAIT_L(0); PG8_BAR; PG8_MMA(0, 0, At, B0); PG8_MMA(0, 1, At, B1); PG8_BAR; PG8_SCHED;
	v_mfma_f32_16x16x32_bf16 v[2:5], v[164:167], v[180:183], v[2:5]
	v_mfma_f32_16x16x32_bf16 v[28:31], v[172:175], v[180:183], v[28:31]
	v_mfma_f32_16x16x32_bf16 v[96:99], v[164:167], v[188:191], v[96:99]
	v_mfma_f32_16x16x32_bf16 v[92:95], v[172:175], v[188:191], v[92:95]
	v_mfma_f32_16x16x32_bf16 v[88:91], v[164:167], v[196:199], v[88:91]
	v_mfma_f32_16x16x32_bf16 v[84:87], v[172:175], v[196:199], v[84:87]
	v_mfma_f32_16x16x32_bf16 v[80:83], v[164:167], v[218:221], v[80:83]
	v_mfma_f32_16x16x32_bf16 v[76:79], v[172:175], v[218:221], v[76:79]
	v_mfma_f32_16x16x32_bf16 v[4:7], v[168:171], v[184:187], v[2:5]
	v_mfma_f32_16x16x32_bf16 v[28:31], v[176:179], v[184:187], v[28:31]
	v_mfma_f32_16x16x32_bf16 v[96:99], v[168:171], v[192:195], v[96:99]
	v_mfma_f32_16x16x32_bf16 v[92:95], v[176:179], v[192:195], v[92:95]
	v_mfma_f32_16x16x32_bf16 v[88:91], v[168:171], v[214:217], v[88:91]
	v_mfma_f32_16x16x32_bf16 v[84:87], v[176:179], v[214:217], v[84:87]
	v_mfma_f32_16x16x32_bf16 v[80:83], v[168:171], v[222:225], v[80:83]
	v_mfma_f32_16x16x32_bf16 v[76:79], v[176:179], v[222:225], v[76:79]

; #define PG8_STAGE(bufoff, gbase, voff) do { _Pragma("unroll") for (int _i = 0; _i < 2; ++_i) \
;         __builtin_amdgcn_global_load_lds((const unsigned*)((const char*)(gbase) + (voff)[_i]), (LAS unsigned*)(lds + (bufoff) + ldsw + _i * 8192), 16, 0, 0); } while (0)
; #define PG8_LDA(dst, b, h) do { _Pragma("unroll") for (int m = 0; m < 4; ++m) _Pragma("unroll") for (int k = 0; k < 2; ++k) dst[m][k] = *(const LAS bf16x8*)(lds + PG8_SA(b, h) + aoff + m * 2048 + k * 1024); } while (0)
; template <class Epi, bool ALIGN_EPI>
; __device__ __forceinline__ void gemm_phase(LAS unsigned char* lds, const Gemm g, const StaticOrder& S, const Epi& E, const int tid) {
;     ...
;             PG8_LDA(At, 1, 1); PG8_STAGE(PG8_SB(1, 0), b3, voffB); PG8_STAGE(PG8_SB(1, 1), b3 + hstepB, voffB); PG8_STAGE(PG8_SA(1, 0), a3, voffA);
	s_barrier
	s_add_u32 s42, s34, 0x8000
	s_addc_u32 s43, s35, 0
	s_add_i32 s87, s87, s56
	s_mov_b32 m0, s87
	ds_read_b128 v[180:183], v155 offset:49152
	ds_read_b128 v[184:187], v155 offset:50176
	ds_read_b128 v[188:191], v155 offset:51200
	ds_read_b128 v[192:195], v155 offset:52224


; #define PG8_STAGE(bufoff, gbase, voff) do { _Pragma("unroll") for (int _i = 0; _i < 2; ++_i) \
;         __builtin_amdgcn_global_load_lds((const unsigned*)((const char*)(gbase) + (voff)[_i]), (LAS unsigned*)(lds + (bufoff) + ldsw + _i * 8192), 16, 0, 0); } while (0)
; #define PG8_LDA(dst, b, h) do { _Pragma("unroll") for (int m = 0; m < 4; ++m) _Pragma("unroll") for (int k = 0; k < 2; ++k) dst[m][k] = *(const LAS bf16x8*)(lds + PG8_SA(b, h) + aoff + m * 2048 + k * 1024); } while (0)
; #define PG8_MMA(ai, bj, At, Bt) do { __builtin_amdgcn_s_setprio(1); _Pragma("unroll") for (int m = 0; m < 4; ++m) _Pragma("unroll") for (int n = 0; n < 2; ++n) _Pragma("unroll") for (int k = 0; k < 2; ++k) \
;         acc[ai][bj][m][n] = __builtin_amdgcn_mfma_f32_16x16x32_bf16(Bt[n][k], At[m][k], acc[ai][bj][m][n], 0, 0, 0); __builtin_amdgcn_s_setprio(0); } while (0)
; #define PG8_WAIT_V(n) asm volatile("s_waitcnt vmcnt(" #n ")" ::: "memory")
; #define PG8_WAIT_L(n) asm volatile("s_waitcnt lgkmcnt(" #n ")" ::: "memory")
; #define PG8_BAR __builtin_amdgcn_s_barrier()
; #define PG8_SCHED __builtin_amdgcn_sched_barrier(0)
; template <class Epi, bool ALIGN_EPI>
; __device__ __forceinline__ void gemm_phase(LAS unsigned char* lds, const Gemm g, const StaticOrder& S, const Epi& E, const int tid) {
;     ...
;             PG8_LDA(At, 1, 1); PG8_STAGE(PG8_SB(1, 0), b3, voffB); PG8_STAGE(PG8_SB(1, 1), b3 + hstepB, voffB); PG8_STAGE(PG8_SA(1, 0), a3, voffA);
;             PG8_WAIT_V(8); PG8_WAIT_L(0); PG8_BAR; PG8_MMA(1, 0, At, B0); PG8_MMA(1, 1, At, B1); PG8_BAR; PG8_SCHED;
	global_load_lds_dwordx4 v140, s[42:43]
	s_add_i32 m0, s87, 0x2000
	s_add_u32 s34, s34, 0xc000
	s_addc_u32 s35, s35, 0
	global_load_lds_dwordx4 v136, s[42:43]
	s_add_i32 s42, s88, s56
	s_mov_b32 m0, s42
	ds_read_b128 v[222:225], v155 offset:56320
	global_load_lds_dwordx4 v140, s[34:35]
	s_add_i32 m0, s42, 0x2000
	ds_read_b128 v[218:221], v155 offset:55296
	global_load_lds_dwordx4 v136, s[34:35]
	s_mov_b32 m0, s76
	ds_read_b128 v[214:217], v155 offset:54272
	global_load_lds_dwordx4 v142, s[22:23]
	s_mov_b32 m0, s77
	ds_read_b128 v[196:199], v155 offset:53248
	global_load_lds_dwordx4 v138, s[22:23]
	s_waitcnt vmcnt(8)
	s_waitcnt lgkmcnt(0)
	s_barrier


; #define PG8_MMA(ai, bj, At, Bt) do { __builtin_amdgcn_s_setprio(1); _Pragma("unroll") for (int m = 0; m < 4; ++m) _Pragma("unroll") for (int n = 0; n < 2; ++n) _Pragma("unroll") for (int k = 0; k < 2; ++k) \
;         acc[ai][bj][m][n] = __builtin_amdgcn_mfma_f32_16x16x32_bf16(Bt[n][k], At[m][k], acc[ai][bj][m][n], 0, 0, 0); __builtin_amdgcn_s_setprio(0); } while (0)
; #define PG8_WAIT_V(n) asm volatile("s_waitcnt vmcnt(" #n ")" ::: "memory")
; #define PG8_WAIT_L(n) asm volatile("s_waitcnt lgkmcnt(" #n ")" ::: "memory")
; #define PG8_BAR __builtin_amdgcn_s_barrier()
; #define PG8_SCHED __builtin_amdgcn_sched_barrier(0)
; template <class Epi, bool ALIGN_EPI>
; __device__ __forceinline__ void gemm_phase(LAS unsigned char* lds, const Gemm g, const StaticOrder& S, const Epi& E, const int tid) {
;     ...
;             PG8_WAIT_V(8); PG8_WAIT_L(0); PG8_BAR; PG8_MMA(1, 0, At, B0); PG8_MMA(1, 1, At, B1); PG8_BAR; PG8_SCHED;
	v_mfma_f32_16x16x32_bf16 v[24:27], v[132:135], v[180:183], v[24:27]
	v_mfma_f32_16x16x32_bf16 v[20:23], v[156:159], v[180:183], v[20:23]
	v_mfma_f32_16x16x32_bf16 v[64:67], v[132:135], v[188:191], v[64:67]
	v_mfma_f32_16x16x32_bf16 v[72:75], v[156:159], v[188:191], v[72:75]
	v_mfma_f32_16x16x32_bf16 v[16:19], v[132:135], v[196:199], v[16:19]
	v_mfma_f32_16x16x32_bf16 v[12:15], v[156:159], v[196:199], v[12:15]
	v_mfma_f32_16x16x32_bf16 v[60:63], v[132:135], v[218:221], v[60:63]
	v_mfma_f32_16x16x32_bf16 v[68:71], v[156:159], v[218:221], v[68:71]
	v_mfma_f32_16x16x32_bf16 v[24:27], v[148:151], v[184:187], v[24:27]
	v_mfma_f32_16x16x32_bf16 v[20:23], v[160:163], v[184:187], v[20:23]
	v_mfma_f32_16x16x32_bf16 v[64:67], v[148:151], v[192:195], v[64:67]
	v_mfma_f32_16x16x32_bf16 v[72:75], v[160:163], v[192:195], v[72:75]
	v_mfma_f32_16x16x32_bf16 v[16:19], v[148:151], v[214:217], v[16:19]
	v_mfma_f32_16x16x32_bf16 v[12:15], v[160:163], v[214:217], v[12:15]
	v_mfma_f32_16x16x32_bf16 v[60:63], v[148:151], v[222:225], v[60:63]
	v_mfma_f32_16x16x32_bf16 v[68:71], v[160:163], v[222:225], v[68:71]


; #define PG8_MMA(ai, bj, At, Bt) do { __builtin_amdgcn_s_setprio(1); _Pragma("unroll") for (int m = 0; m < 4; ++m) _Pragma("unroll") for (int n = 0; n < 2; ++n) _Pragma("unroll") for (int k = 0; k < 2; ++k) \
;         acc[ai][bj][m][n] = __builtin_amdgcn_mfma_f32_16x16x32_bf16(Bt[n][k], At[m][k], acc[ai][bj][m][n], 0, 0, 0); __builtin_amdgcn_s_setprio(0); } while (0)
; #define PG8_WAIT_V(n) asm volatile("s_waitcnt vmcnt(" #n ")" ::: "memory")
; #define PG8_WAIT_L(n) asm volatile("s_waitcnt lgkmcnt(" #n ")" ::: "memory")
; #define PG8_BAR __builtin_amdgcn_s_barrier()
; #define PG8_SCHED __builtin_amdgcn_sched_barrier(0)
; template <class Epi, bool ALIGN_EPI>
; __device__ __forceinline__ void gemm_phase(LAS unsigned char* lds, const Gemm g, const StaticOrder& S, const Epi& E, const int tid) {
;     ...
;             PG8_WAIT_V(8); PG8_WAIT_L(0); PG8_BAR; PG8_MMA(1, 0, At, B0); PG8_MMA(1, 1, At, B1); PG8_BAR; PG8_SCHED;
	v_mfma_f32_16x16x32_bf16 v[128:131], v[164:167], v[180:183], v[128:131]
	v_mfma_f32_16x16x32_bf16 v[124:127], v[172:175], v[180:183], v[124:127]
	v_mfma_f32_16x16x32_bf16 v[120:123], v[164:167], v[188:191], v[120:123]
	v_mfma_f32_16x16x32_bf16 v[116:119], v[172:175], v[188:191], v[116:119]
	v_mfma_f32_16x16x32_bf16 v[112:115], v[164:167], v[196:199], v[112:115]
	v_mfma_f32_16x16x32_bf16 v[108:111], v[172:175], v[196:199], v[108:111]
	v_mfma_f32_16x16x32_bf16 v[104:107], v[164:167], v[218:221], v[104:107]
	v_mfma_f32_16x16x32_bf16 v[100:103], v[172:175], v[218:221], v[100:103]
	v_mfma_f32_16x16x32_bf16 v[128:131], v[168:171], v[184:187], v[128:131]
	v_mfma_f32_16x16x32_bf16 v[124:127], v[176:179], v[184:187], v[124:127]
	v_mfma_f32_16x16x32_bf16 v[120:123], v[168:171], v[192:195], v[120:123]
	v_mfma_f32_16x16x32_bf16 v[116:119], v[176:179], v[192:195], v[116:119]
	v_mfma_f32_16x16x32_bf16 v[112:115], v[168:171], v[214:217], v[112:115]
	v_mfma_f32_16x16x32_bf16 v[108:111], v[176:179], v[214:217], v[108:111]
	v_mfma_f32_16x16x32_bf16 v[104:107], v[168:171], v[222:225], v[104:107]
	v_mfma_f32_16x16x32_bf16 v[100:103], v[176:179], v[222:225], v[100:103]

; #define PG8_BAR __builtin_amdgcn_s_barrier()
; template <class Epi, bool ALIGN_EPI>
; __device__ __forceinline__ void gemm_phase(LAS unsigned char* lds, const Gemm g, const StaticOrder& S, const Epi& E, const int tid) {
;     ...
;         for (int t = 0; t < nt; t += 2) {
;             const bool last = (t == nt - 2);
;             const char* a1 = cA + (size_t)(t + 1) * kstepA;
;             const char* a2 = last ? nA : cA + (size_t)(t + 2) * kstepA; const char* b2 = last ? nB : cB + (size_t)(t + 2) * kstepB;
;             const char* a3 = a2 + kstepA; const char* b3 = b2 + kstepB;
;             PG8_LDB(B0, 0, 0); PG8_LDB(B1, 0, 1); PG8_SCHED; PG8_LDA(At, 0, 0); PG8_STAGE(PG8_SA(1, 1), a1 + hstepA, voffA);
;             PG8_WAIT_V(8); PG8_WAIT_L(0); PG8_BAR; PG8_MMA(0, 0, At, B0); PG8_MMA(0, 1, At, B1); PG8_BAR; PG8_SCHED;
;             PG8_LDA(At, 0, 1); PG8_STAGE(PG8_SB(0, 0), b2, voffB); PG8_STAGE(PG8_SB(0, 1), b2 + hstepB, voffB); PG8_STAGE(PG8_SA(0, 0), a2, voffA);
;             PG8_WAIT_V(8); PG8_WAIT_L(0); PG8_BAR; PG8_MMA(1, 0, At, B0); PG8_MMA(1, 1, At, B1); PG8_BAR; PG8_SCHED;
;             PG8_LDB(B0, 1, 0); PG8_LDB(B1, 1, 1); PG8_SCHED; PG8_LDA(At, 1, 0); PG8_STAGE(PG8_SA(0, 1), a2 + hstepA, voffA);
;             PG8_WAIT_V(8); PG8_WAIT_L(0); PG8_BAR; PG8_MMA(0, 0, At, B0); PG8_MMA(0, 1, At, B1); PG8_BAR; PG8_SCHED;
;             PG8_LDA(At, 1, 1); PG8_STAGE(PG8_SB(1, 0), b3, voffB); PG8_STAGE(PG8_SB(1, 1), b3 + hstepB, voffB); PG8_STAGE(PG8_SA(1, 0), a3, voffA);
;             PG8_WAIT_V(8); PG8_WAIT_L(0); PG8_BAR; PG8_MMA(1, 0, At, B0); PG8_MMA(1, 1, At, B1); PG8_BAR; PG8_SCHED;
;         }
;         if constexpr (ALIGN_EPI) { if (wr == 0) PG8_BAR; }
;         E(acc, cur, wr, wc, lds, rs_pm);
;     __device__ __forceinline__ void operator()(f32x4 (&acc)[2][2][4][2], const Unit& u, int wr, int wc, LAS unsigned char* lds, int& rs_pm) const {
;         int fr, fq; epi_lane(fr, fq);
;         const int row0 = u.pm * BM + wr * 64 + fr, col0 = u.pn * BM + wc * 32 + 8 * fq; u32x4 zb = zero_frag();
; #pragma unroll
;         for (int ai = 0; ai < 2; ++ai)
; #pragma unroll
;             for (int m = 0; m < 4; ++m) { float ss = 0.f;
;                 bf16* const xrow = xb + (((size_t)(u.pm * 32 + u.pn * 4 + (wc >> 1)) * BM + (wr * 64 + fr + ai * HALF + m * 16)) * 64 + (wc & 1) * 32 + 8 * fq);
; #pragma unroll
;                 for (int bj = 0; bj < 2; ++bj) {
	s_barrier
	s_add_i32 s86, s86, 2
	s_add_u32 s84, s84, 0x10000
	s_addc_u32 s85, s85, 0
	s_add_u32 s10, s10, 0x10000
	s_addc_u32 s11, s11, 0
	s_cmpk_gt_u32 s86, 0x55
	s_cbranch_scc0 .LBB0_294
	v_and_b32_e32 v222, 15, v238
	v_lshrrev_b32_e32 v156, 4, v238
	s_lshl_b32 s100, s82, 5
	s_lshl_b32 s101, s83, 2
	v_lshlrev_b32_e32 v222, 7, v222
	s_add_i32 s100, s100, s101
	s_or_b32 s100, s100, s78
	v_lshl_or_b32 v222, v156, 4, v222
	s_ashr_i32 s101, s100, 31
	s_lshl_b64 s[100:101], s[100:101], 15
	s_add_u32 s98, s72, s100
	s_addc_u32 s99, s73, s101
	s_add_u32 s98, s98, s30
	s_addc_u32 s99, s99, s31
	s_lshl_b32 s100, s75, 7
	s_add_u32 s98, s98, s100
	s_addc_u32 s99, s99, 0
	s_lshl_b32 s100, s82, 15
	s_lshl_b32 s101, s75, 7
	s_add_i32 s100, s100, s101
	s_lshl_b32 s101, s83, 4
	s_add_i32 s100, s100, s101
	s_lshl_b32 s101, s74, 2
	s_add_i32 s100, s100, s101
	s_add_u32 s22, s44, s100
	s_addc_u32 s23, s45, 0
	global_load_dwordx4 v[176:179], v222, s[98:99]
	s_add_u32 s100, s98, 0x10000
	s_addc_u32 s101, s99, 0
	global_load_dwordx4 v[180:183], v222, s[100:101]
	global_load_dwordx4 v[184:187], v222, s[98:99] offset:2048
	s_add_u32 s100, s98, 0x10000
	s_addc_u32 s101, s99, 0
	global_load_dwordx4 v[188:191], v222, s[100:101] offset:2048
	s_add_u32 s100, s98, 0x1000
	s_addc_u32 s101, s99, 0
	global_load_dwordx4 v[192:195], v222, s[100:101]
	s_add_u32 s100, s98, 0x11000
	s_addc_u32 s101, s99, 0
	global_load_dwordx4 v[196:199], v222, s[100:101]
	s_add_u32 s100, s98, 0x1000
	s_addc_u32 s101, s99, 0
	global_load_dwordx4 v[214:217], v222, s[100:101] offset:2048
	s_add_u32 s100, s98, 0x11000
	s_addc_u32 s101, s99, 0
	global_load_dwordx4 v[218:221], v222, s[100:101] offset:2048
	s_and_b64 vcc, exec, s[46:47]
	s_cbranch_vccz .LBB0_297
	s_barrier

; #define PG8_STAGE(bufoff, gbase, voff) do { _Pragma("unroll") for (int _i = 0; _i < 2; ++_i) \
;         __builtin_amdgcn_global_load_lds((const unsigned*)((const char*)(gbase) + (voff)[_i]), (LAS unsigned*)(lds + (bufoff) + ldsw + _i * 8192), 16, 0, 0); } while (0)
; #define PG8_LDA(dst, b, h) do { _Pragma("unroll") for (int m = 0; m < 4; ++m) _Pragma("unroll") for (int k = 0; k < 2; ++k) dst[m][k] = *(const LAS bf16x8*)(lds + PG8_SA(b, h) + aoff + m * 2048 + k * 1024); } while (0)
; #define PG8_LDB(dst, b, h) do { _Pragma("unroll") for (int n = 0; n < 2; ++n) _Pragma("unroll") for (int k = 0; k < 2; ++k) dst[n][k] = *(const LAS bf16x8*)(lds + PG8_SB(b, h) + boff + n * 2048 + k * 1024); } while (0)
; #define PG8_SCHED __builtin_amdgcn_sched_barrier(0)
; template <class Epi, bool ALIGN_EPI>
; __device__ __forceinline__ void gemm_phase(LAS unsigned char* lds, const Gemm g, const StaticOrder& S, const Epi& E, const int tid) {
;     ...
;             const bool last = (t == nt - 2);
;             const char* a1 = cA + (size_t)(t + 1) * kstepA;
;             const char* a2 = last ? nA : cA + (size_t)(t + 2) * kstepA; const char* b2 = last ? nB : cB + (size_t)(t + 2) * kstepB;
;             const char* a3 = a2 + kstepA; const char* b3 = b2 + kstepB;
;             PG8_LDB(B0, 0, 0); PG8_LDB(B1, 0, 1); PG8_SCHED; PG8_LDA(At, 0, 0); PG8_STAGE(PG8_SA(1, 1), a1 + hstepA, voffA);
.LBB0_385:
	s_add_u32 s50, s48, 0x4000
	s_addc_u32 s51, s49, 0
	s_cmp_eq_u32 s88, 28
	s_cselect_b32 s54, s84, s50
	s_cselect_b32 s55, s43, s51
	s_cselect_b32 s52, s85, s86
	s_cselect_b32 s53, s41, s87
	s_add_u32 s50, s54, 0x8000
	s_addc_u32 s51, s55, 0
	s_add_i32 s89, 0, 0x10000
	v_add_u32_e32 v0, s89, v167
	s_add_i32 s92, 0, 0x14000
	ds_read_b128 v[132:135], v0
	ds_read_b128 v[136:139], v0 offset:1024
	ds_read_b128 v[152:155], v0 offset:2048
	ds_read_b128 v[156:159], v0 offset:3072
	v_add_u32_e32 v0, s92, v167
	ds_read_b128 v[160:163], v0
	ds_read_b128 v[172:175], v0 offset:1024
	ds_read_b128 v[176:179], v0 offset:2048
	ds_read_b128 v[180:183], v0 offset:3072
	s_add_i32 m0, s71, 0xc000
	ds_read_b128 v[184:187], v171
	ds_read_b128 v[188:191], v171 offset:1024
	ds_read_b128 v[192:195], v171 offset:2048
	ds_read_b128 v[196:199], v171 offset:3072
	ds_read_b128 v[214:217], v171 offset:4096
	ds_read_b128 v[218:221], v171 offset:5120
	ds_read_b128 v[222:225], v171 offset:6144

; #define PG8_STAGE(bufoff, gbase, voff) do { _Pragma("unroll") for (int _i = 0; _i < 2; ++_i) \
;         __builtin_amdgcn_global_load_lds((const unsigned*)((const char*)(gbase) + (voff)[_i]), (LAS unsigned*)(lds + (bufoff) + ldsw + _i * 8192), 16, 0, 0); } while (0)
; #define PG8_LDA(dst, b, h) do { _Pragma("unroll") for (int m = 0; m < 4; ++m) _Pragma("unroll") for (int k = 0; k < 2; ++k) dst[m][k] = *(const LAS bf16x8*)(lds + PG8_SA(b, h) + aoff + m * 2048 + k * 1024); } while (0)
; #define PG8_LDB(dst, b, h) do { _Pragma("unroll") for (int n = 0; n < 2; ++n) _Pragma("unroll") for (int k = 0; k < 2; ++k) dst[n][k] = *(const LAS bf16x8*)(lds + PG8_SB(b, h) + boff + n * 2048 + k * 1024); } while (0)
; #define PG8_MMA(ai, bj, At, Bt) do { __builtin_amdgcn_s_setprio(1); _Pragma("unroll") for (int m = 0; m < 4; ++m) _Pragma("unroll") for (int n = 0; n < 2; ++n) _Pragma("unroll") for (int k = 0; k < 2; ++k) \
;         acc[ai][bj][m][n] = __builtin_amdgcn_mfma_f32_16x16x32_bf16(Bt[n][k], At[m][k], acc[ai][bj][m][n], 0, 0, 0); __builtin_amdgcn_s_setprio(0); } while (0)
; #define PG8_WAIT_V(n) asm volatile("s_waitcnt vmcnt(" #n ")" ::: "memory")
; #define PG8_WAIT_L(n) asm volatile("s_waitcnt lgkmcnt(" #n ")" ::: "memory")
; #define PG8_BAR __builtin_amdgcn_s_barrier()
; #define PG8_SCHED __builtin_amdgcn_sched_barrier(0)
; template <class Epi, bool ALIGN_EPI>
; __device__ __forceinline__ void gemm_phase(LAS unsigned char* lds, const Gemm g, const StaticOrder& S, const Epi& E, const int tid) {
;     ...
;             PG8_LDB(B0, 0, 0); PG8_LDB(B1, 0, 1); PG8_SCHED; PG8_LDA(At, 0, 0); PG8_STAGE(PG8_SA(1, 1), a1 + hstepA, voffA);
;             PG8_WAIT_V(8); PG8_WAIT_L(0); PG8_BAR; PG8_MMA(0, 0, At, B0); PG8_MMA(0, 1, At, B1); PG8_BAR; PG8_SCHED;
	global_load_lds_dwordx4 v148, s[48:49]
	s_add_i32 m0, s71, 0xe000
	ds_read_b128 v[226:229], v171 offset:7168
	global_load_lds_dwordx4 v150, s[48:49]
	s_waitcnt vmcnt(8)
	s_waitcnt lgkmcnt(0)
	s_barrier


; #define PG8_MMA(ai, bj, At, Bt) do { __builtin_amdgcn_s_setprio(1); _Pragma("unroll") for (int m = 0; m < 4; ++m) _Pragma("unroll") for (int n = 0; n < 2; ++n) _Pragma("unroll") for (int k = 0; k < 2; ++k) \
;         acc[ai][bj][m][n] = __builtin_amdgcn_mfma_f32_16x16x32_bf16(Bt[n][k], At[m][k], acc[ai][bj][m][n], 0, 0, 0); __builtin_amdgcn_s_setprio(0); } while (0)
; #define PG8_WAIT_V(n) asm volatile("s_waitcnt vmcnt(" #n ")" ::: "memory")
; #define PG8_WAIT_L(n) asm volatile("s_waitcnt lgkmcnt(" #n ")" ::: "memory")
; #define PG8_BAR __builtin_amdgcn_s_barrier()
; #define PG8_SCHED __builtin_amdgcn_sched_barrier(0)
; template <class Epi, bool ALIGN_EPI>
; __device__ __forceinline__ void gemm_phase(LAS unsigned char* lds, const Gemm g, const StaticOrder& S, const Epi& E, const int tid) {
;     ...
;             PG8_WAIT_V(8); PG8_WAIT_L(0); PG8_BAR; PG8_MMA(0, 0, At, B0); PG8_MMA(0, 1, At, B1); PG8_BAR; PG8_SCHED;
	v_mfma_f32_16x16x32_bf16 v[128:131], v[132:135], v[184:187], v[128:131]
	v_mfma_f32_16x16x32_bf16 v[116:119], v[152:155], v[184:187], v[116:119]
	v_mfma_f32_16x16x32_bf16 v[124:127], v[132:135], v[192:195], v[124:127]
	v_mfma_f32_16x16x32_bf16 v[108:111], v[152:155], v[192:195], v[108:111]
	v_mfma_f32_16x16x32_bf16 v[120:123], v[132:135], v[214:217], v[120:123]
	v_mfma_f32_16x16x32_bf16 v[100:103], v[152:155], v[214:217], v[100:103]
	v_mfma_f32_16x16x32_bf16 v[112:115], v[132:135], v[222:225], v[112:115]
	v_mfma_f32_16x16x32_bf16 v[92:95], v[152:155], v[222:225], v[92:95]
	v_mfma_f32_16x16x32_bf16 v[128:131], v[136:139], v[188:191], v[128:131]
	v_mfma_f32_16x16x32_bf16 v[116:119], v[156:159], v[188:191], v[116:119]
	v_mfma_f32_16x16x32_bf16 v[124:127], v[136:139], v[196:199], v[124:127]
	v_mfma_f32_16x16x32_bf16 v[108:111], v[156:159], v[196:199], v[108:111]
	v_mfma_f32_16x16x32_bf16 v[120:123], v[136:139], v[218:221], v[120:123]
	v_mfma_f32_16x16x32_bf16 v[100:103], v[156:159], v[218:221], v[100:103]
	v_mfma_f32_16x16x32_bf16 v[112:115], v[136:139], v[226:229], v[112:115]
	v_mfma_f32_16x16x32_bf16 v[92:95], v[156:159], v[226:229], v[92:95]


; #define PG8_MMA(ai, bj, At, Bt) do { __builtin_amdgcn_s_setprio(1); _Pragma("unroll") for (int m = 0; m < 4; ++m) _Pragma("unroll") for (int n = 0; n < 2; ++n) _Pragma("unroll") for (int k = 0; k < 2; ++k) \
;         acc[ai][bj][m][n] = __builtin_amdgcn_mfma_f32_16x16x32_bf16(Bt[n][k], At[m][k], acc[ai][bj][m][n], 0, 0, 0); __builtin_amdgcn_s_setprio(0); } while (0)
; #define PG8_WAIT_V(n) asm volatile("s_waitcnt vmcnt(" #n ")" ::: "memory")
; #define PG8_WAIT_L(n) asm volatile("s_waitcnt lgkmcnt(" #n ")" ::: "memory")
; #define PG8_BAR __builtin_amdgcn_s_barrier()
; #define PG8_SCHED __builtin_amdgcn_sched_barrier(0)
; template <class Epi, bool ALIGN_EPI>
; __device__ __forceinline__ void gemm_phase(LAS unsigned char* lds, const Gemm g, const StaticOrder& S, const Epi& E, const int tid) {
;     ...
;             PG8_WAIT_V(8); PG8_WAIT_L(0); PG8_BAR; PG8_MMA(0, 0, At, B0); PG8_MMA(0, 1, At, B1); PG8_BAR; PG8_SCHED;
	v_mfma_f32_16x16x32_bf16 v[104:107], v[160:163], v[184:187], v[104:107]
	v_mfma_f32_16x16x32_bf16 v[80:83], v[176:179], v[184:187], v[80:83]
	v_mfma_f32_16x16x32_bf16 v[96:99], v[160:163], v[192:195], v[96:99]
	v_mfma_f32_16x16x32_bf16 v[68:71], v[176:179], v[192:195], v[68:71]
	v_mfma_f32_16x16x32_bf16 v[88:91], v[160:163], v[214:217], v[88:91]
	v_mfma_f32_16x16x32_bf16 v[60:63], v[176:179], v[214:217], v[60:63]
	v_mfma_f32_16x16x32_bf16 v[76:79], v[160:163], v[222:225], v[76:79]
	v_mfma_f32_16x16x32_bf16 v[48:51], v[176:179], v[222:225], v[48:51]
	v_mfma_f32_16x16x32_bf16 v[104:107], v[172:175], v[188:191], v[104:107]
	v_mfma_f32_16x16x32_bf16 v[80:83], v[180:183], v[188:191], v[80:83]
	v_mfma_f32_16x16x32_bf16 v[96:99], v[172:175], v[196:199], v[96:99]
	v_mfma_f32_16x16x32_bf16 v[68:71], v[180:183], v[196:199], v[68:71]
	v_mfma_f32_16x16x32_bf16 v[88:91], v[172:175], v[218:221], v[88:91]
	v_mfma_f32_16x16x32_bf16 v[60:63], v[180:183], v[218:221], v[60:63]
	v_mfma_f32_16x16x32_bf16 v[76:79], v[172:175], v[226:229], v[76:79]
	v_mfma_f32_16x16x32_bf16 v[48:51], v[180:183], v[226:229], v[48:51]

; #define PG8_STAGE(bufoff, gbase, voff) do { _Pragma("unroll") for (int _i = 0; _i < 2; ++_i) \
;         __builtin_amdgcn_global_load_lds((const unsigned*)((const char*)(gbase) + (voff)[_i]), (LAS unsigned*)(lds + (bufoff) + ldsw + _i * 8192), 16, 0, 0); } while (0)
; #define PG8_LDA(dst, b, h) do { _Pragma("unroll") for (int m = 0; m < 4; ++m) _Pragma("unroll") for (int k = 0; k < 2; ++k) dst[m][k] = *(const LAS bf16x8*)(lds + PG8_SA(b, h) + aoff + m * 2048 + k * 1024); } while (0)
; #define PG8_MMA(ai, bj, At, Bt) do { __builtin_amdgcn_s_setprio(1); _Pragma("unroll") for (int m = 0; m < 4; ++m) _Pragma("unroll") for (int n = 0; n < 2; ++n) _Pragma("unroll") for (int k = 0; k < 2; ++k) \
;         acc[ai][bj][m][n] = __builtin_amdgcn_mfma_f32_16x16x32_bf16(Bt[n][k], At[m][k], acc[ai][bj][m][n], 0, 0, 0); __builtin_amdgcn_s_setprio(0); } while (0)
; #define PG8_WAIT_V(n) asm volatile("s_waitcnt vmcnt(" #n ")" ::: "memory")
; #define PG8_WAIT_L(n) asm volatile("s_waitcnt lgkmcnt(" #n ")" ::: "memory")
; #define PG8_BAR __builtin_amdgcn_s_barrier()
; #define PG8_SCHED __builtin_amdgcn_sched_barrier(0)
; template <class Epi, bool ALIGN_EPI>
; __device__ __forceinline__ void gemm_phase(LAS unsigned char* lds, const Gemm g, const StaticOrder& S, const Epi& E, const int tid) {
;     ...
;             PG8_WAIT_V(8); PG8_WAIT_L(0); PG8_BAR; PG8_MMA(0, 0, At, B0); PG8_MMA(0, 1, At, B1); PG8_BAR; PG8_SCHED;
;             PG8_LDA(At, 0, 1); PG8_STAGE(PG8_SB(0, 0), b2, voffB); PG8_STAGE(PG8_SB(0, 1), b2 + hstepB, voffB); PG8_STAGE(PG8_SA(0, 0), a2, voffA);
	s_barrier
	s_add_i32 s89, s89, s61
	s_mov_b32 m0, s89
	ds_read_b128 v[184:187], v171 offset:16384
	ds_read_b128 v[188:191], v171 offset:17408
	ds_read_b128 v[192:195], v171 offset:18432
	ds_read_b128 v[196:199], v171 offset:19456


; #define PG8_STAGE(bufoff, gbase, voff) do { _Pragma("unroll") for (int _i = 0; _i < 2; ++_i) \
;         __builtin_amdgcn_global_load_lds((const unsigned*)((const char*)(gbase) + (voff)[_i]), (LAS unsigned*)(lds + (bufoff) + ldsw + _i * 8192), 16, 0, 0); } while (0)
; #define PG8_LDA(dst, b, h) do { _Pragma("unroll") for (int m = 0; m < 4; ++m) _Pragma("unroll") for (int k = 0; k < 2; ++k) dst[m][k] = *(const LAS bf16x8*)(lds + PG8_SA(b, h) + aoff + m * 2048 + k * 1024); } while (0)
; #define PG8_MMA(ai, bj, At, Bt) do { __builtin_amdgcn_s_setprio(1); _Pragma("unroll") for (int m = 0; m < 4; ++m) _Pragma("unroll") for (int n = 0; n < 2; ++n) _Pragma("unroll") for (int k = 0; k < 2; ++k) \
;         acc[ai][bj][m][n] = __builtin_amdgcn_mfma_f32_16x16x32_bf16(Bt[n][k], At[m][k], acc[ai][bj][m][n], 0, 0, 0); __builtin_amdgcn_s_setprio(0); } while (0)
; #define PG8_WAIT_V(n) asm volatile("s_waitcnt vmcnt(" #n ")" ::: "memory")
; #define PG8_WAIT_L(n) asm volatile("s_waitcnt lgkmcnt(" #n ")" ::: "memory")
; #define PG8_BAR __builtin_amdgcn_s_barrier()
; #define PG8_SCHED __builtin_amdgcn_sched_barrier(0)
; template <class Epi, bool ALIGN_EPI>
; __device__ __forceinline__ void gemm_phase(LAS unsigned char* lds, const Gemm g, const StaticOrder& S, const Epi& E, const int tid) {
;     ...
;             PG8_LDA(At, 0, 1); PG8_STAGE(PG8_SB(0, 0), b2, voffB); PG8_STAGE(PG8_SB(0, 1), b2 + hstepB, voffB); PG8_STAGE(PG8_SA(0, 0), a2, voffA);
;             PG8_WAIT_V(8); PG8_WAIT_L(0); PG8_BAR; PG8_MMA(1, 0, At, B0); PG8_MMA(1, 1, At, B1); PG8_BAR; PG8_SCHED;
	global_load_lds_dwordx4 v144, s[52:53]
	s_add_i32 m0, s89, 0x2000
	s_add_u32 s90, s52, 0x4000
	s_addc_u32 s91, s53, 0
	s_add_i32 s89, s92, s61
	global_load_lds_dwordx4 v140, s[52:53]
	s_mov_b32 m0, s89
	ds_read_b128 v[226:229], v171 offset:23552
	global_load_lds_dwordx4 v144, s[90:91]
	s_add_i32 m0, s89, 0x2000
	ds_read_b128 v[222:225], v171 offset:22528
	global_load_lds_dwordx4 v140, s[90:91]
	s_mov_b32 m0, s71
	ds_read_b128 v[218:221], v171 offset:21504
	global_load_lds_dwordx4 v146, s[54:55]
	s_mov_b32 m0, s72
	ds_read_b128 v[214:217], v171 offset:20480
	global_load_lds_dwordx4 v142, s[54:55]
	s_nop 0
	s_waitcnt vmcnt(8)
	s_waitcnt lgkmcnt(0)
	s_barrier


; #define PG8_MMA(ai, bj, At, Bt) do { __builtin_amdgcn_s_setprio(1); _Pragma("unroll") for (int m = 0; m < 4; ++m) _Pragma("unroll") for (int n = 0; n < 2; ++n) _Pragma("unroll") for (int k = 0; k < 2; ++k) \
;         acc[ai][bj][m][n] = __builtin_amdgcn_mfma_f32_16x16x32_bf16(Bt[n][k], At[m][k], acc[ai][bj][m][n], 0, 0, 0); __builtin_amdgcn_s_setprio(0); } while (0)
; #define PG8_WAIT_V(n) asm volatile("s_waitcnt vmcnt(" #n ")" ::: "memory")
; #define PG8_WAIT_L(n) asm volatile("s_waitcnt lgkmcnt(" #n ")" ::: "memory")
; #define PG8_BAR __builtin_amdgcn_s_barrier()
; #define PG8_SCHED __builtin_amdgcn_sched_barrier(0)
; template <class Epi, bool ALIGN_EPI>
; __device__ __forceinline__ void gemm_phase(LAS unsigned char* lds, const Gemm g, const StaticOrder& S, const Epi& E, const int tid) {
;     ...
;             PG8_WAIT_V(8); PG8_WAIT_L(0); PG8_BAR; PG8_MMA(1, 0, At, B0); PG8_MMA(1, 1, At, B1); PG8_BAR; PG8_SCHED;
	v_mfma_f32_16x16x32_bf16 v[84:87], v[132:135], v[184:187], v[84:87]
	v_mfma_f32_16x16x32_bf16 v[56:59], v[152:155], v[184:187], v[56:59]
	v_mfma_f32_16x16x32_bf16 v[72:75], v[132:135], v[192:195], v[72:75]
	v_mfma_f32_16x16x32_bf16 v[44:47], v[152:155], v[192:195], v[44:47]
	v_mfma_f32_16x16x32_bf16 v[64:67], v[132:135], v[214:217], v[64:67]
	v_mfma_f32_16x16x32_bf16 v[36:39], v[152:155], v[214:217], v[36:39]
	v_mfma_f32_16x16x32_bf16 v[52:55], v[132:135], v[222:225], v[52:55]
	v_mfma_f32_16x16x32_bf16 v[28:31], v[152:155], v[222:225], v[28:31]
	v_mfma_f32_16x16x32_bf16 v[84:87], v[136:139], v[188:191], v[84:87]
	v_mfma_f32_16x16x32_bf16 v[56:59], v[156:159], v[188:191], v[56:59]
	v_mfma_f32_16x16x32_bf16 v[72:75], v[136:139], v[196:199], v[72:75]
	v_mfma_f32_16x16x32_bf16 v[44:47], v[156:159], v[196:199], v[44:47]
	v_mfma_f32_16x16x32_bf16 v[64:67], v[136:139], v[218:221], v[64:67]
	v_mfma_f32_16x16x32_bf16 v[36:39], v[156:159], v[218:221], v[36:39]
	v_mfma_f32_16x16x32_bf16 v[52:55], v[136:139], v[226:229], v[52:55]
	v_mfma_f32_16x16x32_bf16 v[28:31], v[156:159], v[226:229], v[28:31]


; #define PG8_MMA(ai, bj, At, Bt) do { __builtin_amdgcn_s_setprio(1); _Pragma("unroll") for (int m = 0; m < 4; ++m) _Pragma("unroll") for (int n = 0; n < 2; ++n) _Pragma("unroll") for (int k = 0; k < 2; ++k) \
;         acc[ai][bj][m][n] = __builtin_amdgcn_mfma_f32_16x16x32_bf16(Bt[n][k], At[m][k], acc[ai][bj][m][n], 0, 0, 0); __builtin_amdgcn_s_setprio(0); } while (0)
; #define PG8_WAIT_V(n) asm volatile("s_waitcnt vmcnt(" #n ")" ::: "memory")
; #define PG8_WAIT_L(n) asm volatile("s_waitcnt lgkmcnt(" #n ")" ::: "memory")
; #define PG8_BAR __builtin_amdgcn_s_barrier()
; #define PG8_SCHED __builtin_amdgcn_sched_barrier(0)
; template <class Epi, bool ALIGN_EPI>
; __device__ __forceinline__ void gemm_phase(LAS unsigned char* lds, const Gemm g, const StaticOrder& S, const Epi& E, const int tid) {
;     ...
;             PG8_WAIT_V(8); PG8_WAIT_L(0); PG8_BAR; PG8_MMA(1, 0, At, B0); PG8_MMA(1, 1, At, B1); PG8_BAR; PG8_SCHED;
	v_mfma_f32_16x16x32_bf16 v[40:43], v[160:163], v[184:187], v[40:43]
	v_mfma_f32_16x16x32_bf16 v[20:23], v[176:179], v[184:187], v[20:23]
	v_mfma_f32_16x16x32_bf16 v[32:35], v[160:163], v[192:195], v[32:35]
	v_mfma_f32_16x16x32_bf16 v[12:15], v[176:179], v[192:195], v[12:15]
	v_mfma_f32_16x16x32_bf16 v[24:27], v[160:163], v[214:217], v[24:27]
	v_mfma_f32_16x16x32_bf16 v[8:11], v[176:179], v[214:217], v[8:11]
	v_mfma_f32_16x16x32_bf16 v[16:19], v[160:163], v[222:225], v[16:19]
	v_mfma_f32_16x16x32_bf16 v[2:5], v[176:179], v[222:225], v[4:7]
	v_mfma_f32_16x16x32_bf16 v[40:43], v[172:175], v[188:191], v[40:43]
	v_mfma_f32_16x16x32_bf16 v[20:23], v[180:183], v[188:191], v[20:23]
	v_mfma_f32_16x16x32_bf16 v[32:35], v[172:175], v[196:199], v[32:35]
	v_mfma_f32_16x16x32_bf16 v[12:15], v[180:183], v[196:199], v[12:15]
	v_mfma_f32_16x16x32_bf16 v[24:27], v[172:175], v[218:221], v[24:27]
	v_mfma_f32_16x16x32_bf16 v[8:11], v[180:183], v[218:221], v[8:11]
	v_mfma_f32_16x16x32_bf16 v[16:19], v[172:175], v[226:229], v[16:19]
	v_mfma_f32_16x16x32_bf16 v[2:5], v[180:183], v[226:229], v[2:5]

; #define PG8_STAGE(bufoff, gbase, voff) do { _Pragma("unroll") for (int _i = 0; _i < 2; ++_i) \
;         __builtin_amdgcn_global_load_lds((const unsigned*)((const char*)(gbase) + (voff)[_i]), (LAS unsigned*)(lds + (bufoff) + ldsw + _i * 8192), 16, 0, 0); } while (0)
; #define PG8_LDA(dst, b, h) do { _Pragma("unroll") for (int m = 0; m < 4; ++m) _Pragma("unroll") for (int k = 0; k < 2; ++k) dst[m][k] = *(const LAS bf16x8*)(lds + PG8_SA(b, h) + aoff + m * 2048 + k * 1024); } while (0)
; #define PG8_LDB(dst, b, h) do { _Pragma("unroll") for (int n = 0; n < 2; ++n) _Pragma("unroll") for (int k = 0; k < 2; ++k) dst[n][k] = *(const LAS bf16x8*)(lds + PG8_SB(b, h) + boff + n * 2048 + k * 1024); } while (0)
; #define PG8_SCHED __builtin_amdgcn_sched_barrier(0)
; template <class Epi, bool ALIGN_EPI>
; __device__ __forceinline__ void gemm_phase(LAS unsigned char* lds, const Gemm g, const StaticOrder& S, const Epi& E, const int tid) {
;     ...
;             PG8_LDB(B0, 1, 0); PG8_LDB(B1, 1, 1); PG8_SCHED; PG8_LDA(At, 1, 0); PG8_STAGE(PG8_SA(0, 1), a2 + hstepA, voffA);
	s_barrier
	s_add_i32 s89, 0, 0x18000
	v_add_u32_e32 v0, s89, v167
	s_add_i32 s90, 0, 0x1c000
	ds_read_b128 v[132:135], v0
	ds_read_b128 v[136:139], v0 offset:1024
	ds_read_b128 v[152:155], v0 offset:2048
	ds_read_b128 v[156:159], v0 offset:3072
	v_add_u32_e32 v0, s90, v167
	ds_read_b128 v[160:163], v0
	ds_read_b128 v[172:175], v0 offset:1024
	ds_read_b128 v[176:179], v0 offset:2048
	ds_read_b128 v[180:183], v0 offset:3072
	s_add_u32 s54, s54, 0x4000
	s_addc_u32 s55, s55, 0
	s_mov_b32 m0, s73
	ds_read_b128 v[184:187], v171 offset:32768
	ds_read_b128 v[188:191], v171 offset:33792
	ds_read_b128 v[192:195], v171 offset:34816
	ds_read_b128 v[196:199], v171 offset:35840
	ds_read_b128 v[214:217], v171 offset:36864
	ds_read_b128 v[218:221], v171 offset:37888
	ds_read_b128 v[222:225], v171 offset:38912

; #define PG8_STAGE(bufoff, gbase, voff) do { _Pragma("unroll") for (int _i = 0; _i < 2; ++_i) \
;         __builtin_amdgcn_global_load_lds((const unsigned*)((const char*)(gbase) + (voff)[_i]), (LAS unsigned*)(lds + (bufoff) + ldsw + _i * 8192), 16, 0, 0); } while (0)
; #define PG8_LDA(dst, b, h) do { _Pragma("unroll") for (int m = 0; m < 4; ++m) _Pragma("unroll") for (int k = 0; k < 2; ++k) dst[m][k] = *(const LAS bf16x8*)(lds + PG8_SA(b, h) + aoff + m * 2048 + k * 1024); } while (0)
; #define PG8_LDB(dst, b, h) do { _Pragma("unroll") for (int n = 0; n < 2; ++n) _Pragma("unroll") for (int k = 0; k < 2; ++k) dst[n][k] = *(const LAS bf16x8*)(lds + PG8_SB(b, h) + boff + n * 2048 + k * 1024); } while (0)
; #define PG8_MMA(ai, bj, At, Bt) do { __builtin_amdgcn_s_setprio(1); _Pragma("unroll") for (int m = 0; m < 4; ++m) _Pragma("unroll") for (int n = 0; n < 2; ++n) _Pragma("unroll") for (int k = 0; k < 2; ++k) \
;         acc[ai][bj][m][n] = __builtin_amdgcn_mfma_f32_16x16x32_bf16(Bt[n][k], At[m][k], acc[ai][bj][m][n], 0, 0, 0); __builtin_amdgcn_s_setprio(0); } while (0)
; #define PG8_WAIT_V(n) asm volatile("s_waitcnt vmcnt(" #n ")" ::: "memory")
; #define PG8_WAIT_L(n) asm volatile("s_waitcnt lgkmcnt(" #n ")" ::: "memory")
; #define PG8_BAR __builtin_amdgcn_s_barrier()
; #define PG8_SCHED __builtin_amdgcn_sched_barrier(0)
; template <class Epi, bool ALIGN_EPI>
; __device__ __forceinline__ void gemm_phase(LAS unsigned char* lds, const Gemm g, const StaticOrder& S, const Epi& E, const int tid) {
;     ...
;             PG8_LDB(B0, 1, 0); PG8_LDB(B1, 1, 1); PG8_SCHED; PG8_LDA(At, 1, 0); PG8_STAGE(PG8_SA(0, 1), a2 + hstepA, voffA);
;             PG8_WAIT_V(8); PG8_WAIT_L(0); PG8_BAR; PG8_MMA(0, 0, At, B0); PG8_MMA(0, 1, At, B1); PG8_BAR; PG8_SCHED;
	global_load_lds_dwordx4 v146, s[54:55]
	s_mov_b32 m0, s74
	ds_read_b128 v[226:229], v171 offset:39936
	global_load_lds_dwordx4 v142, s[54:55]
	s_nop 0
	s_waitcnt vmcnt(8)
	s_waitcnt lgkmcnt(0)
	s_barrier


; #define PG8_MMA(ai, bj, At, Bt) do { __builtin_amdgcn_s_setprio(1); _Pragma("unroll") for (int m = 0; m < 4; ++m) _Pragma("unroll") for (int n = 0; n < 2; ++n) _Pragma("unroll") for (int k = 0; k < 2; ++k) \
;         acc[ai][bj][m][n] = __builtin_amdgcn_mfma_f32_16x16x32_bf16(Bt[n][k], At[m][k], acc[ai][bj][m][n], 0, 0, 0); __builtin_amdgcn_s_setprio(0); } while (0)
; #define PG8_WAIT_V(n) asm volatile("s_waitcnt vmcnt(" #n ")" ::: "memory")
; #define PG8_WAIT_L(n) asm volatile("s_waitcnt lgkmcnt(" #n ")" ::: "memory")
; #define PG8_BAR __builtin_amdgcn_s_barrier()
; #define PG8_SCHED __builtin_amdgcn_sched_barrier(0)
; template <class Epi, bool ALIGN_EPI>
; __device__ __forceinline__ void gemm_phase(LAS unsigned char* lds, const Gemm g, const StaticOrder& S, const Epi& E, const int tid) {
;     ...
;             PG8_WAIT_V(8); PG8_WAIT_L(0); PG8_BAR; PG8_MMA(0, 0, At, B0); PG8_MMA(0, 1, At, B1); PG8_BAR; PG8_SCHED;
	v_mfma_f32_16x16x32_bf16 v[128:131], v[132:135], v[184:187], v[128:131]
	v_mfma_f32_16x16x32_bf16 v[116:119], v[152:155], v[184:187], v[116:119]
	v_mfma_f32_16x16x32_bf16 v[124:127], v[132:135], v[192:195], v[124:127]
	v_mfma_f32_16x16x32_bf16 v[108:111], v[152:155], v[192:195], v[108:111]
	v_mfma_f32_16x16x32_bf16 v[120:123], v[132:135], v[214:217], v[120:123]
	v_mfma_f32_16x16x32_bf16 v[100:103], v[152:155], v[214:217], v[100:103]
	v_mfma_f32_16x16x32_bf16 v[112:115], v[132:135], v[222:225], v[112:115]
	v_mfma_f32_16x16x32_bf16 v[92:95], v[152:155], v[222:225], v[92:95]
	v_mfma_f32_16x16x32_bf16 v[128:131], v[136:139], v[188:191], v[128:131]
	v_mfma_f32_16x16x32_bf16 v[116:119], v[156:159], v[188:191], v[116:119]
	v_mfma_f32_16x16x32_bf16 v[124:127], v[136:139], v[196:199], v[124:127]
	v_mfma_f32_16x16x32_bf16 v[108:111], v[156:159], v[196:199], v[108:111]
	v_mfma_f32_16x16x32_bf16 v[120:123], v[136:139], v[218:221], v[120:123]
	v_mfma_f32_16x16x32_bf16 v[100:103], v[156:159], v[218:221], v[100:103]
	v_mfma_f32_16x16x32_bf16 v[112:115], v[136:139], v[226:229], v[112:115]
	v_mfma_f32_16x16x32_bf16 v[92:95], v[156:159], v[226:229], v[92:95]


; #define PG8_MMA(ai, bj, At, Bt) do { __builtin_amdgcn_s_setprio(1); _Pragma("unroll") for (int m = 0; m < 4; ++m) _Pragma("unroll") for (int n = 0; n < 2; ++n) _Pragma("unroll") for (int k = 0; k < 2; ++k) \
;         acc[ai][bj][m][n] = __builtin_amdgcn_mfma_f32_16x16x32_bf16(Bt[n][k], At[m][k], acc[ai][bj][m][n], 0, 0, 0); __builtin_amdgcn_s_setprio(0); } while (0)
; #define PG8_WAIT_V(n) asm volatile("s_waitcnt vmcnt(" #n ")" ::: "memory")
; #define PG8_WAIT_L(n) asm volatile("s_waitcnt lgkmcnt(" #n ")" ::: "memory")
; #define PG8_BAR __builtin_amdgcn_s_barrier()
; #define PG8_SCHED __builtin_amdgcn_sched_barrier(0)
; template <class Epi, bool ALIGN_EPI>
; __device__ __forceinline__ void gemm_phase(LAS unsigned char* lds, const Gemm g, const StaticOrder& S, const Epi& E, const int tid) {
;     ...
;             PG8_WAIT_V(8); PG8_WAIT_L(0); PG8_BAR; PG8_MMA(0, 0, At, B0); PG8_MMA(0, 1, At, B1); PG8_BAR; PG8_SCHED;
	v_mfma_f32_16x16x32_bf16 v[104:107], v[160:163], v[184:187], v[104:107]
	v_mfma_f32_16x16x32_bf16 v[80:83], v[176:179], v[184:187], v[80:83]
	v_mfma_f32_16x16x32_bf16 v[96:99], v[160:163], v[192:195], v[96:99]
	v_mfma_f32_16x16x32_bf16 v[68:71], v[176:179], v[192:195], v[68:71]
	v_mfma_f32_16x16x32_bf16 v[88:91], v[160:163], v[214:217], v[88:91]
	v_mfma_f32_16x16x32_bf16 v[60:63], v[176:179], v[214:217], v[60:63]
	v_mfma_f32_16x16x32_bf16 v[76:79], v[160:163], v[222:225], v[76:79]
	v_mfma_f32_16x16x32_bf16 v[48:51], v[176:179], v[222:225], v[48:51]
	v_mfma_f32_16x16x32_bf16 v[104:107], v[172:175], v[188:191], v[104:107]
	v_mfma_f32_16x16x32_bf16 v[80:83], v[180:183], v[188:191], v[80:83]
	v_mfma_f32_16x16x32_bf16 v[96:99], v[172:175], v[196:199], v[96:99]
	v_mfma_f32_16x16x32_bf16 v[68:71], v[180:183], v[196:199], v[68:71]
	v_mfma_f32_16x16x32_bf16 v[88:91], v[172:175], v[218:221], v[88:91]
	v_mfma_f32_16x16x32_bf16 v[60:63], v[180:183], v[218:221], v[60:63]
	v_mfma_f32_16x16x32_bf16 v[76:79], v[172:175], v[226:229], v[76:79]
	v_mfma_f32_16x16x32_bf16 v[48:51], v[180:183], v[226:229], v[48:51]

; #define PG8_STAGE(bufoff, gbase, voff) do { _Pragma("unroll") for (int _i = 0; _i < 2; ++_i) \
;         __builtin_amdgcn_global_load_lds((const unsigned*)((const char*)(gbase) + (voff)[_i]), (LAS unsigned*)(lds + (bufoff) + ldsw + _i * 8192), 16, 0, 0); } while (0)
; #define PG8_LDA(dst, b, h) do { _Pragma("unroll") for (int m = 0; m < 4; ++m) _Pragma("unroll") for (int k = 0; k < 2; ++k) dst[m][k] = *(const LAS bf16x8*)(lds + PG8_SA(b, h) + aoff + m * 2048 + k * 1024); } while (0)
; template <class Epi, bool ALIGN_EPI>
; __device__ __forceinline__ void gemm_phase(LAS unsigned char* lds, const Gemm g, const StaticOrder& S, const Epi& E, const int tid) {
;     ...
;             PG8_LDA(At, 1, 1); PG8_STAGE(PG8_SB(1, 0), b3, voffB); PG8_STAGE(PG8_SB(1, 1), b3 + hstepB, voffB); PG8_STAGE(PG8_SA(1, 0), a3, voffA);
	s_barrier
	s_add_u32 s54, s52, 0x8000
	s_addc_u32 s55, s53, 0
	s_add_i32 s89, s89, s61
	s_mov_b32 m0, s89
	ds_read_b128 v[184:187], v171 offset:49152
	ds_read_b128 v[188:191], v171 offset:50176
	ds_read_b128 v[192:195], v171 offset:51200
	ds_read_b128 v[196:199], v171 offset:52224


; #define PG8_STAGE(bufoff, gbase, voff) do { _Pragma("unroll") for (int _i = 0; _i < 2; ++_i) \
;         __builtin_amdgcn_global_load_lds((const unsigned*)((const char*)(gbase) + (voff)[_i]), (LAS unsigned*)(lds + (bufoff) + ldsw + _i * 8192), 16, 0, 0); } while (0)
; #define PG8_LDA(dst, b, h) do { _Pragma("unroll") for (int m = 0; m < 4; ++m) _Pragma("unroll") for (int k = 0; k < 2; ++k) dst[m][k] = *(const LAS bf16x8*)(lds + PG8_SA(b, h) + aoff + m * 2048 + k * 1024); } while (0)
; #define PG8_MMA(ai, bj, At, Bt) do { __builtin_amdgcn_s_setprio(1); _Pragma("unroll") for (int m = 0; m < 4; ++m) _Pragma("unroll") for (int n = 0; n < 2; ++n) _Pragma("unroll") for (int k = 0; k < 2; ++k) \
;         acc[ai][bj][m][n] = __builtin_amdgcn_mfma_f32_16x16x32_bf16(Bt[n][k], At[m][k], acc[ai][bj][m][n], 0, 0, 0); __builtin_amdgcn_s_setprio(0); } while (0)
; #define PG8_WAIT_V(n) asm volatile("s_waitcnt vmcnt(" #n ")" ::: "memory")
; #define PG8_WAIT_L(n) asm volatile("s_waitcnt lgkmcnt(" #n ")" ::: "memory")
; #define PG8_BAR __builtin_amdgcn_s_barrier()
; #define PG8_SCHED __builtin_amdgcn_sched_barrier(0)
; template <class Epi, bool ALIGN_EPI>
; __device__ __forceinline__ void gemm_phase(LAS unsigned char* lds, const Gemm g, const StaticOrder& S, const Epi& E, const int tid) {
;     ...
;             PG8_LDA(At, 1, 1); PG8_STAGE(PG8_SB(1, 0), b3, voffB); PG8_STAGE(PG8_SB(1, 1), b3 + hstepB, voffB); PG8_STAGE(PG8_SA(1, 0), a3, voffA);
;             PG8_WAIT_V(8); PG8_WAIT_L(0); PG8_BAR; PG8_MMA(1, 0, At, B0); PG8_MMA(1, 1, At, B1); PG8_BAR; PG8_SCHED;
	global_load_lds_dwordx4 v144, s[54:55]
	s_add_i32 m0, s89, 0x2000
	s_add_u32 s52, s52, 0xc000
	s_addc_u32 s53, s53, 0
	global_load_lds_dwordx4 v140, s[54:55]
	s_add_i32 s54, s90, s61
	s_mov_b32 m0, s54
	ds_read_b128 v[226:229], v171 offset:56320
	global_load_lds_dwordx4 v144, s[52:53]
	s_add_i32 m0, s54, 0x2000
	ds_read_b128 v[222:225], v171 offset:55296
	global_load_lds_dwordx4 v140, s[52:53]
	s_mov_b32 m0, s77
	ds_read_b128 v[218:221], v171 offset:54272
	global_load_lds_dwordx4 v146, s[50:51]
	s_mov_b32 m0, s78
	ds_read_b128 v[214:217], v171 offset:53248
	global_load_lds_dwordx4 v142, s[50:51]
	s_waitcnt vmcnt(8)
	s_waitcnt lgkmcnt(0)
	s_barrier


; #define PG8_MMA(ai, bj, At, Bt) do { __builtin_amdgcn_s_setprio(1); _Pragma("unroll") for (int m = 0; m < 4; ++m) _Pragma("unroll") for (int n = 0; n < 2; ++n) _Pragma("unroll") for (int k = 0; k < 2; ++k) \
;         acc[ai][bj][m][n] = __builtin_amdgcn_mfma_f32_16x16x32_bf16(Bt[n][k], At[m][k], acc[ai][bj][m][n], 0, 0, 0); __builtin_amdgcn_s_setprio(0); } while (0)
; #define PG8_WAIT_V(n) asm volatile("s_waitcnt vmcnt(" #n ")" ::: "memory")
; #define PG8_WAIT_L(n) asm volatile("s_waitcnt lgkmcnt(" #n ")" ::: "memory")
; #define PG8_BAR __builtin_amdgcn_s_barrier()
; #define PG8_SCHED __builtin_amdgcn_sched_barrier(0)
; template <class Epi, bool ALIGN_EPI>
; __device__ __forceinline__ void gemm_phase(LAS unsigned char* lds, const Gemm g, const StaticOrder& S, const Epi& E, const int tid) {
;     ...
;             PG8_WAIT_V(8); PG8_WAIT_L(0); PG8_BAR; PG8_MMA(1, 0, At, B0); PG8_MMA(1, 1, At, B1); PG8_BAR; PG8_SCHED;
	v_mfma_f32_16x16x32_bf16 v[84:87], v[132:135], v[184:187], v[84:87]
	v_mfma_f32_16x16x32_bf16 v[56:59], v[152:155], v[184:187], v[56:59]
	v_mfma_f32_16x16x32_bf16 v[72:75], v[132:135], v[192:195], v[72:75]
	v_mfma_f32_16x16x32_bf16 v[44:47], v[152:155], v[192:195], v[44:47]
	v_mfma_f32_16x16x32_bf16 v[64:67], v[132:135], v[214:217], v[64:67]
	v_mfma_f32_16x16x32_bf16 v[36:39], v[152:155], v[214:217], v[36:39]
	v_mfma_f32_16x16x32_bf16 v[52:55], v[132:135], v[222:225], v[52:55]
	v_mfma_f32_16x16x32_bf16 v[28:31], v[152:155], v[222:225], v[28:31]
	v_mfma_f32_16x16x32_bf16 v[84:87], v[136:139], v[188:191], v[84:87]
	v_mfma_f32_16x16x32_bf16 v[56:59], v[156:159], v[188:191], v[56:59]
	v_mfma_f32_16x16x32_bf16 v[72:75], v[136:139], v[196:199], v[72:75]
	v_mfma_f32_16x16x32_bf16 v[44:47], v[156:159], v[196:199], v[44:47]
	v_mfma_f32_16x16x32_bf16 v[64:67], v[136:139], v[218:221], v[64:67]
	v_mfma_f32_16x16x32_bf16 v[36:39], v[156:159], v[218:221], v[36:39]
	v_mfma_f32_16x16x32_bf16 v[52:55], v[136:139], v[226:229], v[52:55]
	v_mfma_f32_16x16x32_bf16 v[28:31], v[156:159], v[226:229], v[28:31]


; #define PG8_MMA(ai, bj, At, Bt) do { __builtin_amdgcn_s_setprio(1); _Pragma("unroll") for (int m = 0; m < 4; ++m) _Pragma("unroll") for (int n = 0; n < 2; ++n) _Pragma("unroll") for (int k = 0; k < 2; ++k) \
;         acc[ai][bj][m][n] = __builtin_amdgcn_mfma_f32_16x16x32_bf16(Bt[n][k], At[m][k], acc[ai][bj][m][n], 0, 0, 0); __builtin_amdgcn_s_setprio(0); } while (0)
; #define PG8_WAIT_V(n) asm volatile("s_waitcnt vmcnt(" #n ")" ::: "memory")
; #define PG8_WAIT_L(n) asm volatile("s_waitcnt lgkmcnt(" #n ")" ::: "memory")
; #define PG8_BAR __builtin_amdgcn_s_barrier()
; #define PG8_SCHED __builtin_amdgcn_sched_barrier(0)
; template <class Epi, bool ALIGN_EPI>
; __device__ __forceinline__ void gemm_phase(LAS unsigned char* lds, const Gemm g, const StaticOrder& S, const Epi& E, const int tid) {
;     ...
;             PG8_WAIT_V(8); PG8_WAIT_L(0); PG8_BAR; PG8_MMA(1, 0, At, B0); PG8_MMA(1, 1, At, B1); PG8_BAR; PG8_SCHED;
	v_mfma_f32_16x16x32_bf16 v[40:43], v[160:163], v[184:187], v[40:43]
	v_mfma_f32_16x16x32_bf16 v[20:23], v[176:179], v[184:187], v[20:23]
	v_mfma_f32_16x16x32_bf16 v[32:35], v[160:163], v[192:195], v[32:35]
	v_mfma_f32_16x16x32_bf16 v[12:15], v[176:179], v[192:195], v[12:15]
	v_mfma_f32_16x16x32_bf16 v[24:27], v[160:163], v[214:217], v[24:27]
	v_mfma_f32_16x16x32_bf16 v[6:9], v[176:179], v[214:217], v[8:11]
	v_mfma_f32_16x16x32_bf16 v[16:19], v[160:163], v[222:225], v[16:19]
	v_mfma_f32_16x16x32_bf16 v[2:5], v[176:179], v[222:225], v[2:5]
	v_mfma_f32_16x16x32_bf16 v[40:43], v[172:175], v[188:191], v[40:43]
	v_mfma_f32_16x16x32_bf16 v[20:23], v[180:183], v[188:191], v[20:23]
	v_mfma_f32_16x16x32_bf16 v[32:35], v[172:175], v[196:199], v[32:35]
	v_mfma_f32_16x16x32_bf16 v[12:15], v[180:183], v[196:199], v[12:15]
	v_mfma_f32_16x16x32_bf16 v[24:27], v[172:175], v[218:221], v[24:27]
	v_mfma_f32_16x16x32_bf16 v[8:11], v[180:183], v[218:221], v[6:9]
	v_mfma_f32_16x16x32_bf16 v[16:19], v[172:175], v[226:229], v[16:19]
	v_mfma_f32_16x16x32_bf16 v[4:7], v[180:183], v[226:229], v[2:5]

; #define PG8_MMA(ai, bj, At, Bt) do { __builtin_amdgcn_s_setprio(1); _Pragma("unroll") for (int m = 0; m < 4; ++m) _Pragma("unroll") for (int n = 0; n < 2; ++n) _Pragma("unroll") for (int k = 0; k < 2; ++k) \
;         acc[ai][bj][m][n] = __builtin_amdgcn_mfma_f32_16x16x32_bf16(Bt[n][k], At[m][k], acc[ai][bj][m][n], 0, 0, 0); __builtin_amdgcn_s_setprio(0); } while (0)
; #define PG8_WAIT_V(n) asm volatile("s_waitcnt vmcnt(" #n ")" ::: "memory")
; #define PG8_WAIT_L(n) asm volatile("s_waitcnt lgkmcnt(" #n ")" ::: "memory")
; #define PG8_BAR __builtin_amdgcn_s_barrier()
; #define PG8_SCHED __builtin_amdgcn_sched_barrier(0)
; template <class Epi, bool ALIGN_EPI>
; __device__ __forceinline__ void gemm_phase(LAS unsigned char* lds, const Gemm g, const StaticOrder& S, const Epi& E, const int tid) {
;     ...
;             PG8_WAIT_V(8); PG8_WAIT_L(0); PG8_BAR; PG8_MMA(1, 0, At, B0); PG8_MMA(1, 1, At, B1); PG8_BAR; PG8_SCHED;
;         }
;         if constexpr (ALIGN_EPI) { if (wr == 0) PG8_BAR; }
	s_barrier
	s_add_i32 s88, s88, 2
	s_add_u32 s48, s48, 0x10000
	s_addc_u32 s49, s49, 0
	s_add_u32 s86, s86, 0x10000
	s_addc_u32 s87, s87, 0
	s_cmp_gt_u32 s88, 29
	s_cbranch_scc0 .LBB0_385
	s_and_b64 vcc, exec, s[34:35]
	s_cbranch_vccz .LBB0_388
	s_barrier

; #define PG8_STAGE(bufoff, gbase, voff) do { _Pragma("unroll") for (int _i = 0; _i < 2; ++_i) \
;         __builtin_amdgcn_global_load_lds((const unsigned*)((const char*)(gbase) + (voff)[_i]), (LAS unsigned*)(lds + (bufoff) + ldsw + _i * 8192), 16, 0, 0); } while (0)
; #define PG8_LDA(dst, b, h) do { _Pragma("unroll") for (int m = 0; m < 4; ++m) _Pragma("unroll") for (int k = 0; k < 2; ++k) dst[m][k] = *(const LAS bf16x8*)(lds + PG8_SA(b, h) + aoff + m * 2048 + k * 1024); } while (0)
; #define PG8_LDB(dst, b, h) do { _Pragma("unroll") for (int n = 0; n < 2; ++n) _Pragma("unroll") for (int k = 0; k < 2; ++k) dst[n][k] = *(const LAS bf16x8*)(lds + PG8_SB(b, h) + boff + n * 2048 + k * 1024); } while (0)
; #define PG8_SCHED __builtin_amdgcn_sched_barrier(0)
; template <class Epi, bool ALIGN_EPI>
; __device__ __forceinline__ void gemm_phase(LAS unsigned char* lds, const Gemm g, const StaticOrder& S, const Epi& E, const int tid) {
;     ...
;             const bool last = (t == nt - 2);
;             const char* a1 = cA + (size_t)(t + 1) * kstepA;
;             const char* a2 = last ? nA : cA + (size_t)(t + 2) * kstepA; const char* b2 = last ? nB : cB + (size_t)(t + 2) * kstepB;
;             const char* a3 = a2 + kstepA; const char* b3 = b2 + kstepB;
;             PG8_LDB(B0, 0, 0); PG8_LDB(B1, 0, 1); PG8_SCHED; PG8_LDA(At, 0, 0); PG8_STAGE(PG8_SA(1, 1), a1 + hstepA, voffA);
.LBB0_847:
	s_add_u32 s22, s10, 0xfff80080
	s_addc_u32 s23, s11, -1
	s_add_i32 s87, 0, 0x10000
	s_cmp_eq_u32 s86, 28
	s_cselect_b32 s35, s49, s23
	s_cselect_b32 s34, s82, s22
	v_add_u32_e32 v0, s87, v154
	s_cselect_b32 s23, s47, s85
	s_cselect_b32 s22, s83, s84
	s_add_i32 s90, 0, 0x14000
	s_waitcnt lgkmcnt(0)
	ds_read_b128 v[132:135], v0
	ds_read_b128 v[148:151], v0 offset:1024
	ds_read_b128 v[156:159], v0 offset:2048
	ds_read_b128 v[160:163], v0 offset:3072
	v_add_u32_e32 v0, s90, v154
	ds_read_b128 v[164:167], v0
	ds_read_b128 v[168:171], v0 offset:1024
	ds_read_b128 v[172:175], v0 offset:2048
	ds_read_b128 v[176:179], v0 offset:3072
	s_add_i32 m0, s70, 0xc000
	ds_read_b128 v[180:183], v155
	ds_read_b128 v[184:187], v155 offset:1024
	ds_read_b128 v[188:191], v155 offset:2048
	ds_read_b128 v[192:195], v155 offset:3072
	ds_read_b128 v[196:199], v155 offset:4096
	ds_read_b128 v[214:217], v155 offset:5120
	ds_read_b128 v[218:221], v155 offset:6144

; #define PG8_STAGE(bufoff, gbase, voff) do { _Pragma("unroll") for (int _i = 0; _i < 2; ++_i) \
;         __builtin_amdgcn_global_load_lds((const unsigned*)((const char*)(gbase) + (voff)[_i]), (LAS unsigned*)(lds + (bufoff) + ldsw + _i * 8192), 16, 0, 0); } while (0)
; #define PG8_LDA(dst, b, h) do { _Pragma("unroll") for (int m = 0; m < 4; ++m) _Pragma("unroll") for (int k = 0; k < 2; ++k) dst[m][k] = *(const LAS bf16x8*)(lds + PG8_SA(b, h) + aoff + m * 2048 + k * 1024); } while (0)
; #define PG8_LDB(dst, b, h) do { _Pragma("unroll") for (int n = 0; n < 2; ++n) _Pragma("unroll") for (int k = 0; k < 2; ++k) dst[n][k] = *(const LAS bf16x8*)(lds + PG8_SB(b, h) + boff + n * 2048 + k * 1024); } while (0)
; #define PG8_MMA(ai, bj, At, Bt) do { __builtin_amdgcn_s_setprio(1); _Pragma("unroll") for (int m = 0; m < 4; ++m) _Pragma("unroll") for (int n = 0; n < 2; ++n) _Pragma("unroll") for (int k = 0; k < 2; ++k) \
;         acc[ai][bj][m][n] = __builtin_amdgcn_mfma_f32_16x16x32_bf16(Bt[n][k], At[m][k], acc[ai][bj][m][n], 0, 0, 0); __builtin_amdgcn_s_setprio(0); } while (0)
; #define PG8_WAIT_V(n) asm volatile("s_waitcnt vmcnt(" #n ")" ::: "memory")
; #define PG8_WAIT_L(n) asm volatile("s_waitcnt lgkmcnt(" #n ")" ::: "memory")
; #define PG8_BAR __builtin_amdgcn_s_barrier()
; #define PG8_SCHED __builtin_amdgcn_sched_barrier(0)
; template <class Epi, bool ALIGN_EPI>
; __device__ __forceinline__ void gemm_phase(LAS unsigned char* lds, const Gemm g, const StaticOrder& S, const Epi& E, const int tid) {
;     ...
;             PG8_LDB(B0, 0, 0); PG8_LDB(B1, 0, 1); PG8_SCHED; PG8_LDA(At, 0, 0); PG8_STAGE(PG8_SA(1, 1), a1 + hstepA, voffA);
;             PG8_WAIT_V(8); PG8_WAIT_L(0); PG8_BAR; PG8_MMA(0, 0, At, B0); PG8_MMA(0, 1, At, B1); PG8_BAR; PG8_SCHED;
	global_load_lds_dwordx4 v144, s[10:11]
	s_add_i32 m0, s70, 0xe000
	ds_read_b128 v[222:225], v155 offset:7168
	global_load_lds_dwordx4 v146, s[10:11]
	s_waitcnt vmcnt(8)
	s_waitcnt lgkmcnt(0)
	s_barrier


; #define PG8_MMA(ai, bj, At, Bt) do { __builtin_amdgcn_s_setprio(1); _Pragma("unroll") for (int m = 0; m < 4; ++m) _Pragma("unroll") for (int n = 0; n < 2; ++n) _Pragma("unroll") for (int k = 0; k < 2; ++k) \
;         acc[ai][bj][m][n] = __builtin_amdgcn_mfma_f32_16x16x32_bf16(Bt[n][k], At[m][k], acc[ai][bj][m][n], 0, 0, 0); __builtin_amdgcn_s_setprio(0); } while (0)
; #define PG8_WAIT_V(n) asm volatile("s_waitcnt vmcnt(" #n ")" ::: "memory")
; #define PG8_WAIT_L(n) asm volatile("s_waitcnt lgkmcnt(" #n ")" ::: "memory")
; #define PG8_BAR __builtin_amdgcn_s_barrier()
; #define PG8_SCHED __builtin_amdgcn_sched_barrier(0)
; template <class Epi, bool ALIGN_EPI>
; __device__ __forceinline__ void gemm_phase(LAS unsigned char* lds, const Gemm g, const StaticOrder& S, const Epi& E, const int tid) {
;     ...
;             PG8_WAIT_V(8); PG8_WAIT_L(0); PG8_BAR; PG8_MMA(0, 0, At, B0); PG8_MMA(0, 1, At, B1); PG8_BAR; PG8_SCHED;
	v_mfma_f32_16x16x32_bf16 v[8:11], v[132:135], v[180:183], v[8:11]
	v_mfma_f32_16x16x32_bf16 v[56:59], v[156:159], v[180:183], v[56:59]
	v_mfma_f32_16x16x32_bf16 v[52:55], v[132:135], v[188:191], v[52:55]
	v_mfma_f32_16x16x32_bf16 v[48:51], v[156:159], v[188:191], v[48:51]
	v_mfma_f32_16x16x32_bf16 v[44:47], v[132:135], v[196:199], v[44:47]
	v_mfma_f32_16x16x32_bf16 v[40:43], v[156:159], v[196:199], v[40:43]
	v_mfma_f32_16x16x32_bf16 v[36:39], v[132:135], v[218:221], v[36:39]
	v_mfma_f32_16x16x32_bf16 v[32:35], v[156:159], v[218:221], v[32:35]
	v_mfma_f32_16x16x32_bf16 v[8:11], v[148:151], v[184:187], v[8:11]
	v_mfma_f32_16x16x32_bf16 v[56:59], v[160:163], v[184:187], v[56:59]
	v_mfma_f32_16x16x32_bf16 v[52:55], v[148:151], v[192:195], v[52:55]
	v_mfma_f32_16x16x32_bf16 v[48:51], v[160:163], v[192:195], v[48:51]
	v_mfma_f32_16x16x32_bf16 v[44:47], v[148:151], v[214:217], v[44:47]
	v_mfma_f32_16x16x32_bf16 v[40:43], v[160:163], v[214:217], v[40:43]
	v_mfma_f32_16x16x32_bf16 v[36:39], v[148:151], v[222:225], v[36:39]
	v_mfma_f32_16x16x32_bf16 v[32:35], v[160:163], v[222:225], v[32:35]


; #define PG8_MMA(ai, bj, At, Bt) do { __builtin_amdgcn_s_setprio(1); _Pragma("unroll") for (int m = 0; m < 4; ++m) _Pragma("unroll") for (int n = 0; n < 2; ++n) _Pragma("unroll") for (int k = 0; k < 2; ++k) \
;         acc[ai][bj][m][n] = __builtin_amdgcn_mfma_f32_16x16x32_bf16(Bt[n][k], At[m][k], acc[ai][bj][m][n], 0, 0, 0); __builtin_amdgcn_s_setprio(0); } while (0)
; #define PG8_WAIT_V(n) asm volatile("s_waitcnt vmcnt(" #n ")" ::: "memory")
; #define PG8_WAIT_L(n) asm volatile("s_waitcnt lgkmcnt(" #n ")" ::: "memory")
; #define PG8_BAR __builtin_amdgcn_s_barrier()
; #define PG8_SCHED __builtin_amdgcn_sched_barrier(0)
; template <class Epi, bool ALIGN_EPI>
; __device__ __forceinline__ void gemm_phase(LAS unsigned char* lds, const Gemm g, const StaticOrder& S, const Epi& E, const int tid) {
;     ...
;             PG8_WAIT_V(8); PG8_WAIT_L(0); PG8_BAR; PG8_MMA(0, 0, At, B0); PG8_MMA(0, 1, At, B1); PG8_BAR; PG8_SCHED;
	v_mfma_f32_16x16x32_bf16 v[2:5], v[164:167], v[180:183], v[4:7]
	v_mfma_f32_16x16x32_bf16 v[28:31], v[172:175], v[180:183], v[28:31]
	v_mfma_f32_16x16x32_bf16 v[96:99], v[164:167], v[188:191], v[96:99]
	v_mfma_f32_16x16x32_bf16 v[92:95], v[172:175], v[188:191], v[92:95]
	v_mfma_f32_16x16x32_bf16 v[88:91], v[164:167], v[196:199], v[88:91]
	v_mfma_f32_16x16x32_bf16 v[84:87], v[172:175], v[196:199], v[84:87]
	v_mfma_f32_16x16x32_bf16 v[80:83], v[164:167], v[218:221], v[80:83]
	v_mfma_f32_16x16x32_bf16 v[76:79], v[172:175], v[218:221], v[76:79]
	v_mfma_f32_16x16x32_bf16 v[2:5], v[168:171], v[184:187], v[2:5]
	v_mfma_f32_16x16x32_bf16 v[28:31], v[176:179], v[184:187], v[28:31]
	v_mfma_f32_16x16x32_bf16 v[96:99], v[168:171], v[192:195], v[96:99]
	v_mfma_f32_16x16x32_bf16 v[92:95], v[176:179], v[192:195], v[92:95]
	v_mfma_f32_16x16x32_bf16 v[88:91], v[168:171], v[214:217], v[88:91]
	v_mfma_f32_16x16x32_bf16 v[84:87], v[176:179], v[214:217], v[84:87]
	v_mfma_f32_16x16x32_bf16 v[80:83], v[168:171], v[222:225], v[80:83]
	v_mfma_f32_16x16x32_bf16 v[76:79], v[176:179], v[222:225], v[76:79]

; #define PG8_STAGE(bufoff, gbase, voff) do { _Pragma("unroll") for (int _i = 0; _i < 2; ++_i) \
;         __builtin_amdgcn_global_load_lds((const unsigned*)((const char*)(gbase) + (voff)[_i]), (LAS unsigned*)(lds + (bufoff) + ldsw + _i * 8192), 16, 0, 0); } while (0)
; #define PG8_LDA(dst, b, h) do { _Pragma("unroll") for (int m = 0; m < 4; ++m) _Pragma("unroll") for (int k = 0; k < 2; ++k) dst[m][k] = *(const LAS bf16x8*)(lds + PG8_SA(b, h) + aoff + m * 2048 + k * 1024); } while (0)
; #define PG8_MMA(ai, bj, At, Bt) do { __builtin_amdgcn_s_setprio(1); _Pragma("unroll") for (int m = 0; m < 4; ++m) _Pragma("unroll") for (int n = 0; n < 2; ++n) _Pragma("unroll") for (int k = 0; k < 2; ++k) \
;         acc[ai][bj][m][n] = __builtin_amdgcn_mfma_f32_16x16x32_bf16(Bt[n][k], At[m][k], acc[ai][bj][m][n], 0, 0, 0); __builtin_amdgcn_s_setprio(0); } while (0)
; #define PG8_WAIT_V(n) asm volatile("s_waitcnt vmcnt(" #n ")" ::: "memory")
; #define PG8_WAIT_L(n) asm volatile("s_waitcnt lgkmcnt(" #n ")" ::: "memory")
; #define PG8_BAR __builtin_amdgcn_s_barrier()
; #define PG8_SCHED __builtin_amdgcn_sched_barrier(0)
; template <class Epi, bool ALIGN_EPI>
; __device__ __forceinline__ void gemm_phase(LAS unsigned char* lds, const Gemm g, const StaticOrder& S, const Epi& E, const int tid) {
;     ...
;             PG8_WAIT_V(8); PG8_WAIT_L(0); PG8_BAR; PG8_MMA(0, 0, At, B0); PG8_MMA(0, 1, At, B1); PG8_BAR; PG8_SCHED;
;             PG8_LDA(At, 0, 1); PG8_STAGE(PG8_SB(0, 0), b2, voffB); PG8_STAGE(PG8_SB(0, 1), b2 + hstepB, voffB); PG8_STAGE(PG8_SA(0, 0), a2, voffA);
	s_barrier
	s_add_i32 s87, s87, s61
	s_mov_b32 m0, s87
	ds_read_b128 v[180:183], v155 offset:16384
	ds_read_b128 v[184:187], v155 offset:17408
	ds_read_b128 v[188:191], v155 offset:18432
	ds_read_b128 v[192:195], v155 offset:19456
	ds_read_b128 v[196:199], v155 offset:20480
	ds_read_b128 v[214:217], v155 offset:21504


; #define PG8_STAGE(bufoff, gbase, voff) do { _Pragma("unroll") for (int _i = 0; _i < 2; ++_i) \
;         __builtin_amdgcn_global_load_lds((const unsigned*)((const char*)(gbase) + (voff)[_i]), (LAS unsigned*)(lds + (bufoff) + ldsw + _i * 8192), 16, 0, 0); } while (0)
; #define PG8_LDA(dst, b, h) do { _Pragma("unroll") for (int m = 0; m < 4; ++m) _Pragma("unroll") for (int k = 0; k < 2; ++k) dst[m][k] = *(const LAS bf16x8*)(lds + PG8_SA(b, h) + aoff + m * 2048 + k * 1024); } while (0)
; #define PG8_MMA(ai, bj, At, Bt) do { __builtin_amdgcn_s_setprio(1); _Pragma("unroll") for (int m = 0; m < 4; ++m) _Pragma("unroll") for (int n = 0; n < 2; ++n) _Pragma("unroll") for (int k = 0; k < 2; ++k) \
;         acc[ai][bj][m][n] = __builtin_amdgcn_mfma_f32_16x16x32_bf16(Bt[n][k], At[m][k], acc[ai][bj][m][n], 0, 0, 0); __builtin_amdgcn_s_setprio(0); } while (0)
; #define PG8_WAIT_V(n) asm volatile("s_waitcnt vmcnt(" #n ")" ::: "memory")
; #define PG8_WAIT_L(n) asm volatile("s_waitcnt lgkmcnt(" #n ")" ::: "memory")
; #define PG8_BAR __builtin_amdgcn_s_barrier()
; #define PG8_SCHED __builtin_amdgcn_sched_barrier(0)
; template <class Epi, bool ALIGN_EPI>
; __device__ __forceinline__ void gemm_phase(LAS unsigned char* lds, const Gemm g, const StaticOrder& S, const Epi& E, const int tid) {
;     ...
;             PG8_LDA(At, 0, 1); PG8_STAGE(PG8_SB(0, 0), b2, voffB); PG8_STAGE(PG8_SB(0, 1), b2 + hstepB, voffB); PG8_STAGE(PG8_SA(0, 0), a2, voffA);
;             PG8_WAIT_V(8); PG8_WAIT_L(0); PG8_BAR; PG8_MMA(1, 0, At, B0); PG8_MMA(1, 1, At, B1); PG8_BAR; PG8_SCHED;
	global_load_lds_dwordx4 v140, s[22:23]
	s_add_i32 m0, s87, 0x2000
	s_add_u32 s88, s22, 0x4000
	s_addc_u32 s89, s23, 0
	s_add_i32 s87, s90, s61
	global_load_lds_dwordx4 v136, s[22:23]
	s_mov_b32 m0, s87
	v_lshl_add_u64 v[152:153], s[34:35], 0, v[142:143]
	global_load_lds_dwordx4 v140, s[88:89]
	s_add_i32 m0, s87, 0x2000
	v_lshl_add_u64 v[200:201], s[34:35], 0, v[138:139]
	global_load_lds_dwordx4 v136, s[88:89]
	s_mov_b32 m0, s70
	ds_read_b128 v[222:225], v155 offset:23552
	global_load_lds_dwordx4 v[152:153], off
	s_mov_b32 m0, s71
	ds_read_b128 v[218:221], v155 offset:22528
	global_load_lds_dwordx4 v[200:201], off
	s_nop 0
	s_waitcnt vmcnt(8)
	s_waitcnt lgkmcnt(0)
	s_barrier


; #define PG8_MMA(ai, bj, At, Bt) do { __builtin_amdgcn_s_setprio(1); _Pragma("unroll") for (int m = 0; m < 4; ++m) _Pragma("unroll") for (int n = 0; n < 2; ++n) _Pragma("unroll") for (int k = 0; k < 2; ++k) \
;         acc[ai][bj][m][n] = __builtin_amdgcn_mfma_f32_16x16x32_bf16(Bt[n][k], At[m][k], acc[ai][bj][m][n], 0, 0, 0); __builtin_amdgcn_s_setprio(0); } while (0)
; #define PG8_WAIT_V(n) asm volatile("s_waitcnt vmcnt(" #n ")" ::: "memory")
; #define PG8_WAIT_L(n) asm volatile("s_waitcnt lgkmcnt(" #n ")" ::: "memory")
; #define PG8_BAR __builtin_amdgcn_s_barrier()
; #define PG8_SCHED __builtin_amdgcn_sched_barrier(0)
; template <class Epi, bool ALIGN_EPI>
; __device__ __forceinline__ void gemm_phase(LAS unsigned char* lds, const Gemm g, const StaticOrder& S, const Epi& E, const int tid) {
;     ...
;             PG8_WAIT_V(8); PG8_WAIT_L(0); PG8_BAR; PG8_MMA(1, 0, At, B0); PG8_MMA(1, 1, At, B1); PG8_BAR; PG8_SCHED;
	v_mfma_f32_16x16x32_bf16 v[24:27], v[132:135], v[180:183], v[24:27]
	v_mfma_f32_16x16x32_bf16 v[20:23], v[156:159], v[180:183], v[20:23]
	v_mfma_f32_16x16x32_bf16 v[64:67], v[132:135], v[188:191], v[64:67]
	v_mfma_f32_16x16x32_bf16 v[72:75], v[156:159], v[188:191], v[72:75]
	v_mfma_f32_16x16x32_bf16 v[16:19], v[132:135], v[196:199], v[16:19]
	v_mfma_f32_16x16x32_bf16 v[12:15], v[156:159], v[196:199], v[12:15]
	v_mfma_f32_16x16x32_bf16 v[60:63], v[132:135], v[218:221], v[60:63]
	v_mfma_f32_16x16x32_bf16 v[68:71], v[156:159], v[218:221], v[68:71]
	v_mfma_f32_16x16x32_bf16 v[24:27], v[148:151], v[184:187], v[24:27]
	v_mfma_f32_16x16x32_bf16 v[20:23], v[160:163], v[184:187], v[20:23]
	v_mfma_f32_16x16x32_bf16 v[64:67], v[148:151], v[192:195], v[64:67]
	v_mfma_f32_16x16x32_bf16 v[72:75], v[160:163], v[192:195], v[72:75]
	v_mfma_f32_16x16x32_bf16 v[16:19], v[148:151], v[214:217], v[16:19]
	v_mfma_f32_16x16x32_bf16 v[12:15], v[160:163], v[214:217], v[12:15]
	v_mfma_f32_16x16x32_bf16 v[60:63], v[148:151], v[222:225], v[60:63]
	v_mfma_f32_16x16x32_bf16 v[68:71], v[160:163], v[222:225], v[68:71]


; #define PG8_MMA(ai, bj, At, Bt) do { __builtin_amdgcn_s_setprio(1); _Pragma("unroll") for (int m = 0; m < 4; ++m) _Pragma("unroll") for (int n = 0; n < 2; ++n) _Pragma("unroll") for (int k = 0; k < 2; ++k) \
;         acc[ai][bj][m][n] = __builtin_amdgcn_mfma_f32_16x16x32_bf16(Bt[n][k], At[m][k], acc[ai][bj][m][n], 0, 0, 0); __builtin_amdgcn_s_setprio(0); } while (0)
; #define PG8_WAIT_V(n) asm volatile("s_waitcnt vmcnt(" #n ")" ::: "memory")
; #define PG8_WAIT_L(n) asm volatile("s_waitcnt lgkmcnt(" #n ")" ::: "memory")
; #define PG8_BAR __builtin_amdgcn_s_barrier()
; #define PG8_SCHED __builtin_amdgcn_sched_barrier(0)
; template <class Epi, bool ALIGN_EPI>
; __device__ __forceinline__ void gemm_phase(LAS unsigned char* lds, const Gemm g, const StaticOrder& S, const Epi& E, const int tid) {
;     ...
;             PG8_WAIT_V(8); PG8_WAIT_L(0); PG8_BAR; PG8_MMA(1, 0, At, B0); PG8_MMA(1, 1, At, B1); PG8_BAR; PG8_SCHED;
	v_mfma_f32_16x16x32_bf16 v[128:131], v[164:167], v[180:183], v[128:131]
	v_mfma_f32_16x16x32_bf16 v[124:127], v[172:175], v[180:183], v[124:127]
	v_mfma_f32_16x16x32_bf16 v[120:123], v[164:167], v[188:191], v[120:123]
	v_mfma_f32_16x16x32_bf16 v[116:119], v[172:175], v[188:191], v[116:119]
	v_mfma_f32_16x16x32_bf16 v[112:115], v[164:167], v[196:199], v[112:115]
	v_mfma_f32_16x16x32_bf16 v[108:111], v[172:175], v[196:199], v[108:111]
	v_mfma_f32_16x16x32_bf16 v[104:107], v[164:167], v[218:221], v[104:107]
	v_mfma_f32_16x16x32_bf16 v[100:103], v[172:175], v[218:221], v[100:103]
	v_mfma_f32_16x16x32_bf16 v[128:131], v[168:171], v[184:187], v[128:131]
	v_mfma_f32_16x16x32_bf16 v[124:127], v[176:179], v[184:187], v[124:127]
	v_mfma_f32_16x16x32_bf16 v[120:123], v[168:171], v[192:195], v[120:123]
	v_mfma_f32_16x16x32_bf16 v[116:119], v[176:179], v[192:195], v[116:119]
	v_mfma_f32_16x16x32_bf16 v[112:115], v[168:171], v[214:217], v[112:115]
	v_mfma_f32_16x16x32_bf16 v[108:111], v[176:179], v[214:217], v[108:111]
	v_mfma_f32_16x16x32_bf16 v[104:107], v[168:171], v[222:225], v[104:107]
	v_mfma_f32_16x16x32_bf16 v[100:103], v[176:179], v[222:225], v[100:103]

; #define PG8_STAGE(bufoff, gbase, voff) do { _Pragma("unroll") for (int _i = 0; _i < 2; ++_i) \
;         __builtin_amdgcn_global_load_lds((const unsigned*)((const char*)(gbase) + (voff)[_i]), (LAS unsigned*)(lds + (bufoff) + ldsw + _i * 8192), 16, 0, 0); } while (0)
; #define PG8_LDA(dst, b, h) do { _Pragma("unroll") for (int m = 0; m < 4; ++m) _Pragma("unroll") for (int k = 0; k < 2; ++k) dst[m][k] = *(const LAS bf16x8*)(lds + PG8_SA(b, h) + aoff + m * 2048 + k * 1024); } while (0)
; #define PG8_LDB(dst, b, h) do { _Pragma("unroll") for (int n = 0; n < 2; ++n) _Pragma("unroll") for (int k = 0; k < 2; ++k) dst[n][k] = *(const LAS bf16x8*)(lds + PG8_SB(b, h) + boff + n * 2048 + k * 1024); } while (0)
; #define PG8_MMA(ai, bj, At, Bt) do { __builtin_amdgcn_s_setprio(1); _Pragma("unroll") for (int m = 0; m < 4; ++m) _Pragma("unroll") for (int n = 0; n < 2; ++n) _Pragma("unroll") for (int k = 0; k < 2; ++k) \
;         acc[ai][bj][m][n] = __builtin_amdgcn_mfma_f32_16x16x32_bf16(Bt[n][k], At[m][k], acc[ai][bj][m][n], 0, 0, 0); __builtin_amdgcn_s_setprio(0); } while (0)
; #define PG8_WAIT_V(n) asm volatile("s_waitcnt vmcnt(" #n ")" ::: "memory")
; #define PG8_WAIT_L(n) asm volatile("s_waitcnt lgkmcnt(" #n ")" ::: "memory")
; #define PG8_BAR __builtin_amdgcn_s_barrier()
; #define PG8_SCHED __builtin_amdgcn_sched_barrier(0)
; template <class Epi, bool ALIGN_EPI>
; __device__ __forceinline__ void gemm_phase(LAS unsigned char* lds, const Gemm g, const StaticOrder& S, const Epi& E, const int tid) {
;     ...
;             PG8_WAIT_V(8); PG8_WAIT_L(0); PG8_BAR; PG8_MMA(1, 0, At, B0); PG8_MMA(1, 1, At, B1); PG8_BAR; PG8_SCHED;
;             PG8_LDB(B0, 1, 0); PG8_LDB(B1, 1, 1); PG8_SCHED; PG8_LDA(At, 1, 0); PG8_STAGE(PG8_SA(0, 1), a2 + hstepA, voffA);
	s_barrier
	s_add_i32 s87, 0, 0x18000
	v_add_u32_e32 v0, s87, v154
	s_add_i32 s88, 0, 0x1c000
	ds_read_b128 v[132:135], v0
	ds_read_b128 v[148:151], v0 offset:1024
	ds_read_b128 v[156:159], v0 offset:2048
	ds_read_b128 v[160:163], v0 offset:3072
	v_add_u32_e32 v0, s88, v154
	ds_read_b128 v[164:167], v0
	ds_read_b128 v[168:171], v0 offset:1024
	ds_read_b128 v[172:175], v0 offset:2048
	ds_read_b128 v[176:179], v0 offset:3072
	s_add_u32 s34, s34, 0x80000
	s_addc_u32 s35, s35, 0
	s_mov_b32 m0, s72
	ds_read_b128 v[180:183], v155 offset:32768
	ds_read_b128 v[184:187], v155 offset:33792
	ds_read_b128 v[188:191], v155 offset:34816
	ds_read_b128 v[192:195], v155 offset:35840
	ds_read_b128 v[196:199], v155 offset:36864
	ds_read_b128 v[214:217], v155 offset:37888
	ds_read_b128 v[218:221], v155 offset:38912

; #define PG8_STAGE(bufoff, gbase, voff) do { _Pragma("unroll") for (int _i = 0; _i < 2; ++_i) \
;         __builtin_amdgcn_global_load_lds((const unsigned*)((const char*)(gbase) + (voff)[_i]), (LAS unsigned*)(lds + (bufoff) + ldsw + _i * 8192), 16, 0, 0); } while (0)
; #define PG8_LDA(dst, b, h) do { _Pragma("unroll") for (int m = 0; m < 4; ++m) _Pragma("unroll") for (int k = 0; k < 2; ++k) dst[m][k] = *(const LAS bf16x8*)(lds + PG8_SA(b, h) + aoff + m * 2048 + k * 1024); } while (0)
; #define PG8_LDB(dst, b, h) do { _Pragma("unroll") for (int n = 0; n < 2; ++n) _Pragma("unroll") for (int k = 0; k < 2; ++k) dst[n][k] = *(const LAS bf16x8*)(lds + PG8_SB(b, h) + boff + n * 2048 + k * 1024); } while (0)
; #define PG8_MMA(ai, bj, At, Bt) do { __builtin_amdgcn_s_setprio(1); _Pragma("unroll") for (int m = 0; m < 4; ++m) _Pragma("unroll") for (int n = 0; n < 2; ++n) _Pragma("unroll") for (int k = 0; k < 2; ++k) \
;         acc[ai][bj][m][n] = __builtin_amdgcn_mfma_f32_16x16x32_bf16(Bt[n][k], At[m][k], acc[ai][bj][m][n], 0, 0, 0); __builtin_amdgcn_s_setprio(0); } while (0)
; #define PG8_WAIT_V(n) asm volatile("s_waitcnt vmcnt(" #n ")" ::: "memory")
; #define PG8_WAIT_L(n) asm volatile("s_waitcnt lgkmcnt(" #n ")" ::: "memory")
; #define PG8_BAR __builtin_amdgcn_s_barrier()
; #define PG8_SCHED __builtin_amdgcn_sched_barrier(0)
; template <class Epi, bool ALIGN_EPI>
; __device__ __forceinline__ void gemm_phase(LAS unsigned char* lds, const Gemm g, const StaticOrder& S, const Epi& E, const int tid) {
;     ...
;             PG8_LDB(B0, 1, 0); PG8_LDB(B1, 1, 1); PG8_SCHED; PG8_LDA(At, 1, 0); PG8_STAGE(PG8_SA(0, 1), a2 + hstepA, voffA);
;             PG8_WAIT_V(8); PG8_WAIT_L(0); PG8_BAR; PG8_MMA(0, 0, At, B0); PG8_MMA(0, 1, At, B1); PG8_BAR; PG8_SCHED;
	global_load_lds_dwordx4 v142, s[34:35]
	s_mov_b32 m0, s73
	ds_read_b128 v[222:225], v155 offset:39936
	global_load_lds_dwordx4 v138, s[34:35]
	s_nop 0
	s_waitcnt vmcnt(8)
	s_waitcnt lgkmcnt(0)
	s_barrier


; #define PG8_MMA(ai, bj, At, Bt) do { __builtin_amdgcn_s_setprio(1); _Pragma("unroll") for (int m = 0; m < 4; ++m) _Pragma("unroll") for (int n = 0; n < 2; ++n) _Pragma("unroll") for (int k = 0; k < 2; ++k) \
;         acc[ai][bj][m][n] = __builtin_amdgcn_mfma_f32_16x16x32_bf16(Bt[n][k], At[m][k], acc[ai][bj][m][n], 0, 0, 0); __builtin_amdgcn_s_setprio(0); } while (0)
; #define PG8_WAIT_V(n) asm volatile("s_waitcnt vmcnt(" #n ")" ::: "memory")
; #define PG8_WAIT_L(n) asm volatile("s_waitcnt lgkmcnt(" #n ")" ::: "memory")
; #define PG8_BAR __builtin_amdgcn_s_barrier()
; #define PG8_SCHED __builtin_amdgcn_sched_barrier(0)
; template <class Epi, bool ALIGN_EPI>
; __device__ __forceinline__ void gemm_phase(LAS unsigned char* lds, const Gemm g, const StaticOrder& S, const Epi& E, const int tid) {
;     ...
;             PG8_WAIT_V(8); PG8_WAIT_L(0); PG8_BAR; PG8_MMA(0, 0, At, B0); PG8_MMA(0, 1, At, B1); PG8_BAR; PG8_SCHED;
	v_mfma_f32_16x16x32_bf16 v[6:9], v[132:135], v[180:183], v[8:11]
	v_mfma_f32_16x16x32_bf16 v[56:59], v[156:159], v[180:183], v[56:59]
	v_mfma_f32_16x16x32_bf16 v[52:55], v[132:135], v[188:191], v[52:55]
	v_mfma_f32_16x16x32_bf16 v[48:51], v[156:159], v[188:191], v[48:51]
	v_mfma_f32_16x16x32_bf16 v[44:47], v[132:135], v[196:199], v[44:47]
	v_mfma_f32_16x16x32_bf16 v[40:43], v[156:159], v[196:199], v[40:43]
	v_mfma_f32_16x16x32_bf16 v[36:39], v[132:135], v[218:221], v[36:39]
	v_mfma_f32_16x16x32_bf16 v[32:35], v[156:159], v[218:221], v[32:35]
	v_mfma_f32_16x16x32_bf16 v[8:11], v[148:151], v[184:187], v[6:9]
	v_mfma_f32_16x16x32_bf16 v[56:59], v[160:163], v[184:187], v[56:59]
	v_mfma_f32_16x16x32_bf16 v[52:55], v[148:151], v[192:195], v[52:55]
	v_mfma_f32_16x16x32_bf16 v[48:51], v[160:163], v[192:195], v[48:51]
	v_mfma_f32_16x16x32_bf16 v[44:47], v[148:151], v[214:217], v[44:47]
	v_mfma_f32_16x16x32_bf16 v[40:43], v[160:163], v[214:217], v[40:43]
	v_mfma_f32_16x16x32_bf16 v[36:39], v[148:151], v[222:225], v[36:39]
	v_mfma_f32_16x16x32_bf16 v[32:35], v[160:163], v[222:225], v[32:35]


; #define PG8_MMA(ai, bj, At, Bt) do { __builtin_amdgcn_s_setprio(1); _Pragma("unroll") for (int m = 0; m < 4; ++m) _Pragma("unroll") for (int n = 0; n < 2; ++n) _Pragma("unroll") for (int k = 0; k < 2; ++k) \
;         acc[ai][bj][m][n] = __builtin_amdgcn_mfma_f32_16x16x32_bf16(Bt[n][k], At[m][k], acc[ai][bj][m][n], 0, 0, 0); __builtin_amdgcn_s_setprio(0); } while (0)
; #define PG8_WAIT_V(n) asm volatile("s_waitcnt vmcnt(" #n ")" ::: "memory")
; #define PG8_WAIT_L(n) asm volatile("s_waitcnt lgkmcnt(" #n ")" ::: "memory")
; #define PG8_BAR __builtin_amdgcn_s_barrier()
; #define PG8_SCHED __builtin_amdgcn_sched_barrier(0)
; template <class Epi, bool ALIGN_EPI>
; __device__ __forceinline__ void gemm_phase(LAS unsigned char* lds, const Gemm g, const StaticOrder& S, const Epi& E, const int tid) {
;     ...
;             PG8_WAIT_V(8); PG8_WAIT_L(0); PG8_BAR; PG8_MMA(0, 0, At, B0); PG8_MMA(0, 1, At, B1); PG8_BAR; PG8_SCHED;
	v_mfma_f32_16x16x32_bf16 v[2:5], v[164:167], v[180:183], v[2:5]
	v_mfma_f32_16x16x32_bf16 v[28:31], v[172:175], v[180:183], v[28:31]
	v_mfma_f32_16x16x32_bf16 v[96:99], v[164:167], v[188:191], v[96:99]
	v_mfma_f32_16x16x32_bf16 v[92:95], v[172:175], v[188:191], v[92:95]
	v_mfma_f32_16x16x32_bf16 v[88:91], v[164:167], v[196:199], v[88:91]
	v_mfma_f32_16x16x32_bf16 v[84:87], v[172:175], v[196:199], v[84:87]
	v_mfma_f32_16x16x32_bf16 v[80:83], v[164:167], v[218:221], v[80:83]
	v_mfma_f32_16x16x32_bf16 v[76:79], v[172:175], v[218:221], v[76:79]
	v_mfma_f32_16x16x32_bf16 v[4:7], v[168:171], v[184:187], v[2:5]
	v_mfma_f32_16x16x32_bf16 v[28:31], v[176:179], v[184:187], v[28:31]
	v_mfma_f32_16x16x32_bf16 v[96:99], v[168:171], v[192:195], v[96:99]
	v_mfma_f32_16x16x32_bf16 v[92:95], v[176:179], v[192:195], v[92:95]
	v_mfma_f32_16x16x32_bf16 v[88:91], v[168:171], v[214:217], v[88:91]
	v_mfma_f32_16x16x32_bf16 v[84:87], v[176:179], v[214:217], v[84:87]
	v_mfma_f32_16x16x32_bf16 v[80:83], v[168:171], v[222:225], v[80:83]
	v_mfma_f32_16x16x32_bf16 v[76:79], v[176:179], v[222:225], v[76:79]

; #define PG8_STAGE(bufoff, gbase, voff) do { _Pragma("unroll") for (int _i = 0; _i < 2; ++_i) \
;         __builtin_amdgcn_global_load_lds((const unsigned*)((const char*)(gbase) + (voff)[_i]), (LAS unsigned*)(lds + (bufoff) + ldsw + _i * 8192), 16, 0, 0); } while (0)
; #define PG8_LDA(dst, b, h) do { _Pragma("unroll") for (int m = 0; m < 4; ++m) _Pragma("unroll") for (int k = 0; k < 2; ++k) dst[m][k] = *(const LAS bf16x8*)(lds + PG8_SA(b, h) + aoff + m * 2048 + k * 1024); } while (0)
; #define PG8_MMA(ai, bj, At, Bt) do { __builtin_amdgcn_s_setprio(1); _Pragma("unroll") for (int m = 0; m < 4; ++m) _Pragma("unroll") for (int n = 0; n < 2; ++n) _Pragma("unroll") for (int k = 0; k < 2; ++k) \
;         acc[ai][bj][m][n] = __builtin_amdgcn_mfma_f32_16x16x32_bf16(Bt[n][k], At[m][k], acc[ai][bj][m][n], 0, 0, 0); __builtin_amdgcn_s_setprio(0); } while (0)
; #define PG8_WAIT_V(n) asm volatile("s_waitcnt vmcnt(" #n ")" ::: "memory")
; #define PG8_WAIT_L(n) asm volatile("s_waitcnt lgkmcnt(" #n ")" ::: "memory")
; #define PG8_BAR __builtin_amdgcn_s_barrier()
; #define PG8_SCHED __builtin_amdgcn_sched_barrier(0)
; template <class Epi, bool ALIGN_EPI>
; __device__ __forceinline__ void gemm_phase(LAS unsigned char* lds, const Gemm g, const StaticOrder& S, const Epi& E, const int tid) {
;     ...
;             PG8_WAIT_V(8); PG8_WAIT_L(0); PG8_BAR; PG8_MMA(0, 0, At, B0); PG8_MMA(0, 1, At, B1); PG8_BAR; PG8_SCHED;
;             PG8_LDA(At, 1, 1); PG8_STAGE(PG8_SB(1, 0), b3, voffB); PG8_STAGE(PG8_SB(1, 1), b3 + hstepB, voffB); PG8_STAGE(PG8_SA(1, 0), a3, voffA);
	s_barrier
	s_add_u32 s34, s22, 0x8000
	s_addc_u32 s35, s23, 0
	s_add_i32 s87, s87, s61
	s_mov_b32 m0, s87
	ds_read_b128 v[180:183], v155 offset:49152
	ds_read_b128 v[184:187], v155 offset:50176
	ds_read_b128 v[188:191], v155 offset:51200
	ds_read_b128 v[192:195], v155 offset:52224


; #define PG8_STAGE(bufoff, gbase, voff) do { _Pragma("unroll") for (int _i = 0; _i < 2; ++_i) \
;         __builtin_amdgcn_global_load_lds((const unsigned*)((const char*)(gbase) + (voff)[_i]), (LAS unsigned*)(lds + (bufoff) + ldsw + _i * 8192), 16, 0, 0); } while (0)
; #define PG8_LDA(dst, b, h) do { _Pragma("unroll") for (int m = 0; m < 4; ++m) _Pragma("unroll") for (int k = 0; k < 2; ++k) dst[m][k] = *(const LAS bf16x8*)(lds + PG8_SA(b, h) + aoff + m * 2048 + k * 1024); } while (0)
; #define PG8_MMA(ai, bj, At, Bt) do { __builtin_amdgcn_s_setprio(1); _Pragma("unroll") for (int m = 0; m < 4; ++m) _Pragma("unroll") for (int n = 0; n < 2; ++n) _Pragma("unroll") for (int k = 0; k < 2; ++k) \
;         acc[ai][bj][m][n] = __builtin_amdgcn_mfma_f32_16x16x32_bf16(Bt[n][k], At[m][k], acc[ai][bj][m][n], 0, 0, 0); __builtin_amdgcn_s_setprio(0); } while (0)
; #define PG8_WAIT_V(n) asm volatile("s_waitcnt vmcnt(" #n ")" ::: "memory")
; #define PG8_WAIT_L(n) asm volatile("s_waitcnt lgkmcnt(" #n ")" ::: "memory")
; #define PG8_BAR __builtin_amdgcn_s_barrier()
; #define PG8_SCHED __builtin_amdgcn_sched_barrier(0)
; template <class Epi, bool ALIGN_EPI>
; __device__ __forceinline__ void gemm_phase(LAS unsigned char* lds, const Gemm g, const StaticOrder& S, const Epi& E, const int tid) {
;     ...
;             PG8_LDA(At, 1, 1); PG8_STAGE(PG8_SB(1, 0), b3, voffB); PG8_STAGE(PG8_SB(1, 1), b3 + hstepB, voffB); PG8_STAGE(PG8_SA(1, 0), a3, voffA);
;             PG8_WAIT_V(8); PG8_WAIT_L(0); PG8_BAR; PG8_MMA(1, 0, At, B0); PG8_MMA(1, 1, At, B1); PG8_BAR; PG8_SCHED;
	global_load_lds_dwordx4 v140, s[34:35]
	s_add_i32 m0, s87, 0x2000
	s_add_u32 s22, s22, 0xc000
	s_addc_u32 s23, s23, 0
	global_load_lds_dwordx4 v136, s[34:35]
	s_add_i32 s34, s88, s61
	s_mov_b32 m0, s34
	ds_read_b128 v[222:225], v155 offset:56320
	global_load_lds_dwordx4 v140, s[22:23]
	s_add_i32 m0, s34, 0x2000
	ds_read_b128 v[218:221], v155 offset:55296
	global_load_lds_dwordx4 v136, s[22:23]
	v_lshl_add_u64 v[2:3], v[152:153], 0, s[6:7]
	s_mov_b32 m0, s78
	ds_read_b128 v[214:217], v155 offset:54272
	global_load_lds_dwordx4 v[2:3], off
	v_lshl_add_u64 v[2:3], v[200:201], 0, s[6:7]
	s_mov_b32 m0, s79
	ds_read_b128 v[196:199], v155 offset:53248
	global_load_lds_dwordx4 v[2:3], off
	s_waitcnt vmcnt(8)
	s_waitcnt lgkmcnt(0)
	s_barrier


; #define PG8_MMA(ai, bj, At, Bt) do { __builtin_amdgcn_s_setprio(1); _Pragma("unroll") for (int m = 0; m < 4; ++m) _Pragma("unroll") for (int n = 0; n < 2; ++n) _Pragma("unroll") for (int k = 0; k < 2; ++k) \
;         acc[ai][bj][m][n] = __builtin_amdgcn_mfma_f32_16x16x32_bf16(Bt[n][k], At[m][k], acc[ai][bj][m][n], 0, 0, 0); __builtin_amdgcn_s_setprio(0); } while (0)
; #define PG8_WAIT_V(n) asm volatile("s_waitcnt vmcnt(" #n ")" ::: "memory")
; #define PG8_WAIT_L(n) asm volatile("s_waitcnt lgkmcnt(" #n ")" ::: "memory")
; #define PG8_BAR __builtin_amdgcn_s_barrier()
; #define PG8_SCHED __builtin_amdgcn_sched_barrier(0)
; template <class Epi, bool ALIGN_EPI>
; __device__ __forceinline__ void gemm_phase(LAS unsigned char* lds, const Gemm g, const StaticOrder& S, const Epi& E, const int tid) {
;     ...
;             PG8_WAIT_V(8); PG8_WAIT_L(0); PG8_BAR; PG8_MMA(1, 0, At, B0); PG8_MMA(1, 1, At, B1); PG8_BAR; PG8_SCHED;
	v_mfma_f32_16x16x32_bf16 v[24:27], v[132:135], v[180:183], v[24:27]
	v_mfma_f32_16x16x32_bf16 v[20:23], v[156:159], v[180:183], v[20:23]
	v_mfma_f32_16x16x32_bf16 v[64:67], v[132:135], v[188:191], v[64:67]
	v_mfma_f32_16x16x32_bf16 v[72:75], v[156:159], v[188:191], v[72:75]
	v_mfma_f32_16x16x32_bf16 v[16:19], v[132:135], v[196:199], v[16:19]
	v_mfma_f32_16x16x32_bf16 v[12:15], v[156:159], v[196:199], v[12:15]
	v_mfma_f32_16x16x32_bf16 v[60:63], v[132:135], v[218:221], v[60:63]
	v_mfma_f32_16x16x32_bf16 v[68:71], v[156:159], v[218:221], v[68:71]
	v_mfma_f32_16x16x32_bf16 v[24:27], v[148:151], v[184:187], v[24:27]
	v_mfma_f32_16x16x32_bf16 v[20:23], v[160:163], v[184:187], v[20:23]
	v_mfma_f32_16x16x32_bf16 v[64:67], v[148:151], v[192:195], v[64:67]
	v_mfma_f32_16x16x32_bf16 v[72:75], v[160:163], v[192:195], v[72:75]
	v_mfma_f32_16x16x32_bf16 v[16:19], v[148:151], v[214:217], v[16:19]
	v_mfma_f32_16x16x32_bf16 v[12:15], v[160:163], v[214:217], v[12:15]
	v_mfma_f32_16x16x32_bf16 v[60:63], v[148:151], v[222:225], v[60:63]
	v_mfma_f32_16x16x32_bf16 v[68:71], v[160:163], v[222:225], v[68:71]


; #define PG8_MMA(ai, bj, At, Bt) do { __builtin_amdgcn_s_setprio(1); _Pragma("unroll") for (int m = 0; m < 4; ++m) _Pragma("unroll") for (int n = 0; n < 2; ++n) _Pragma("unroll") for (int k = 0; k < 2; ++k) \
;         acc[ai][bj][m][n] = __builtin_amdgcn_mfma_f32_16x16x32_bf16(Bt[n][k], At[m][k], acc[ai][bj][m][n], 0, 0, 0); __builtin_amdgcn_s_setprio(0); } while (0)
; #define PG8_WAIT_V(n) asm volatile("s_waitcnt vmcnt(" #n ")" ::: "memory")
; #define PG8_WAIT_L(n) asm volatile("s_waitcnt lgkmcnt(" #n ")" ::: "memory")
; #define PG8_BAR __builtin_amdgcn_s_barrier()
; #define PG8_SCHED __builtin_amdgcn_sched_barrier(0)
; template <class Epi, bool ALIGN_EPI>
; __device__ __forceinline__ void gemm_phase(LAS unsigned char* lds, const Gemm g, const StaticOrder& S, const Epi& E, const int tid) {
;     ...
;             PG8_WAIT_V(8); PG8_WAIT_L(0); PG8_BAR; PG8_MMA(1, 0, At, B0); PG8_MMA(1, 1, At, B1); PG8_BAR; PG8_SCHED;
	v_mfma_f32_16x16x32_bf16 v[128:131], v[164:167], v[180:183], v[128:131]
	v_mfma_f32_16x16x32_bf16 v[124:127], v[172:175], v[180:183], v[124:127]
	v_mfma_f32_16x16x32_bf16 v[120:123], v[164:167], v[188:191], v[120:123]
	v_mfma_f32_16x16x32_bf16 v[116:119], v[172:175], v[188:191], v[116:119]
	v_mfma_f32_16x16x32_bf16 v[112:115], v[164:167], v[196:199], v[112:115]
	v_mfma_f32_16x16x32_bf16 v[108:111], v[172:175], v[196:199], v[108:111]
	v_mfma_f32_16x16x32_bf16 v[104:107], v[164:167], v[218:221], v[104:107]
	v_mfma_f32_16x16x32_bf16 v[100:103], v[172:175], v[218:221], v[100:103]
	v_mfma_f32_16x16x32_bf16 v[128:131], v[168:171], v[184:187], v[128:131]
	v_mfma_f32_16x16x32_bf16 v[124:127], v[176:179], v[184:187], v[124:127]
	v_mfma_f32_16x16x32_bf16 v[120:123], v[168:171], v[192:195], v[120:123]
	v_mfma_f32_16x16x32_bf16 v[116:119], v[176:179], v[192:195], v[116:119]
	v_mfma_f32_16x16x32_bf16 v[112:115], v[168:171], v[214:217], v[112:115]
	v_mfma_f32_16x16x32_bf16 v[108:111], v[176:179], v[214:217], v[108:111]
	v_mfma_f32_16x16x32_bf16 v[104:107], v[168:171], v[222:225], v[104:107]
	v_mfma_f32_16x16x32_bf16 v[100:103], v[176:179], v[222:225], v[100:103]

; #define PG8_MMA(ai, bj, At, Bt) do { __builtin_amdgcn_s_setprio(1); _Pragma("unroll") for (int m = 0; m < 4; ++m) _Pragma("unroll") for (int n = 0; n < 2; ++n) _Pragma("unroll") for (int k = 0; k < 2; ++k) \
;         acc[ai][bj][m][n] = __builtin_amdgcn_mfma_f32_16x16x32_bf16(Bt[n][k], At[m][k], acc[ai][bj][m][n], 0, 0, 0); __builtin_amdgcn_s_setprio(0); } while (0)
; #define PG8_WAIT_V(n) asm volatile("s_waitcnt vmcnt(" #n ")" ::: "memory")
; #define PG8_WAIT_L(n) asm volatile("s_waitcnt lgkmcnt(" #n ")" ::: "memory")
; #define PG8_BAR __builtin_amdgcn_s_barrier()
; #define PG8_SCHED __builtin_amdgcn_sched_barrier(0)
; __device__ __forceinline__ u32x4 zero_frag() { unsigned z_ = 0u; asm volatile("" : "+v"(z_)); return (u32x4){z_, z_, z_, z_}; }
; __device__ __forceinline__ void epi_lane(int& fr, int& fq) { unsigned ones = ~0u; asm volatile("" : "+s"(ones)); const int ln = (int)__builtin_amdgcn_mbcnt_hi(ones, __builtin_amdgcn_mbcnt_lo(ones, 0u)); fr = ln & 15; fq = ln >> 4; }
; template <class Epi, bool ALIGN_EPI>
; __device__ __forceinline__ void gemm_phase(LAS unsigned char* lds, const Gemm g, const StaticOrder& S, const Epi& E, const int tid) {
;     ...
;             PG8_WAIT_V(8); PG8_WAIT_L(0); PG8_BAR; PG8_MMA(1, 0, At, B0); PG8_MMA(1, 1, At, B1); PG8_BAR; PG8_SCHED;
;         }
;         if constexpr (ALIGN_EPI) { if (wr == 0) PG8_BAR; }
;     __device__ __forceinline__ void operator()(f32x4 (&acc)[2][2][4][2], const Unit& u, int wr, int wc, LAS unsigned char* lds, int& rs_pm) const {
;         int fr, fq; epi_lane(fr, fq);
;         const int row0 = u.pm * BM + wr * 64 + fr, col0 = u.pn * BM + wc * 32 + 8 * fq; u32x4 zb = zero_frag();
; #pragma unroll
;         for (int ai = 0; ai < 2; ++ai)
; #pragma unroll
;             for (int m = 0; m < 4; ++m) { float ss = 0.f;
;                 bf16* const xrow = xb + (((size_t)(u.pm * 32 + u.pn * 4 + (wc >> 1)) * BM + (wr * 64 + fr + ai * HALF + m * 16)) * 64 + (wc & 1) * 32 + 8 * fq);
; #pragma unroll
;                 for (int bj = 0; bj < 2; ++bj) {
;                     const u32x4 xw = *(const u32x4*)(xrow + (size_t)bj * (2 * BM * 64));
	s_barrier
	s_add_i32 s86, s86, 2
	s_add_u32 s10, s10, 0x100
	s_addc_u32 s11, s11, 0
	s_add_u32 s84, s84, 0x10000
	s_addc_u32 s85, s85, 0
	s_cmp_gt_u32 s86, 29
	s_cbranch_scc0 .LBB0_847
	v_and_b32_e32 v222, 15, v238
	v_lshrrev_b32_e32 v156, 4, v238
	s_lshl_b32 s100, s40, 5
	s_lshl_b32 s101, s41, 2
	v_lshlrev_b32_e32 v222, 7, v222
	s_add_i32 s100, s100, s101
	s_or_b32 s100, s100, s80
	v_lshl_or_b32 v222, v156, 4, v222
	s_ashr_i32 s101, s100, 31
	s_lshl_b64 s[100:101], s[100:101], 15
	s_add_u32 s98, s74, s100
	s_addc_u32 s99, s75, s101
	s_add_u32 s98, s98, s30
	s_addc_u32 s99, s99, s31
	s_lshl_b32 s100, s77, 7
	s_add_u32 s98, s98, s100
	s_addc_u32 s99, s99, 0
	s_lshl_b32 s100, s40, 15
	s_lshl_b32 s101, s77, 7
	s_add_i32 s100, s100, s101
	s_lshl_b32 s101, s41, 4
	s_add_i32 s100, s100, s101
	s_lshl_b32 s101, s76, 2
	s_add_i32 s100, s100, s101
	s_add_u32 s22, s42, s100
	s_addc_u32 s23, s43, 0
	global_load_dwordx4 v[176:179], v222, s[98:99]
	s_add_u32 s100, s98, 0x10000
	s_addc_u32 s101, s99, 0
	global_load_dwordx4 v[180:183], v222, s[100:101]
	global_load_dwordx4 v[184:187], v222, s[98:99] offset:2048
	s_add_u32 s100, s98, 0x10000
	s_addc_u32 s101, s99, 0
	global_load_dwordx4 v[188:191], v222, s[100:101] offset:2048
	s_add_u32 s100, s98, 0x1000
	s_addc_u32 s101, s99, 0
	global_load_dwordx4 v[192:195], v222, s[100:101]
	s_add_u32 s100, s98, 0x11000
	s_addc_u32 s101, s99, 0
	global_load_dwordx4 v[196:199], v222, s[100:101]
	s_add_u32 s100, s98, 0x1000
	s_addc_u32 s101, s99, 0
	global_load_dwordx4 v[214:217], v222, s[100:101] offset:2048
	s_add_u32 s100, s98, 0x11000
	s_addc_u32 s101, s99, 0
	global_load_dwordx4 v[218:221], v222, s[100:101] offset:2048
	s_and_b64 vcc, exec, s[44:45]
	s_cbranch_vccz .LBB0_850
	s_barrier
